# GEMM and attention LDS-DMA in saddr form (SGPR base + 32-bit lane offset) on top of v1 attention trims
# speedup vs baseline: 1.0095x; 1.0095x over previous
; #define PG8_STAGE(bufoff, gbase, voff) do { _Pragma("unroll") for (int _i = 0; _i < 2; ++_i) \
;         __builtin_amdgcn_global_load_lds((const unsigned*)((const char*)(gbase) + (voff)[_i]), (PG8_LAS unsigned*)(lds + (bufoff) + ldsw + _i * 8192), 16, 0, 0); } while (0)
; #define PG8_LDA(dst, b, h) do { _Pragma("unroll") for (int m = 0; m < 4; ++m) _Pragma("unroll") for (int k = 0; k < 2; ++k) dst[m][k] = *(const PG8_LAS bf16x8*)(lds + PG8_SA(b, h) + aoff + m * 2048 + k * 1024); } while (0)
; #define PG8_LDB(dst, b, h) do { _Pragma("unroll") for (int n = 0; n < 2; ++n) _Pragma("unroll") for (int k = 0; k < 2; ++k) dst[n][k] = *(const PG8_LAS bf16x8*)(lds + PG8_SB(b, h) + boff + n * 2048 + k * 1024); } while (0)
; #define PG8_MMA(ai, bj, At, Bt) do { __builtin_amdgcn_s_setprio(1); _Pragma("unroll") for (int m = 0; m < 4; ++m) _Pragma("unroll") for (int n = 0; n < 2; ++n) _Pragma("unroll") for (int k = 0; k < 2; ++k) \
;         acc[ai][bj][m][n] = __builtin_amdgcn_mfma_f32_16x16x32_bf16(Bt[n][k], At[m][k], acc[ai][bj][m][n], 0, 0, 0); __builtin_amdgcn_s_setprio(0); } while (0)
; #define PG8_WAIT_V(n) asm volatile("s_waitcnt vmcnt(" #n ")" ::: "memory")
; #define PG8_WAIT_L(n) asm volatile("s_waitcnt lgkmcnt(" #n ")" ::: "memory")
; #define PG8_BAR __builtin_amdgcn_s_barrier()
; #define PG8_SCHED __builtin_amdgcn_sched_barrier(0)
; template <class Epi, class Sched, bool ALIGN_EPI = false, bool SP2 = false>
; __device__ __forceinline__ void gemm_phase(PG8_LAS unsigned char* lds, const Gemm g, const Sched& S, const Epi& E) {
;     ...
;             const bool last = (t == nt - 2);
;             const char* a1 = cA + (size_t)(t + 1) * kstep;
;             const char* a2 = last ? nA : cA + (size_t)(t + 2) * kstep; const char* b2 = last ? nB : cB + (size_t)(t + 2) * kstep;
;             const char* a3 = a2 + kstep; const char* b3 = b2 + kstep;
;             if (last && has_next) S.a_ready(nxt);
;             if constexpr (SP2) {
;             PG8_LDB(B0, 0, 0); PG8_LDB(B1, 0, 1); PG8_SCHED; PG8_LDA(At, 0, 0); PG8_STAGE(PG8_SA(1, 1), a1 + hstep, voffA);
;             PG8_WAIT_V(8); PG8_WAIT_L(0); PG8_BAR; PG8_MMA(0, 0, At, B0); PG8_MMA(0, 1, At, B1); PG8_BAR; PG8_SCHED;
;             PG8_LDA(At, 0, 1); PG8_STAGE(PG8_SB(0, 0), b2, voffB); PG8_STAGE(PG8_SB(0, 1), b2 + hstep, voffB); PG8_STAGE(PG8_SA(0, 0), a2, voffA);
.LBB0_208:
	s_add_u32 s26, s24, 0xfffc0080
	s_addc_u32 s27, s25, -1
	s_add_i32 s43, 0, 0x10000
	s_cmp_eq_u32 s42, 12
	s_cselect_b32 s29, s11, s27
	s_cselect_b32 s28, s21, s26
	s_cselect_b32 s27, s9, s33
	s_cselect_b32 s26, s23, s31
	s_add_i32 s45, 0, 0x14000
	v_add_u32_e32 v156, s43, v149
	v_add_u32_e32 v172, s45, v149
	ds_read_b128 v[140:143], v156
	ds_read_b128 v[144:147], v156 offset:1024
	ds_read_b128 v[152:155], v156 offset:2048
	ds_read_b128 v[156:159], v156 offset:3072
	ds_read_b128 v[160:163], v172
	ds_read_b128 v[164:167], v172 offset:1024
	ds_read_b128 v[168:171], v172 offset:2048
	ds_read_b128 v[172:175], v172 offset:3072
	s_add_i32 m0, s46, 0xc000
	ds_read_b128 v[176:179], v151
	ds_read_b128 v[180:183], v151 offset:1024
	ds_read_b128 v[184:187], v151 offset:2048
	ds_read_b128 v[188:191], v151 offset:3072
	ds_read_b128 v[192:195], v151 offset:4096
	ds_read_b128 v[196:199], v151 offset:5120
	ds_read_b128 v[200:203], v151 offset:6144
	ds_read_b128 v[210:213], v151 offset:7168
	global_load_lds_dwordx4 v136, s[24:25]
	s_add_i32 m0, s46, 0xe000
	s_nop 0
	global_load_lds_dwordx4 v138, s[24:25]
	s_waitcnt vmcnt(8)
	s_waitcnt lgkmcnt(0)
	s_barrier
	s_setprio 1
	s_waitcnt lgkmcnt(0)
	v_mfma_f32_16x16x32_bf16 v[126:129], v[140:143], v[176:179], v[126:129]
	v_mfma_f32_16x16x32_bf16 v[122:125], v[152:155], v[176:179], v[122:125]
	v_mfma_f32_16x16x32_bf16 v[110:113], v[140:143], v[184:187], v[110:113]
	v_mfma_f32_16x16x32_bf16 v[106:109], v[152:155], v[184:187], v[106:109]
	v_mfma_f32_16x16x32_bf16 v[94:97], v[140:143], v[192:195], v[94:97]
	v_mfma_f32_16x16x32_bf16 v[90:93], v[152:155], v[192:195], v[90:93]
	v_mfma_f32_16x16x32_bf16 v[78:81], v[140:143], v[200:203], v[78:81]
	v_mfma_f32_16x16x32_bf16 v[74:77], v[152:155], v[200:203], v[74:77]
	v_mfma_f32_16x16x32_bf16 v[126:129], v[144:147], v[180:183], v[126:129]
	v_mfma_f32_16x16x32_bf16 v[122:125], v[156:159], v[180:183], v[122:125]
	v_mfma_f32_16x16x32_bf16 v[110:113], v[144:147], v[188:191], v[110:113]
	v_mfma_f32_16x16x32_bf16 v[106:109], v[156:159], v[188:191], v[106:109]
	v_mfma_f32_16x16x32_bf16 v[94:97], v[144:147], v[196:199], v[94:97]
	v_mfma_f32_16x16x32_bf16 v[90:93], v[156:159], v[196:199], v[90:93]
	v_mfma_f32_16x16x32_bf16 v[78:81], v[144:147], v[210:213], v[78:81]
	v_mfma_f32_16x16x32_bf16 v[74:77], v[156:159], v[210:213], v[74:77]
	s_setprio 0
	s_setprio 1
	v_mfma_f32_16x16x32_bf16 v[118:121], v[160:163], v[176:179], v[118:121]
	v_mfma_f32_16x16x32_bf16 v[114:117], v[168:171], v[176:179], v[114:117]
	v_mfma_f32_16x16x32_bf16 v[102:105], v[160:163], v[184:187], v[102:105]
	v_mfma_f32_16x16x32_bf16 v[98:101], v[168:171], v[184:187], v[98:101]
	v_mfma_f32_16x16x32_bf16 v[86:89], v[160:163], v[192:195], v[86:89]
	v_mfma_f32_16x16x32_bf16 v[82:85], v[168:171], v[192:195], v[82:85]
	v_mfma_f32_16x16x32_bf16 v[70:73], v[160:163], v[200:203], v[70:73]
	v_mfma_f32_16x16x32_bf16 v[66:69], v[168:171], v[200:203], v[66:69]
	v_mfma_f32_16x16x32_bf16 v[118:121], v[164:167], v[180:183], v[118:121]
	v_mfma_f32_16x16x32_bf16 v[114:117], v[172:175], v[180:183], v[114:117]
	v_mfma_f32_16x16x32_bf16 v[102:105], v[164:167], v[188:191], v[102:105]
	v_mfma_f32_16x16x32_bf16 v[98:101], v[172:175], v[188:191], v[98:101]
	v_mfma_f32_16x16x32_bf16 v[86:89], v[164:167], v[196:199], v[86:89]
	v_mfma_f32_16x16x32_bf16 v[82:85], v[172:175], v[196:199], v[82:85]
	v_mfma_f32_16x16x32_bf16 v[70:73], v[164:167], v[210:213], v[70:73]
	v_mfma_f32_16x16x32_bf16 v[66:69], v[172:175], v[210:213], v[66:69]
	s_setprio 0
	s_barrier
	s_add_i32 s43, s43, s37
	v_lshl_add_u64 v[204:205], s[26:27], 0, v[0:1]
	s_mov_b32 m0, s43
	ds_read_b128 v[176:179], v151 offset:16384
	ds_read_b128 v[180:183], v151 offset:17408
	ds_read_b128 v[184:187], v151 offset:18432
	ds_read_b128 v[188:191], v151 offset:19456
	ds_read_b128 v[192:195], v151 offset:20480
	ds_read_b128 v[196:199], v151 offset:21504
	ds_read_b128 v[200:203], v151 offset:22528
	ds_read_b128 v[210:213], v151 offset:23552
	global_load_lds_dwordx4 v[204:205], off
	s_add_i32 m0, s43, 0x2000
	s_add_u32 s56, s26, 0x40000
	v_lshl_add_u64 v[206:207], s[26:27], 0, v[134:135]
	s_addc_u32 s57, s27, 0
	s_add_i32 s43, s45, s37
	global_load_lds_dwordx4 v[206:207], off
	s_mov_b32 m0, s43
	v_lshl_add_u64 v[216:217], s[28:29], 0, v[132:133]
	global_load_lds_dwordx4 v0, s[56:57]
	s_add_i32 m0, s43, 0x2000
	s_nop 0
	global_load_lds_dwordx4 v134, s[56:57]
	v_lshl_add_u64 v[214:215], s[28:29], 0, v[130:131]
	s_mov_b32 m0, s46
	s_nop 0
	global_load_lds_dwordx4 v[214:215], off
	s_mov_b32 m0, s47
	s_nop 0
	global_load_lds_dwordx4 v[216:217], off
	s_waitcnt vmcnt(8)
	s_waitcnt lgkmcnt(0)
	s_barrier
; #define PG8_STAGE(bufoff, gbase, voff) do { _Pragma("unroll") for (int _i = 0; _i < 2; ++_i) \
;         __builtin_amdgcn_global_load_lds((const unsigned*)((const char*)(gbase) + (voff)[_i]), (PG8_LAS unsigned*)(lds + (bufoff) + ldsw + _i * 8192), 16, 0, 0); } while (0)
; #define PG8_LDA(dst, b, h) do { _Pragma("unroll") for (int m = 0; m < 4; ++m) _Pragma("unroll") for (int k = 0; k < 2; ++k) dst[m][k] = *(const PG8_LAS bf16x8*)(lds + PG8_SA(b, h) + aoff + m * 2048 + k * 1024); } while (0)
; #define PG8_LDB(dst, b, h) do { _Pragma("unroll") for (int n = 0; n < 2; ++n) _Pragma("unroll") for (int k = 0; k < 2; ++k) dst[n][k] = *(const PG8_LAS bf16x8*)(lds + PG8_SB(b, h) + boff + n * 2048 + k * 1024); } while (0)
; #define PG8_MMA(ai, bj, At, Bt) do { __builtin_amdgcn_s_setprio(1); _Pragma("unroll") for (int m = 0; m < 4; ++m) _Pragma("unroll") for (int n = 0; n < 2; ++n) _Pragma("unroll") for (int k = 0; k < 2; ++k) \
;         acc[ai][bj][m][n] = __builtin_amdgcn_mfma_f32_16x16x32_bf16(Bt[n][k], At[m][k], acc[ai][bj][m][n], 0, 0, 0); __builtin_amdgcn_s_setprio(0); } while (0)
; #define PG8_WAIT_V(n) asm volatile("s_waitcnt vmcnt(" #n ")" ::: "memory")
; #define PG8_WAIT_L(n) asm volatile("s_waitcnt lgkmcnt(" #n ")" ::: "memory")
; #define PG8_BAR __builtin_amdgcn_s_barrier()
; #define PG8_SCHED __builtin_amdgcn_sched_barrier(0)
; template <class Epi, class Sched, bool ALIGN_EPI = false, bool SP2 = false>
; __device__ __forceinline__ void gemm_phase(PG8_LAS unsigned char* lds, const Gemm g, const Sched& S, const Epi& E) {
;     ...
;             PG8_WAIT_V(8); PG8_WAIT_L(0); PG8_BAR; PG8_MMA(1, 0, At, B0); PG8_MMA(1, 1, At, B1); PG8_BAR; PG8_SCHED;
;             PG8_LDB(B0, 1, 0); PG8_LDB(B1, 1, 1); PG8_SCHED; PG8_LDA(At, 1, 0); PG8_STAGE(PG8_SA(0, 1), a2 + hstep, voffA);
;             PG8_WAIT_V(8); PG8_WAIT_L(0); PG8_BAR; PG8_MMA(0, 0, At, B0); PG8_MMA(0, 1, At, B1); PG8_BAR; PG8_SCHED;
	s_setprio 1
	s_waitcnt lgkmcnt(0)
	v_mfma_f32_16x16x32_bf16 v[62:65], v[140:143], v[176:179], v[62:65]
	v_mfma_f32_16x16x32_bf16 v[58:61], v[152:155], v[176:179], v[58:61]
	v_mfma_f32_16x16x32_bf16 v[46:49], v[140:143], v[184:187], v[46:49]
	v_mfma_f32_16x16x32_bf16 v[42:45], v[152:155], v[184:187], v[42:45]
	v_mfma_f32_16x16x32_bf16 v[30:33], v[140:143], v[192:195], v[30:33]
	v_mfma_f32_16x16x32_bf16 v[26:29], v[152:155], v[192:195], v[26:29]
	v_mfma_f32_16x16x32_bf16 v[14:17], v[140:143], v[200:203], v[14:17]
	v_mfma_f32_16x16x32_bf16 v[10:13], v[152:155], v[200:203], v[10:13]
	v_mfma_f32_16x16x32_bf16 v[62:65], v[144:147], v[180:183], v[62:65]
	v_mfma_f32_16x16x32_bf16 v[58:61], v[156:159], v[180:183], v[58:61]
	v_mfma_f32_16x16x32_bf16 v[46:49], v[144:147], v[188:191], v[46:49]
	v_mfma_f32_16x16x32_bf16 v[42:45], v[156:159], v[188:191], v[42:45]
	v_mfma_f32_16x16x32_bf16 v[30:33], v[144:147], v[196:199], v[30:33]
	v_mfma_f32_16x16x32_bf16 v[26:29], v[156:159], v[196:199], v[26:29]
	v_mfma_f32_16x16x32_bf16 v[14:17], v[144:147], v[210:213], v[14:17]
	v_mfma_f32_16x16x32_bf16 v[10:13], v[156:159], v[210:213], v[10:13]
	s_setprio 0
	s_setprio 1
	v_mfma_f32_16x16x32_bf16 v[54:57], v[160:163], v[176:179], v[54:57]
	v_mfma_f32_16x16x32_bf16 v[50:53], v[168:171], v[176:179], v[50:53]
	v_mfma_f32_16x16x32_bf16 v[38:41], v[160:163], v[184:187], v[38:41]
	v_mfma_f32_16x16x32_bf16 v[34:37], v[168:171], v[184:187], v[34:37]
	v_mfma_f32_16x16x32_bf16 v[22:25], v[160:163], v[192:195], v[22:25]
	v_mfma_f32_16x16x32_bf16 v[18:21], v[168:171], v[192:195], v[18:21]
	v_mfma_f32_16x16x32_bf16 v[6:9], v[160:163], v[200:203], v[6:9]
	v_mfma_f32_16x16x32_bf16 v[2:5], v[168:171], v[200:203], v[2:5]
	v_mfma_f32_16x16x32_bf16 v[54:57], v[164:167], v[180:183], v[54:57]
	v_mfma_f32_16x16x32_bf16 v[50:53], v[172:175], v[180:183], v[50:53]
	v_mfma_f32_16x16x32_bf16 v[38:41], v[164:167], v[188:191], v[38:41]
	v_mfma_f32_16x16x32_bf16 v[34:37], v[172:175], v[188:191], v[34:37]
	v_mfma_f32_16x16x32_bf16 v[22:25], v[164:167], v[196:199], v[22:25]
	v_mfma_f32_16x16x32_bf16 v[18:21], v[172:175], v[196:199], v[18:21]
	v_mfma_f32_16x16x32_bf16 v[6:9], v[164:167], v[210:213], v[6:9]
	v_mfma_f32_16x16x32_bf16 v[2:5], v[172:175], v[210:213], v[2:5]
	s_setprio 0
	s_barrier
	s_add_i32 s43, 0, 0x18000
	s_add_i32 s45, 0, 0x1c000
	v_add_u32_e32 v156, s43, v149
	v_add_u32_e32 v172, s45, v149
	ds_read_b128 v[140:143], v156
	ds_read_b128 v[144:147], v156 offset:1024
	ds_read_b128 v[152:155], v156 offset:2048
	ds_read_b128 v[156:159], v156 offset:3072
	ds_read_b128 v[160:163], v172
	ds_read_b128 v[164:167], v172 offset:1024
	ds_read_b128 v[168:171], v172 offset:2048
	ds_read_b128 v[172:175], v172 offset:3072
	s_add_u32 s28, s28, 0x40000
	s_addc_u32 s29, s29, 0
	s_mov_b32 m0, s52
	ds_read_b128 v[176:179], v151 offset:32768
	ds_read_b128 v[180:183], v151 offset:33792
	ds_read_b128 v[184:187], v151 offset:34816
	ds_read_b128 v[188:191], v151 offset:35840
	ds_read_b128 v[192:195], v151 offset:36864
	ds_read_b128 v[196:199], v151 offset:37888
	ds_read_b128 v[200:203], v151 offset:38912
	ds_read_b128 v[210:213], v151 offset:39936
	global_load_lds_dwordx4 v130, s[28:29]
	s_mov_b32 m0, s53
	s_nop 0
	global_load_lds_dwordx4 v132, s[28:29]
	s_waitcnt vmcnt(8)
	s_waitcnt lgkmcnt(0)
	s_barrier
	s_setprio 1
	s_waitcnt lgkmcnt(0)
	v_mfma_f32_16x16x32_bf16 v[126:129], v[140:143], v[176:179], v[126:129]
	v_mfma_f32_16x16x32_bf16 v[122:125], v[152:155], v[176:179], v[122:125]
	v_mfma_f32_16x16x32_bf16 v[110:113], v[140:143], v[184:187], v[110:113]
	v_mfma_f32_16x16x32_bf16 v[106:109], v[152:155], v[184:187], v[106:109]
	v_mfma_f32_16x16x32_bf16 v[94:97], v[140:143], v[192:195], v[94:97]
	v_mfma_f32_16x16x32_bf16 v[90:93], v[152:155], v[192:195], v[90:93]
	v_mfma_f32_16x16x32_bf16 v[78:81], v[140:143], v[200:203], v[78:81]
	v_mfma_f32_16x16x32_bf16 v[74:77], v[152:155], v[200:203], v[74:77]
	v_mfma_f32_16x16x32_bf16 v[126:129], v[144:147], v[180:183], v[126:129]
	v_mfma_f32_16x16x32_bf16 v[122:125], v[156:159], v[180:183], v[122:125]
	v_mfma_f32_16x16x32_bf16 v[110:113], v[144:147], v[188:191], v[110:113]
	v_mfma_f32_16x16x32_bf16 v[106:109], v[156:159], v[188:191], v[106:109]
	v_mfma_f32_16x16x32_bf16 v[94:97], v[144:147], v[196:199], v[94:97]
	v_mfma_f32_16x16x32_bf16 v[90:93], v[156:159], v[196:199], v[90:93]
	v_mfma_f32_16x16x32_bf16 v[78:81], v[144:147], v[210:213], v[78:81]
	v_mfma_f32_16x16x32_bf16 v[74:77], v[156:159], v[210:213], v[74:77]
	s_setprio 0
	s_setprio 1
	v_mfma_f32_16x16x32_bf16 v[118:121], v[160:163], v[176:179], v[118:121]
	v_mfma_f32_16x16x32_bf16 v[114:117], v[168:171], v[176:179], v[114:117]
	v_mfma_f32_16x16x32_bf16 v[102:105], v[160:163], v[184:187], v[102:105]
	v_mfma_f32_16x16x32_bf16 v[98:101], v[168:171], v[184:187], v[98:101]
	v_mfma_f32_16x16x32_bf16 v[86:89], v[160:163], v[192:195], v[86:89]
	v_mfma_f32_16x16x32_bf16 v[82:85], v[168:171], v[192:195], v[82:85]
	v_mfma_f32_16x16x32_bf16 v[70:73], v[160:163], v[200:203], v[70:73]
	v_mfma_f32_16x16x32_bf16 v[66:69], v[168:171], v[200:203], v[66:69]
	v_mfma_f32_16x16x32_bf16 v[118:121], v[164:167], v[180:183], v[118:121]
	v_mfma_f32_16x16x32_bf16 v[114:117], v[172:175], v[180:183], v[114:117]
	v_mfma_f32_16x16x32_bf16 v[102:105], v[164:167], v[188:191], v[102:105]
	v_mfma_f32_16x16x32_bf16 v[98:101], v[172:175], v[188:191], v[98:101]
	v_mfma_f32_16x16x32_bf16 v[86:89], v[164:167], v[196:199], v[86:89]
	v_mfma_f32_16x16x32_bf16 v[82:85], v[172:175], v[196:199], v[82:85]
	v_mfma_f32_16x16x32_bf16 v[70:73], v[164:167], v[210:213], v[70:73]
	v_mfma_f32_16x16x32_bf16 v[66:69], v[172:175], v[210:213], v[66:69]
	s_setprio 0
	s_barrier
; #define PG8_STAGE(bufoff, gbase, voff) do { _Pragma("unroll") for (int _i = 0; _i < 2; ++_i) \
;         __builtin_amdgcn_global_load_lds((const unsigned*)((const char*)(gbase) + (voff)[_i]), (PG8_LAS unsigned*)(lds + (bufoff) + ldsw + _i * 8192), 16, 0, 0); } while (0)
; #define PG8_LDA(dst, b, h) do { _Pragma("unroll") for (int m = 0; m < 4; ++m) _Pragma("unroll") for (int k = 0; k < 2; ++k) dst[m][k] = *(const PG8_LAS bf16x8*)(lds + PG8_SA(b, h) + aoff + m * 2048 + k * 1024); } while (0)
; #define PG8_MMA(ai, bj, At, Bt) do { __builtin_amdgcn_s_setprio(1); _Pragma("unroll") for (int m = 0; m < 4; ++m) _Pragma("unroll") for (int n = 0; n < 2; ++n) _Pragma("unroll") for (int k = 0; k < 2; ++k) \
;         acc[ai][bj][m][n] = __builtin_amdgcn_mfma_f32_16x16x32_bf16(Bt[n][k], At[m][k], acc[ai][bj][m][n], 0, 0, 0); __builtin_amdgcn_s_setprio(0); } while (0)
; #define PG8_WAIT_V(n) asm volatile("s_waitcnt vmcnt(" #n ")" ::: "memory")
; #define PG8_WAIT_L(n) asm volatile("s_waitcnt lgkmcnt(" #n ")" ::: "memory")
; #define PG8_BAR __builtin_amdgcn_s_barrier()
; #define PG8_SCHED __builtin_amdgcn_sched_barrier(0)
; template <class Epi, class Sched, bool ALIGN_EPI = false, bool SP2 = false>
; __device__ __forceinline__ void gemm_phase(PG8_LAS unsigned char* lds, const Gemm g, const Sched& S, const Epi& E) {
;     ...
;             PG8_LDA(At, 1, 1); PG8_STAGE(PG8_SB(1, 0), b3, voffB); PG8_STAGE(PG8_SB(1, 1), b3 + hstep, voffB); PG8_STAGE(PG8_SA(1, 0), a3, voffA);
;             PG8_WAIT_V(8); PG8_WAIT_L(0); PG8_BAR; PG8_MMA(1, 0, At, B0); PG8_MMA(1, 1, At, B1); PG8_BAR; PG8_SCHED;
	s_add_i32 s28, s43, s37
	v_lshl_add_u64 v[204:205], v[204:205], 0, s[60:61]
	s_mov_b32 m0, s28
	ds_read_b128 v[176:179], v151 offset:49152
	ds_read_b128 v[180:183], v151 offset:50176
	ds_read_b128 v[184:187], v151 offset:51200
	ds_read_b128 v[188:191], v151 offset:52224
	ds_read_b128 v[192:195], v151 offset:53248
	ds_read_b128 v[196:199], v151 offset:54272
	ds_read_b128 v[200:203], v151 offset:55296
	ds_read_b128 v[210:213], v151 offset:56320
	global_load_lds_dwordx4 v[204:205], off
	s_add_i32 m0, s28, 0x2000
	s_add_u32 s26, s26, 0x40080
	v_lshl_add_u64 v[204:205], v[206:207], 0, s[60:61]
	s_addc_u32 s27, s27, 0
	s_add_i32 s28, s45, s37
	global_load_lds_dwordx4 v[204:205], off
	s_mov_b32 m0, s28
	s_nop 0
	global_load_lds_dwordx4 v0, s[26:27]
	s_add_i32 m0, s28, 0x2000
	s_nop 0
	global_load_lds_dwordx4 v134, s[26:27]
	v_lshl_add_u64 v[204:205], v[214:215], 0, s[60:61]
	s_mov_b32 m0, s75
	s_nop 0
	global_load_lds_dwordx4 v[204:205], off
	v_lshl_add_u64 v[204:205], v[216:217], 0, s[60:61]
	s_mov_b32 m0, s80
	s_nop 0
	global_load_lds_dwordx4 v[204:205], off
	s_waitcnt vmcnt(8)
	s_waitcnt lgkmcnt(0)
	s_barrier
	s_setprio 1
	s_waitcnt lgkmcnt(0)
	v_mfma_f32_16x16x32_bf16 v[62:65], v[140:143], v[176:179], v[62:65]
	v_mfma_f32_16x16x32_bf16 v[58:61], v[152:155], v[176:179], v[58:61]
	v_mfma_f32_16x16x32_bf16 v[46:49], v[140:143], v[184:187], v[46:49]
	v_mfma_f32_16x16x32_bf16 v[42:45], v[152:155], v[184:187], v[42:45]
	v_mfma_f32_16x16x32_bf16 v[30:33], v[140:143], v[192:195], v[30:33]
	v_mfma_f32_16x16x32_bf16 v[26:29], v[152:155], v[192:195], v[26:29]
	v_mfma_f32_16x16x32_bf16 v[14:17], v[140:143], v[200:203], v[14:17]
	v_mfma_f32_16x16x32_bf16 v[10:13], v[152:155], v[200:203], v[10:13]
	v_mfma_f32_16x16x32_bf16 v[62:65], v[144:147], v[180:183], v[62:65]
	v_mfma_f32_16x16x32_bf16 v[58:61], v[156:159], v[180:183], v[58:61]
	v_mfma_f32_16x16x32_bf16 v[46:49], v[144:147], v[188:191], v[46:49]
	v_mfma_f32_16x16x32_bf16 v[42:45], v[156:159], v[188:191], v[42:45]
	v_mfma_f32_16x16x32_bf16 v[30:33], v[144:147], v[196:199], v[30:33]
	v_mfma_f32_16x16x32_bf16 v[26:29], v[156:159], v[196:199], v[26:29]
	v_mfma_f32_16x16x32_bf16 v[14:17], v[144:147], v[210:213], v[14:17]
	v_mfma_f32_16x16x32_bf16 v[10:13], v[156:159], v[210:213], v[10:13]
	s_setprio 0
	s_setprio 1
	v_mfma_f32_16x16x32_bf16 v[54:57], v[160:163], v[176:179], v[54:57]
	v_mfma_f32_16x16x32_bf16 v[50:53], v[168:171], v[176:179], v[50:53]
	v_mfma_f32_16x16x32_bf16 v[38:41], v[160:163], v[184:187], v[38:41]
	v_mfma_f32_16x16x32_bf16 v[34:37], v[168:171], v[184:187], v[34:37]
	v_mfma_f32_16x16x32_bf16 v[22:25], v[160:163], v[192:195], v[22:25]
	v_mfma_f32_16x16x32_bf16 v[18:21], v[168:171], v[192:195], v[18:21]
	v_mfma_f32_16x16x32_bf16 v[6:9], v[160:163], v[200:203], v[6:9]
	v_mfma_f32_16x16x32_bf16 v[2:5], v[168:171], v[200:203], v[2:5]
	v_mfma_f32_16x16x32_bf16 v[54:57], v[164:167], v[180:183], v[54:57]
	v_mfma_f32_16x16x32_bf16 v[50:53], v[172:175], v[180:183], v[50:53]
	v_mfma_f32_16x16x32_bf16 v[38:41], v[164:167], v[188:191], v[38:41]
	v_mfma_f32_16x16x32_bf16 v[34:37], v[172:175], v[188:191], v[34:37]
	v_mfma_f32_16x16x32_bf16 v[22:25], v[164:167], v[196:199], v[22:25]
	v_mfma_f32_16x16x32_bf16 v[18:21], v[172:175], v[196:199], v[18:21]
	v_mfma_f32_16x16x32_bf16 v[6:9], v[164:167], v[210:213], v[6:9]
	v_mfma_f32_16x16x32_bf16 v[2:5], v[172:175], v[210:213], v[2:5]
	s_setprio 0
	s_barrier
	s_add_i32 s42, s42, 2
	s_add_u32 s24, s24, 0x100
	s_addc_u32 s25, s25, 0
	s_add_u32 s31, s31, 0x100
	s_addc_u32 s33, s33, 0
	s_cmp_gt_u32 s42, 13
	s_cbranch_scc0 .LBB0_208
	s_and_b64 vcc, exec, s[6:7]
	s_cbranch_vccz .LBB0_211
	s_barrier

; #define PG8_STAGE(bufoff, gbase, voff) do { _Pragma("unroll") for (int _i = 0; _i < 2; ++_i) \
;         __builtin_amdgcn_global_load_lds((const unsigned*)((const char*)(gbase) + (voff)[_i]), (PG8_LAS unsigned*)(lds + (bufoff) + ldsw + _i * 8192), 16, 0, 0); } while (0)
; #define PG8_LDA(dst, b, h) do { _Pragma("unroll") for (int m = 0; m < 4; ++m) _Pragma("unroll") for (int k = 0; k < 2; ++k) dst[m][k] = *(const PG8_LAS bf16x8*)(lds + PG8_SA(b, h) + aoff + m * 2048 + k * 1024); } while (0)
; #define PG8_LDB(dst, b, h) do { _Pragma("unroll") for (int n = 0; n < 2; ++n) _Pragma("unroll") for (int k = 0; k < 2; ++k) dst[n][k] = *(const PG8_LAS bf16x8*)(lds + PG8_SB(b, h) + boff + n * 2048 + k * 1024); } while (0)
; #define PG8_MMA(ai, bj, At, Bt) do { __builtin_amdgcn_s_setprio(1); _Pragma("unroll") for (int m = 0; m < 4; ++m) _Pragma("unroll") for (int n = 0; n < 2; ++n) _Pragma("unroll") for (int k = 0; k < 2; ++k) \
;         acc[ai][bj][m][n] = __builtin_amdgcn_mfma_f32_16x16x32_bf16(Bt[n][k], At[m][k], acc[ai][bj][m][n], 0, 0, 0); __builtin_amdgcn_s_setprio(0); } while (0)
; #define PG8_WAIT_V(n) asm volatile("s_waitcnt vmcnt(" #n ")" ::: "memory")
; #define PG8_WAIT_L(n) asm volatile("s_waitcnt lgkmcnt(" #n ")" ::: "memory")
; #define PG8_BAR __builtin_amdgcn_s_barrier()
; #define PG8_SCHED __builtin_amdgcn_sched_barrier(0)
; template <class Epi, class Sched, bool ALIGN_EPI = false, bool SP2 = false>
; __device__ __forceinline__ void gemm_phase(PG8_LAS unsigned char* lds, const Gemm g, const Sched& S, const Epi& E) {
;     ...
;             const bool last = (t == nt - 2);
;             const char* a1 = cA + (size_t)(t + 1) * kstep;
;             const char* a2 = last ? nA : cA + (size_t)(t + 2) * kstep; const char* b2 = last ? nB : cB + (size_t)(t + 2) * kstep;
;             const char* a3 = a2 + kstep; const char* b3 = b2 + kstep;
;             if (last && has_next) S.a_ready(nxt);
;             if constexpr (SP2) {
;             PG8_LDB(B0, 0, 0); PG8_LDB(B1, 0, 1); PG8_SCHED; PG8_LDA(At, 0, 0); PG8_STAGE(PG8_SA(1, 1), a1 + hstep, voffA);
;             PG8_WAIT_V(8); PG8_WAIT_L(0); PG8_BAR; PG8_MMA(0, 0, At, B0); PG8_MMA(0, 1, At, B1); PG8_BAR; PG8_SCHED;
;             PG8_LDA(At, 0, 1); PG8_STAGE(PG8_SB(0, 0), b2, voffB); PG8_STAGE(PG8_SB(0, 1), b2 + hstep, voffB); PG8_STAGE(PG8_SA(0, 0), a2, voffA);
.LBB0_376:
	s_add_u32 s20, s18, 0xfffc0080
	s_addc_u32 s21, s19, -1
	s_add_i32 s46, 0, 0x10000
	s_cmp_eq_u32 s45, 12
	s_cselect_b32 s23, s7, s21
	s_cselect_b32 s22, s41, s20
	v_add_u32_e32 v140, s46, v143
	s_cselect_b32 s21, s5, s43
	s_cselect_b32 s20, s42, s31
	s_add_i32 s52, 0, 0x14000
	ds_read_b128 v[146:149], v140
	ds_read_b128 v[150:153], v140 offset:1024
	ds_read_b128 v[154:157], v140 offset:2048
	ds_read_b128 v[158:161], v140 offset:3072
	v_add_u32_e32 v140, s52, v143
	ds_read_b128 v[162:165], v140
	ds_read_b128 v[166:169], v140 offset:1024
	ds_read_b128 v[170:173], v140 offset:2048
	ds_read_b128 v[174:177], v140 offset:3072
	s_add_i32 m0, s26, 0xc000
	ds_read_b128 v[178:181], v145
	ds_read_b128 v[182:185], v145 offset:1024
	ds_read_b128 v[186:189], v145 offset:2048
	ds_read_b128 v[190:193], v145 offset:3072
	ds_read_b128 v[194:197], v145 offset:4096
	ds_read_b128 v[198:201], v145 offset:5120
	ds_read_b128 v[202:205], v145 offset:6144
	ds_read_b128 v[210:213], v145 offset:7168
	global_load_lds_dwordx4 v136, s[18:19]
	s_add_i32 m0, s26, 0xe000
	s_nop 0
	global_load_lds_dwordx4 v138, s[18:19]
	s_waitcnt vmcnt(8)
	s_waitcnt lgkmcnt(0)
	s_barrier
	s_setprio 1
	s_waitcnt lgkmcnt(0)
	v_mfma_f32_16x16x32_bf16 v[126:129], v[146:149], v[178:181], v[126:129]
	v_mfma_f32_16x16x32_bf16 v[122:125], v[154:157], v[178:181], v[122:125]
	v_mfma_f32_16x16x32_bf16 v[114:117], v[146:149], v[186:189], v[114:117]
	v_mfma_f32_16x16x32_bf16 v[106:109], v[154:157], v[186:189], v[106:109]
	v_mfma_f32_16x16x32_bf16 v[98:101], v[146:149], v[194:197], v[98:101]
	v_mfma_f32_16x16x32_bf16 v[90:93], v[154:157], v[194:197], v[90:93]
	v_mfma_f32_16x16x32_bf16 v[82:85], v[146:149], v[202:205], v[82:85]
	v_mfma_f32_16x16x32_bf16 v[74:77], v[154:157], v[202:205], v[74:77]
	v_mfma_f32_16x16x32_bf16 v[126:129], v[150:153], v[182:185], v[126:129]
	v_mfma_f32_16x16x32_bf16 v[122:125], v[158:161], v[182:185], v[122:125]
	v_mfma_f32_16x16x32_bf16 v[114:117], v[150:153], v[190:193], v[114:117]
	v_mfma_f32_16x16x32_bf16 v[106:109], v[158:161], v[190:193], v[106:109]
	v_mfma_f32_16x16x32_bf16 v[98:101], v[150:153], v[198:201], v[98:101]
	v_mfma_f32_16x16x32_bf16 v[90:93], v[158:161], v[198:201], v[90:93]
	v_mfma_f32_16x16x32_bf16 v[82:85], v[150:153], v[210:213], v[82:85]
	v_mfma_f32_16x16x32_bf16 v[74:77], v[158:161], v[210:213], v[74:77]
	s_setprio 0
	s_setprio 1
	v_mfma_f32_16x16x32_bf16 v[118:121], v[162:165], v[178:181], v[118:121]
	v_mfma_f32_16x16x32_bf16 v[110:113], v[170:173], v[178:181], v[110:113]
	v_mfma_f32_16x16x32_bf16 v[102:105], v[162:165], v[186:189], v[102:105]
	v_mfma_f32_16x16x32_bf16 v[94:97], v[170:173], v[186:189], v[94:97]
	v_mfma_f32_16x16x32_bf16 v[86:89], v[162:165], v[194:197], v[86:89]
	v_mfma_f32_16x16x32_bf16 v[78:81], v[170:173], v[194:197], v[78:81]
	v_mfma_f32_16x16x32_bf16 v[70:73], v[162:165], v[202:205], v[70:73]
	v_mfma_f32_16x16x32_bf16 v[66:69], v[170:173], v[202:205], v[66:69]
	v_mfma_f32_16x16x32_bf16 v[118:121], v[166:169], v[182:185], v[118:121]
	v_mfma_f32_16x16x32_bf16 v[110:113], v[174:177], v[182:185], v[110:113]
	v_mfma_f32_16x16x32_bf16 v[102:105], v[166:169], v[190:193], v[102:105]
	v_mfma_f32_16x16x32_bf16 v[94:97], v[174:177], v[190:193], v[94:97]
	v_mfma_f32_16x16x32_bf16 v[86:89], v[166:169], v[198:201], v[86:89]
	v_mfma_f32_16x16x32_bf16 v[78:81], v[174:177], v[198:201], v[78:81]
	v_mfma_f32_16x16x32_bf16 v[70:73], v[166:169], v[210:213], v[70:73]
	v_mfma_f32_16x16x32_bf16 v[66:69], v[174:177], v[210:213], v[66:69]
	s_setprio 0
	s_barrier
	s_add_i32 s46, s46, s24
	v_lshl_add_u64 v[140:141], s[20:21], 0, v[0:1]
	s_mov_b32 m0, s46
	ds_read_b128 v[178:181], v145 offset:16384
	ds_read_b128 v[182:185], v145 offset:17408
	ds_read_b128 v[186:189], v145 offset:18432
	ds_read_b128 v[190:193], v145 offset:19456
	ds_read_b128 v[194:197], v145 offset:20480
	ds_read_b128 v[198:201], v145 offset:21504
	ds_read_b128 v[202:205], v145 offset:22528
	ds_read_b128 v[210:213], v145 offset:23552
	global_load_lds_dwordx4 v[140:141], off
	s_add_i32 m0, s46, 0x2000
	s_add_u32 s46, s20, 0x40000
	v_lshl_add_u64 v[206:207], s[20:21], 0, v[130:131]
	s_addc_u32 s47, s21, 0
	s_add_i32 s52, s52, s24
	global_load_lds_dwordx4 v[206:207], off
	s_mov_b32 m0, s52
	v_lshl_add_u64 v[216:217], s[22:23], 0, v[132:133]
	global_load_lds_dwordx4 v0, s[46:47]
	s_add_i32 m0, s52, 0x2000
	s_nop 0
	global_load_lds_dwordx4 v130, s[46:47]
	v_lshl_add_u64 v[214:215], s[22:23], 0, v[134:135]
	s_mov_b32 m0, s26
	s_nop 0
	global_load_lds_dwordx4 v[214:215], off
	s_mov_b32 m0, s27
	s_nop 0
	global_load_lds_dwordx4 v[216:217], off
	s_waitcnt vmcnt(8)
	s_waitcnt lgkmcnt(0)
	s_barrier
; #define PG8_STAGE(bufoff, gbase, voff) do { _Pragma("unroll") for (int _i = 0; _i < 2; ++_i) \
;         __builtin_amdgcn_global_load_lds((const unsigned*)((const char*)(gbase) + (voff)[_i]), (PG8_LAS unsigned*)(lds + (bufoff) + ldsw + _i * 8192), 16, 0, 0); } while (0)
; #define PG8_LDA(dst, b, h) do { _Pragma("unroll") for (int m = 0; m < 4; ++m) _Pragma("unroll") for (int k = 0; k < 2; ++k) dst[m][k] = *(const PG8_LAS bf16x8*)(lds + PG8_SA(b, h) + aoff + m * 2048 + k * 1024); } while (0)
; #define PG8_LDB(dst, b, h) do { _Pragma("unroll") for (int n = 0; n < 2; ++n) _Pragma("unroll") for (int k = 0; k < 2; ++k) dst[n][k] = *(const PG8_LAS bf16x8*)(lds + PG8_SB(b, h) + boff + n * 2048 + k * 1024); } while (0)
; #define PG8_MMA(ai, bj, At, Bt) do { __builtin_amdgcn_s_setprio(1); _Pragma("unroll") for (int m = 0; m < 4; ++m) _Pragma("unroll") for (int n = 0; n < 2; ++n) _Pragma("unroll") for (int k = 0; k < 2; ++k) \
;         acc[ai][bj][m][n] = __builtin_amdgcn_mfma_f32_16x16x32_bf16(Bt[n][k], At[m][k], acc[ai][bj][m][n], 0, 0, 0); __builtin_amdgcn_s_setprio(0); } while (0)
; #define PG8_WAIT_V(n) asm volatile("s_waitcnt vmcnt(" #n ")" ::: "memory")
; #define PG8_WAIT_L(n) asm volatile("s_waitcnt lgkmcnt(" #n ")" ::: "memory")
; #define PG8_BAR __builtin_amdgcn_s_barrier()
; #define PG8_SCHED __builtin_amdgcn_sched_barrier(0)
; template <class Epi, class Sched, bool ALIGN_EPI = false, bool SP2 = false>
; __device__ __forceinline__ void gemm_phase(PG8_LAS unsigned char* lds, const Gemm g, const Sched& S, const Epi& E) {
;     ...
;             PG8_WAIT_V(8); PG8_WAIT_L(0); PG8_BAR; PG8_MMA(1, 0, At, B0); PG8_MMA(1, 1, At, B1); PG8_BAR; PG8_SCHED;
;             PG8_LDB(B0, 1, 0); PG8_LDB(B1, 1, 1); PG8_SCHED; PG8_LDA(At, 1, 0); PG8_STAGE(PG8_SA(0, 1), a2 + hstep, voffA);
;             PG8_WAIT_V(8); PG8_WAIT_L(0); PG8_BAR; PG8_MMA(0, 0, At, B0); PG8_MMA(0, 1, At, B1); PG8_BAR; PG8_SCHED;
	s_setprio 1
	s_waitcnt lgkmcnt(0)
	v_mfma_f32_16x16x32_bf16 v[62:65], v[146:149], v[178:181], v[62:65]
	v_mfma_f32_16x16x32_bf16 v[58:61], v[154:157], v[178:181], v[58:61]
	v_mfma_f32_16x16x32_bf16 v[50:53], v[146:149], v[186:189], v[50:53]
	v_mfma_f32_16x16x32_bf16 v[42:45], v[154:157], v[186:189], v[42:45]
	v_mfma_f32_16x16x32_bf16 v[34:37], v[146:149], v[194:197], v[34:37]
	v_mfma_f32_16x16x32_bf16 v[26:29], v[154:157], v[194:197], v[26:29]
	v_mfma_f32_16x16x32_bf16 v[18:21], v[146:149], v[202:205], v[18:21]
	v_mfma_f32_16x16x32_bf16 v[10:13], v[154:157], v[202:205], v[10:13]
	v_mfma_f32_16x16x32_bf16 v[62:65], v[150:153], v[182:185], v[62:65]
	v_mfma_f32_16x16x32_bf16 v[58:61], v[158:161], v[182:185], v[58:61]
	v_mfma_f32_16x16x32_bf16 v[50:53], v[150:153], v[190:193], v[50:53]
	v_mfma_f32_16x16x32_bf16 v[42:45], v[158:161], v[190:193], v[42:45]
	v_mfma_f32_16x16x32_bf16 v[34:37], v[150:153], v[198:201], v[34:37]
	v_mfma_f32_16x16x32_bf16 v[26:29], v[158:161], v[198:201], v[26:29]
	v_mfma_f32_16x16x32_bf16 v[18:21], v[150:153], v[210:213], v[18:21]
	v_mfma_f32_16x16x32_bf16 v[10:13], v[158:161], v[210:213], v[10:13]
	s_setprio 0
	s_setprio 1
	v_mfma_f32_16x16x32_bf16 v[54:57], v[162:165], v[178:181], v[54:57]
	v_mfma_f32_16x16x32_bf16 v[46:49], v[170:173], v[178:181], v[46:49]
	v_mfma_f32_16x16x32_bf16 v[38:41], v[162:165], v[186:189], v[38:41]
	v_mfma_f32_16x16x32_bf16 v[30:33], v[170:173], v[186:189], v[30:33]
	v_mfma_f32_16x16x32_bf16 v[22:25], v[162:165], v[194:197], v[22:25]
	v_mfma_f32_16x16x32_bf16 v[14:17], v[170:173], v[194:197], v[14:17]
	v_mfma_f32_16x16x32_bf16 v[6:9], v[162:165], v[202:205], v[6:9]
	v_mfma_f32_16x16x32_bf16 v[2:5], v[170:173], v[202:205], v[2:5]
	v_mfma_f32_16x16x32_bf16 v[54:57], v[166:169], v[182:185], v[54:57]
	v_mfma_f32_16x16x32_bf16 v[46:49], v[174:177], v[182:185], v[46:49]
	v_mfma_f32_16x16x32_bf16 v[38:41], v[166:169], v[190:193], v[38:41]
	v_mfma_f32_16x16x32_bf16 v[30:33], v[174:177], v[190:193], v[30:33]
	v_mfma_f32_16x16x32_bf16 v[22:25], v[166:169], v[198:201], v[22:25]
	v_mfma_f32_16x16x32_bf16 v[14:17], v[174:177], v[198:201], v[14:17]
	v_mfma_f32_16x16x32_bf16 v[6:9], v[166:169], v[210:213], v[6:9]
	v_mfma_f32_16x16x32_bf16 v[2:5], v[174:177], v[210:213], v[2:5]
	s_setprio 0
	s_barrier
	s_add_i32 s46, 0, 0x18000
	s_add_i32 s47, 0, 0x1c000
	v_add_u32_e32 v158, s46, v143
	v_add_u32_e32 v174, s47, v143
	ds_read_b128 v[146:149], v158
	ds_read_b128 v[150:153], v158 offset:1024
	ds_read_b128 v[154:157], v158 offset:2048
	ds_read_b128 v[158:161], v158 offset:3072
	ds_read_b128 v[162:165], v174
	ds_read_b128 v[166:169], v174 offset:1024
	ds_read_b128 v[170:173], v174 offset:2048
	ds_read_b128 v[174:177], v174 offset:3072
	s_add_u32 s22, s22, 0x40000
	s_addc_u32 s23, s23, 0
	s_mov_b32 m0, s28
	ds_read_b128 v[178:181], v145 offset:32768
	ds_read_b128 v[182:185], v145 offset:33792
	ds_read_b128 v[186:189], v145 offset:34816
	ds_read_b128 v[190:193], v145 offset:35840
	ds_read_b128 v[194:197], v145 offset:36864
	ds_read_b128 v[198:201], v145 offset:37888
	ds_read_b128 v[202:205], v145 offset:38912
	ds_read_b128 v[210:213], v145 offset:39936
	global_load_lds_dwordx4 v134, s[22:23]
	s_mov_b32 m0, s29
	s_nop 0
	global_load_lds_dwordx4 v132, s[22:23]
	s_waitcnt vmcnt(8)
	s_waitcnt lgkmcnt(0)
	s_barrier
	s_setprio 1
	s_waitcnt lgkmcnt(0)
	v_mfma_f32_16x16x32_bf16 v[126:129], v[146:149], v[178:181], v[126:129]
	v_mfma_f32_16x16x32_bf16 v[122:125], v[154:157], v[178:181], v[122:125]
	v_mfma_f32_16x16x32_bf16 v[114:117], v[146:149], v[186:189], v[114:117]
	v_mfma_f32_16x16x32_bf16 v[106:109], v[154:157], v[186:189], v[106:109]
	v_mfma_f32_16x16x32_bf16 v[98:101], v[146:149], v[194:197], v[98:101]
	v_mfma_f32_16x16x32_bf16 v[90:93], v[154:157], v[194:197], v[90:93]
	v_mfma_f32_16x16x32_bf16 v[82:85], v[146:149], v[202:205], v[82:85]
	v_mfma_f32_16x16x32_bf16 v[74:77], v[154:157], v[202:205], v[74:77]
	v_mfma_f32_16x16x32_bf16 v[126:129], v[150:153], v[182:185], v[126:129]
	v_mfma_f32_16x16x32_bf16 v[122:125], v[158:161], v[182:185], v[122:125]
	v_mfma_f32_16x16x32_bf16 v[114:117], v[150:153], v[190:193], v[114:117]
	v_mfma_f32_16x16x32_bf16 v[106:109], v[158:161], v[190:193], v[106:109]
	v_mfma_f32_16x16x32_bf16 v[98:101], v[150:153], v[198:201], v[98:101]
	v_mfma_f32_16x16x32_bf16 v[90:93], v[158:161], v[198:201], v[90:93]
	v_mfma_f32_16x16x32_bf16 v[82:85], v[150:153], v[210:213], v[82:85]
	v_mfma_f32_16x16x32_bf16 v[74:77], v[158:161], v[210:213], v[74:77]
	s_setprio 0
	s_setprio 1
	v_mfma_f32_16x16x32_bf16 v[118:121], v[162:165], v[178:181], v[118:121]
	v_mfma_f32_16x16x32_bf16 v[110:113], v[170:173], v[178:181], v[110:113]
	v_mfma_f32_16x16x32_bf16 v[102:105], v[162:165], v[186:189], v[102:105]
	v_mfma_f32_16x16x32_bf16 v[94:97], v[170:173], v[186:189], v[94:97]
	v_mfma_f32_16x16x32_bf16 v[86:89], v[162:165], v[194:197], v[86:89]
	v_mfma_f32_16x16x32_bf16 v[78:81], v[170:173], v[194:197], v[78:81]
	v_mfma_f32_16x16x32_bf16 v[70:73], v[162:165], v[202:205], v[70:73]
	v_mfma_f32_16x16x32_bf16 v[66:69], v[170:173], v[202:205], v[66:69]
	v_mfma_f32_16x16x32_bf16 v[118:121], v[166:169], v[182:185], v[118:121]
	v_mfma_f32_16x16x32_bf16 v[110:113], v[174:177], v[182:185], v[110:113]
	v_mfma_f32_16x16x32_bf16 v[102:105], v[166:169], v[190:193], v[102:105]
	v_mfma_f32_16x16x32_bf16 v[94:97], v[174:177], v[190:193], v[94:97]
	v_mfma_f32_16x16x32_bf16 v[86:89], v[166:169], v[198:201], v[86:89]
	v_mfma_f32_16x16x32_bf16 v[78:81], v[174:177], v[198:201], v[78:81]
	v_mfma_f32_16x16x32_bf16 v[70:73], v[166:169], v[210:213], v[70:73]
	v_mfma_f32_16x16x32_bf16 v[66:69], v[174:177], v[210:213], v[66:69]
	s_setprio 0
	s_barrier
; #define PG8_STAGE(bufoff, gbase, voff) do { _Pragma("unroll") for (int _i = 0; _i < 2; ++_i) \
;         __builtin_amdgcn_global_load_lds((const unsigned*)((const char*)(gbase) + (voff)[_i]), (PG8_LAS unsigned*)(lds + (bufoff) + ldsw + _i * 8192), 16, 0, 0); } while (0)
; #define PG8_LDA(dst, b, h) do { _Pragma("unroll") for (int m = 0; m < 4; ++m) _Pragma("unroll") for (int k = 0; k < 2; ++k) dst[m][k] = *(const PG8_LAS bf16x8*)(lds + PG8_SA(b, h) + aoff + m * 2048 + k * 1024); } while (0)
; #define PG8_MMA(ai, bj, At, Bt) do { __builtin_amdgcn_s_setprio(1); _Pragma("unroll") for (int m = 0; m < 4; ++m) _Pragma("unroll") for (int n = 0; n < 2; ++n) _Pragma("unroll") for (int k = 0; k < 2; ++k) \
;         acc[ai][bj][m][n] = __builtin_amdgcn_mfma_f32_16x16x32_bf16(Bt[n][k], At[m][k], acc[ai][bj][m][n], 0, 0, 0); __builtin_amdgcn_s_setprio(0); } while (0)
; #define PG8_WAIT_V(n) asm volatile("s_waitcnt vmcnt(" #n ")" ::: "memory")
; #define PG8_WAIT_L(n) asm volatile("s_waitcnt lgkmcnt(" #n ")" ::: "memory")
; #define PG8_BAR __builtin_amdgcn_s_barrier()
; #define PG8_SCHED __builtin_amdgcn_sched_barrier(0)
; template <class Epi, class Sched, bool ALIGN_EPI = false, bool SP2 = false>
; __device__ __forceinline__ void gemm_phase(PG8_LAS unsigned char* lds, const Gemm g, const Sched& S, const Epi& E) {
;     ...
;             PG8_LDA(At, 1, 1); PG8_STAGE(PG8_SB(1, 0), b3, voffB); PG8_STAGE(PG8_SB(1, 1), b3 + hstep, voffB); PG8_STAGE(PG8_SA(1, 0), a3, voffA);
;             PG8_WAIT_V(8); PG8_WAIT_L(0); PG8_BAR; PG8_MMA(1, 0, At, B0); PG8_MMA(1, 1, At, B1); PG8_BAR; PG8_SCHED;
	s_add_i32 s22, s46, s24
	v_lshl_add_u64 v[140:141], v[140:141], 0, s[60:61]
	s_mov_b32 m0, s22
	ds_read_b128 v[178:181], v145 offset:49152
	ds_read_b128 v[182:185], v145 offset:50176
	ds_read_b128 v[186:189], v145 offset:51200
	ds_read_b128 v[190:193], v145 offset:52224
	ds_read_b128 v[194:197], v145 offset:53248
	ds_read_b128 v[198:201], v145 offset:54272
	ds_read_b128 v[202:205], v145 offset:55296
	ds_read_b128 v[210:213], v145 offset:56320
	global_load_lds_dwordx4 v[140:141], off
	s_add_i32 m0, s22, 0x2000
	s_add_u32 s20, s20, 0x40080
	v_lshl_add_u64 v[140:141], v[206:207], 0, s[60:61]
	s_addc_u32 s21, s21, 0
	s_add_i32 s22, s47, s24
	global_load_lds_dwordx4 v[140:141], off
	s_mov_b32 m0, s22
	s_nop 0
	global_load_lds_dwordx4 v0, s[20:21]
	s_add_i32 m0, s22, 0x2000
	s_nop 0
	global_load_lds_dwordx4 v130, s[20:21]
	v_lshl_add_u64 v[140:141], v[214:215], 0, s[60:61]
	s_mov_b32 m0, s36
	s_nop 0
	global_load_lds_dwordx4 v[140:141], off
	v_lshl_add_u64 v[140:141], v[216:217], 0, s[60:61]
	s_mov_b32 m0, s37
	s_nop 0
	global_load_lds_dwordx4 v[140:141], off
	s_waitcnt vmcnt(8)
	s_waitcnt lgkmcnt(0)
	s_barrier
	s_setprio 1
	s_waitcnt lgkmcnt(0)
	v_mfma_f32_16x16x32_bf16 v[62:65], v[146:149], v[178:181], v[62:65]
	v_mfma_f32_16x16x32_bf16 v[58:61], v[154:157], v[178:181], v[58:61]
	v_mfma_f32_16x16x32_bf16 v[50:53], v[146:149], v[186:189], v[50:53]
	v_mfma_f32_16x16x32_bf16 v[42:45], v[154:157], v[186:189], v[42:45]
	v_mfma_f32_16x16x32_bf16 v[34:37], v[146:149], v[194:197], v[34:37]
	v_mfma_f32_16x16x32_bf16 v[26:29], v[154:157], v[194:197], v[26:29]
	v_mfma_f32_16x16x32_bf16 v[18:21], v[146:149], v[202:205], v[18:21]
	v_mfma_f32_16x16x32_bf16 v[10:13], v[154:157], v[202:205], v[10:13]
	v_mfma_f32_16x16x32_bf16 v[62:65], v[150:153], v[182:185], v[62:65]
	v_mfma_f32_16x16x32_bf16 v[58:61], v[158:161], v[182:185], v[58:61]
	v_mfma_f32_16x16x32_bf16 v[50:53], v[150:153], v[190:193], v[50:53]
	v_mfma_f32_16x16x32_bf16 v[42:45], v[158:161], v[190:193], v[42:45]
	v_mfma_f32_16x16x32_bf16 v[34:37], v[150:153], v[198:201], v[34:37]
	v_mfma_f32_16x16x32_bf16 v[26:29], v[158:161], v[198:201], v[26:29]
	v_mfma_f32_16x16x32_bf16 v[18:21], v[150:153], v[210:213], v[18:21]
	v_mfma_f32_16x16x32_bf16 v[10:13], v[158:161], v[210:213], v[10:13]
	s_setprio 0
	s_setprio 1
	v_mfma_f32_16x16x32_bf16 v[54:57], v[162:165], v[178:181], v[54:57]
	v_mfma_f32_16x16x32_bf16 v[46:49], v[170:173], v[178:181], v[46:49]
	v_mfma_f32_16x16x32_bf16 v[38:41], v[162:165], v[186:189], v[38:41]
	v_mfma_f32_16x16x32_bf16 v[30:33], v[170:173], v[186:189], v[30:33]
	v_mfma_f32_16x16x32_bf16 v[22:25], v[162:165], v[194:197], v[22:25]
	v_mfma_f32_16x16x32_bf16 v[14:17], v[170:173], v[194:197], v[14:17]
	v_mfma_f32_16x16x32_bf16 v[6:9], v[162:165], v[202:205], v[6:9]
	v_mfma_f32_16x16x32_bf16 v[2:5], v[170:173], v[202:205], v[2:5]
	v_mfma_f32_16x16x32_bf16 v[54:57], v[166:169], v[182:185], v[54:57]
	v_mfma_f32_16x16x32_bf16 v[46:49], v[174:177], v[182:185], v[46:49]
	v_mfma_f32_16x16x32_bf16 v[38:41], v[166:169], v[190:193], v[38:41]
	v_mfma_f32_16x16x32_bf16 v[30:33], v[174:177], v[190:193], v[30:33]
	v_mfma_f32_16x16x32_bf16 v[22:25], v[166:169], v[198:201], v[22:25]
	v_mfma_f32_16x16x32_bf16 v[14:17], v[174:177], v[198:201], v[14:17]
	v_mfma_f32_16x16x32_bf16 v[6:9], v[166:169], v[210:213], v[6:9]
	v_mfma_f32_16x16x32_bf16 v[2:5], v[174:177], v[210:213], v[2:5]
	s_setprio 0
	s_barrier
	s_add_i32 s45, s45, 2
	s_add_u32 s18, s18, 0x100
	s_addc_u32 s19, s19, 0
	s_add_u32 s31, s31, 0x100
	s_addc_u32 s43, s43, 0
	s_cmp_gt_u32 s45, 13
	s_cbranch_scc0 .LBB0_376
	s_and_b64 vcc, exec, s[2:3]
	s_cbranch_vccz .LBB0_379
	s_barrier

; #define WAIT_BAR(N) asm volatile("s_waitcnt vmcnt(" #N ") lgkmcnt(0)\n\ts_barrier":::"memory")
;   #define DMA_K(t,slot) glds16(ksrc+(long)(t)*KVBLK*PQ,(unsigned)__builtin_amdgcn_readfirstlane(kdst+(slot)))
;   #define DMA_V(t,slot) glds16(vsrc+(long)(t)*KVBLK*PQ,(unsigned)__builtin_amdgcn_readfirstlane(vdst+(slot)))
;   #define CMASK(P0,P1,t) do{}while(0)
;   #define START(P0,P1) do{ const float rm=rowmax(P0,P1); resc=false; \
;     { const float dl=rm; mhat=fadd_s(mhat,dl); \
;       _Pragma("unroll") for(int r=0;r<16;++r){P0[r]=fsub_s(P0[r],dl);P1[r]=fsub_s(P1[r],dl);} \
;       _Pragma("unroll") for(int r=0;r<16;++r)negm[r]=-mhat; asm volatile("":"+v"(negm)); } \
;     _Pragma("unroll") for(int r=0;r<16;++r)P0[r]=__builtin_amdgcn_exp2f(P0[r]); }while(0)
;   #define CMASK(P0,P1,t) do{}while(0)
; template<int THRL,int MODE> __device__ __forceinline__ void attn_unit128(const bf16*Qblk,const bf16*__restrict__ Kh,const bf16*__restrict__ Vh,bf16*Oblk,const int NT,char*shm,const bf16*O1blk,bf16*AOblk,const float lam,const float*sln,const float omli){
;   int tid_=threadIdx.x; asm volatile("":"+v"(tid_));
;   const int tid=tid_,lane=tid&63,r32=lane&31,hi=lane>>5; const int wid=__builtin_amdgcn_readfirstlane(tid>>6);
;   const bf16*Qw=Qblk+(long)wid*QBLK*PQ;
;   const unsigned lds0=(unsigned)(uintptr_t)shm;
;   float*wsf=(float*)(shm+LDS_WS8)+wid*64;
;   const unsigned koff=(unsigned)(lane*PQ+wid*8)*2u;
;   const unsigned voff=(unsigned)((16*(wid&3)+(lane>>2))*PQ+(wid>>2)*32+(lane&3)*8)*2u;
;   const unsigned kdst=lds0+LDS_K+wid*1024, vdst=lds0+LDS_V+wid*1024;
;     ...
;   const char*Kbase=shm+LDS_K; bf16x8 kf[8];
;   const lds_cptr shm3=(lds_cptr)shm; const lds_cptr kp0=shm3+LDS_K+hi*1024+r32*16; const lds_cptr vp0=shm3+LDS_V+((lane>>4)&1)*32+(lane&3)*8+(4*hi+((lane&15)>>2))*64;
;   DMA_K(0,0);DMA_V(0,0);DMA_K(1,SLOTB);
;   bf16x8 qr[4];
;   #pragma unroll
;   for(int d0=0;d0<4;++d0)qr[d0]=*reinterpret_cast<const bf16x8*>(&Qw[(long)r32*PQ+d0*16+hi*8]);
;   float mhat=0.f,l_reg=0.f;f32x16 o[4];o[0]=f32x16{};o[1]=f32x16{};o[2]=f32x16{};o[3]=f32x16{};f32x16 negm=f32x16{};asm volatile("":"+v"(negm));
;     ...
;   bool resc=false;
;     ...
;   f32x16 pA0,pA1,pB0,pB1;
;   int sl_prev=0,sl_cur=0,sl_next=SLOTB;
;     ...
;   DMA_K(2,2*SLOTB);
;   WAIT_BAR(4);
;   qkt(pA0,pA1,Kbase,qr,negm,r32,hi);asm volatile("s_nop 15\n\ts_nop 7":"+v"(pA0),"+v"(pA1));CMASK(pA0,pA1,0);
;   START(pA0,pA1);
.LBB0_539:
	s_and_b64 vcc, exec, s[0:1]
	s_cbranch_vccz .LBB0_504
	s_lshl_b32 s0, s35, 8
	s_ashr_i32 s17, s35, 8
	s_and_b32 s0, s0, 0x3f00
	s_bfe_u32 s42, s35, 0x20006
	s_addk_i32 s0, 0x100
	s_mul_i32 s4, s17, 0x4100
	s_mul_hi_i32 s1, s17, 0x4100
	s_add_u32 s0, s4, s0
	s_addc_u32 s1, s1, 0
	s_mul_hi_i32 s16, s17, 0x4920000
	s_mul_i32 s17, s17, 0x4920000
	s_add_u32 s4, s58, s17
	s_addc_u32 s5, s59, s16
	s_lshl_b32 s26, s42, 7
	s_lshl_b32 s19, s42, 8
	s_add_u32 s10, s4, s19
	s_addc_u32 s11, s5, 0
	s_add_u32 s36, s10, 0x800
	s_mul_i32 s6, s1, 0x1200
	s_mul_hi_u32 s7, s0, 0x1200
	s_addc_u32 s37, s11, 0
	s_add_i32 s7, s7, s6
	s_mul_i32 s6, s0, 0x1200
	s_add_u32 s6, s58, s6
	s_addc_u32 s7, s59, s7
	s_add_u32 s28, s6, s26
	s_addc_u32 s92, s7, 0
	v_mov_b32_e32 v52, v220
	s_add_u32 s4, s4, s26
	s_addc_u32 s5, s5, 0
	v_readfirstlane_b32 s6, v52
	s_ashr_i32 s80, s6, 6
	s_mul_i32 s8, s80, 0x24000
	s_mul_hi_i32 s7, s80, 0x24000
	s_add_u32 s20, s28, s8
	s_addc_u32 s21, s92, s7
	s_and_b32 s8, s6, 0x3fffffc0
	s_ashr_i32 s6, s6, 3
	s_lshl_b32 s7, s80, 4
	v_bfe_u32 v2, v52, 2, 4
	s_and_b32 s6, s6, 0x7fffffe0
	v_and_or_b32 v2, s7, 48, v2
	v_mov_b32_e32 v3, s6
	s_movk_i32 s6, 0x900
	v_mad_u32_u24 v2, v2, s6, v3
	v_lshlrev_b32_e32 v236, 3, v52
	s_lshl_b32 s6, s80, 10
	v_and_b32_e32 v233, 63, v52
	v_mov_b32_e32 v0, s7
	v_and_b32_e32 v53, 24, v236
	s_cmp_lg_u32 0, -1
	v_mad_u32_u24 v0, v233, s81, v0
	v_or_b32_e32 v2, v2, v53
	s_cselect_b32 s7, 0, 0
	v_lshlrev_b32_e32 v2, 1, v2
	s_add_i32 s22, s6, s7
	v_lshl_add_u64 v[50:51], s[4:5], 0, v[0:1]
	s_mov_b64 s[6:7], 0x400
	v_lshl_add_u64 v[212:213], v[50:51], 0, s[6:7]
	s_mov_b32 s6, m0
	s_mov_b32 m0, s22
	s_nop 0
	global_load_lds_dwordx4 v[212:213], off
	s_mov_b32 m0, s6
	v_mov_b32_e32 v0, v2
	s_add_i32 s24, s22, 0x6000
	v_lshl_add_u64 v[2:3], s[36:37], 0, v[0:1]
	s_mov_b32 s6, m0
	s_mov_b32 m0, s24
	s_nop 0
	global_load_lds_dwordx4 v[2:3], off
	s_mov_b32 m0, s6
	s_add_u32 s6, s10, 0x880
	s_addc_u32 s7, s11, 0
	v_lshl_add_u64 v[2:3], s[6:7], 0, v[0:1]
	s_mov_b64 s[30:31], 0x48400
	v_and_b32_e32 v234, 31, v52
	v_bfe_u32 v235, v52, 5, 1
	s_add_i32 s9, s22, 0x8000
	s_mov_b32 s18, m0
	s_mov_b32 m0, s9
	s_nop 0
	global_load_lds_dwordx4 v[2:3], off
	s_mov_b32 m0, s18
	v_lshl_add_u64 v[2:3], v[50:51], 0, s[30:31]
	s_add_i32 s9, s22, 0x2000
	s_mov_b32 s18, m0
	s_mov_b32 m0, s9
	s_nop 0
	global_load_lds_dwordx4 v[2:3], off
	s_mov_b32 m0, s18
	v_mul_u32_u24_e32 v2, 0x900, v234
	v_lshlrev_b32_e32 v241, 4, v235
	v_lshl_or_b32 v2, v2, 1, v241
	global_load_dwordx4 v[190:193], v2, s[20:21]
	global_load_dwordx4 v[186:189], v2, s[20:21] offset:32
	global_load_dwordx4 v[182:185], v2, s[20:21] offset:64
	global_load_dwordx4 v[178:181], v2, s[20:21] offset:96
	v_lshlrev_b32_e32 v3, 10, v235
	v_lshlrev_b32_e32 v4, 4, v234
	v_mov_b32_e32 v18, v1
	v_mov_b32_e32 v19, v1
	v_mov_b32_e32 v20, v1
	v_mov_b32_e32 v21, v1
	v_mov_b32_e32 v22, v1
	v_mov_b32_e32 v23, v1
	v_mov_b32_e32 v24, v1
	v_mov_b32_e32 v25, v1
	v_mov_b32_e32 v26, v1
	v_mov_b32_e32 v27, v1
	v_mov_b32_e32 v28, v1
	v_mov_b32_e32 v29, v1
	v_mov_b32_e32 v30, v1
	v_mov_b32_e32 v31, v1
	v_mov_b32_e32 v32, v1
	v_mov_b32_e32 v33, v1
	s_mov_b64 s[20:21], 0x90400
	v_add3_u32 v240, 0, v3, v4
	v_lshl_add_u64 v[2:3], v[50:51], 0, s[20:21]
	s_add_i32 s9, s22, 0x4000
	s_mov_b32 s18, m0
	s_mov_b32 m0, s9
	s_nop 0
	global_load_lds_dwordx4 v[2:3], off
	s_mov_b32 m0, s18
	s_waitcnt vmcnt(4) lgkmcnt(0)
	s_barrier
	ds_read_b128 v[2:5], v240
	ds_read_b128 v[6:9], v240 offset:512
	s_lshl_b32 s8, s8, 2
	s_add_i32 s23, s8, 0
	s_mov_b64 s[8:9], 0xd8400
	s_add_i32 s23, s23, 0x12000
	v_lshlrev_b32_e32 v56, 8, v235
	s_waitcnt vmcnt(3) lgkmcnt(1)
	v_mfma_f32_32x32x16_bf16 v[34:49], v[2:5], v[190:193], v[18:33]
	s_mov_b32 s25, -1
	s_mov_b32 s18, 0
	s_movk_i32 s43, 0x2000
	s_movk_i32 s33, 0x4000
	v_cmp_gt_u32_e64 s[40:41], 32, v233
	v_lshl_add_u32 v237, v234, 2, s23
	v_mov_b32_e32 v242, 0
	s_waitcnt lgkmcnt(0)
	v_mfma_f32_32x32x16_bf16 v[18:33], v[6:9], v[190:193], v[18:33]
	ds_read_b128 v[2:5], v240 offset:2048
	ds_read_b128 v[6:9], v240 offset:2560
	ds_read_b128 v[10:13], v240 offset:4608
	ds_read_b128 v[14:17], v240 offset:4096
	s_waitcnt vmcnt(2) lgkmcnt(3)
	v_mfma_f32_32x32x16_bf16 v[34:49], v[2:5], v[186:189], v[34:49]
	v_lshlrev_b32_e32 v5, 1, v52
	v_and_b32_e32 v5, 32, v5
	v_add3_u32 v58, 0, v5, v53
	v_mov_b32_e32 v2, v1
	v_mov_b32_e32 v3, v1
	v_mov_b32_e32 v4, v1
	v_mov_b32_e32 v5, v1
	s_waitcnt lgkmcnt(2)
	v_mfma_f32_32x32x16_bf16 v[18:33], v[6:9], v[186:189], v[18:33]
	v_lshlrev_b32_e32 v6, 4, v52
	v_and_b32_e32 v57, 0xc0, v6
	v_mov_b32_e32 v6, v1
	v_mov_b32_e32 v7, v1
	v_mov_b32_e32 v8, v1
	v_mov_b32_e32 v9, v1
	v_add3_u32 v238, v58, v56, v57
	s_waitcnt vmcnt(1) lgkmcnt(0)
	v_mfma_f32_32x32x16_bf16 v[34:49], v[14:17], v[182:185], v[34:49]
	ds_read_b128 v[52:55], v240 offset:6656
	ds_read_b128 v[14:17], v240 offset:6144
	v_mfma_f32_32x32x16_bf16 v[18:33], v[10:13], v[182:185], v[18:33]
	v_mov_b32_e32 v10, v1
	v_mov_b32_e32 v11, v1
	v_mov_b32_e32 v12, v1
	v_mov_b32_e32 v13, v1
	s_waitcnt vmcnt(0) lgkmcnt(0)
	v_mfma_f32_32x32x16_bf16 v[34:49], v[14:17], v[178:181], v[34:49]
	v_mov_b32_e32 v16, v1
	v_mov_b32_e32 v17, v1
	v_mov_b32_e32 v14, v1
	v_mov_b32_e32 v15, v1
	v_mfma_f32_32x32x16_bf16 v[18:33], v[52:55], v[178:181], v[18:33]
	s_nop 15
	s_nop 7
	s_nop 0
	v_max3_f32 v52, v34, v35, v18
	v_max3_f32 v53, v36, v37, v19
	s_nop 0
	v_max3_f32 v52, v52, v20, v21
	v_max3_f32 v53, v53, v40, v41
	s_nop 0
	v_max3_f32 v52, v52, v38, v39
	v_max3_f32 v53, v53, v24, v25
	s_nop 0
	v_max3_f32 v52, v52, v22, v23
	v_max3_f32 v53, v53, v44, v45
	s_nop 0
	v_max3_f32 v52, v52, v42, v43
	v_max3_f32 v53, v53, v28, v29
	s_nop 0
	v_max3_f32 v52, v52, v26, v27
	v_max3_f32 v53, v53, v48, v49
	s_nop 0
	v_max3_f32 v52, v52, v46, v47
	v_max3_f32 v53, v53, v32, v33
	s_nop 0
	v_max3_f32 v52, v52, v30, v31
	s_nop 0
	v_max_f32_e32 v52, v52, v53
	s_nop 0
	v_mov_b32_e32 v53, v52
	s_nop 1
	v_permlane32_swap_b32_e32 v52, v53
	v_max_f32_e32 v52, v52, v53
	s_nop 0
	v_add_f32_e32 v239, v1, v52
	v_sub_f32_e32 v18, v18, v52
	v_sub_f32_e32 v19, v19, v52
	v_sub_f32_e32 v34, v34, v52
	v_sub_f32_e32 v35, v35, v52
	v_sub_f32_e32 v36, v36, v52
	s_nop 0
	v_xor_b32_e32 v66, 0x80000000, v239
	v_mov_b32_e32 v67, v66
	v_mov_b32_e32 v68, v66
	v_mov_b32_e32 v69, v66
	v_mov_b32_e32 v70, v66
	v_mov_b32_e32 v71, v66
	v_mov_b32_e32 v72, v66
	v_mov_b32_e32 v73, v66
	v_mov_b32_e32 v74, v66
	v_mov_b32_e32 v75, v66
	v_mov_b32_e32 v76, v66
	v_mov_b32_e32 v77, v66
	v_mov_b32_e32 v78, v66
	v_mov_b32_e32 v79, v66
	v_mov_b32_e32 v80, v66
	v_mov_b32_e32 v81, v66
	s_waitcnt vmcnt(0) lgkmcnt(0)
	s_barrier
; #define WAIT_BAR(N) asm volatile("s_waitcnt vmcnt(" #N ") lgkmcnt(0)\n\ts_barrier":::"memory")
;   #define DMA_K(t,slot) glds16(ksrc+(long)(t)*KVBLK*PQ,(unsigned)__builtin_amdgcn_readfirstlane(kdst+(slot)))
;   #define DMA_V(t,slot) glds16(vsrc+(long)(t)*KVBLK*PQ,(unsigned)__builtin_amdgcn_readfirstlane(vdst+(slot)))
;   #define CMASK(P0,P1,t) do{}while(0)
;   #define START(P0,P1) do{ const float rm=rowmax(P0,P1); resc=false; \
;     { const float dl=rm; mhat=fadd_s(mhat,dl); \
;       _Pragma("unroll") for(int r=0;r<16;++r){P0[r]=fsub_s(P0[r],dl);P1[r]=fsub_s(P1[r],dl);} \
;       _Pragma("unroll") for(int r=0;r<16;++r)negm[r]=-mhat; asm volatile("":"+v"(negm)); } \
;     _Pragma("unroll") for(int r=0;r<16;++r)P0[r]=__builtin_amdgcn_exp2f(P0[r]); }while(0)
;   #define ROT() do{sl_prev=sl_cur;sl_cur=sl_next;sl_next=(sl_next==(NSLOT-1)*SLOTB)?0:sl_next+SLOTB;}while(0)
;   #define CMASK(P0,P1,t) do{}while(0)
;   #define CMASK(P0,P1,t) do{}while(0)
;   #define DMA_K(t,slot) glds16((const char*)Kh+(size_t)(t)*(KVBLK*PQ*2)+koff,(unsigned)__builtin_amdgcn_readfirstlane(kdst+(slot)))
;   #define DMA_V(t,slot) do{ glds16((const char*)Vh+(size_t)(t)*(KVBLK*PQ*2)+voff,(unsigned)__builtin_amdgcn_readfirstlane(vdst+2*(slot))); glds16((const char*)Vh+(size_t)(t)*(KVBLK*PQ*2)+128+voff,(unsigned)__builtin_amdgcn_readfirstlane(vdst+2*(slot)+8192)); }while(0)
;   #define CMASK(P0,P1,t) do{}while(0)
;   #define ROT() do{sl_prev=sl_cur;sl_cur=sl_next;sl_next=(sl_next==(NSLOT-1)*SLOTB)?0:sl_next+SLOTB;}while(0)
;   #define CMASK(P0,P1,t) do{}while(0)
;   #define CMASK(P0,P1,t) do{}while(0)
; template<int THRL,int MODE> __device__ __forceinline__ void attn_unit128(const bf16*Qblk,const bf16*__restrict__ Kh,const bf16*__restrict__ Vh,bf16*Oblk,const int NT,char*shm,const bf16*O1blk,bf16*AOblk,const float lam,const float*sln,const float omli){
;     ...
;   f32x16 pA0,pA1,pB0,pB1;
;   int sl_prev=0,sl_cur=0,sl_next=SLOTB;
;     ...
;   DMA_K(2,2*SLOTB);
;   WAIT_BAR(4);
;   qkt(pA0,pA1,Kbase,qr,negm,r32,hi);asm volatile("s_nop 15\n\ts_nop 7":"+v"(pA0),"+v"(pA1));CMASK(pA0,pA1,0);
;   START(pA0,pA1);
;   _Pragma("unroll") for(int r=0;r<16;++r)pA1[r]=__builtin_amdgcn_exp2f(pA1[r]);
;   WAIT_BAR(0);
;   DMA_K(3,0);DMA_V(1,SLOTB);
;   ROT();
;   kload8(kf,kp0+sl_cur);
;   WAIT_BAR(3);
;   s16x4 vlo[8],vhi[8]; u32x4 pw0,pw1,pw2,pw3;
	v_exp_f32_e32 v82, v18
	v_exp_f32_e32 v83, v19
	v_lshl_add_u64 v[18:19], v[50:51], 0, s[8:9]
	s_mov_b32 s8, m0
	s_mov_b32 m0, s22
	s_nop 0
	global_load_lds_dwordx4 v[18:19], off
	s_mov_b32 m0, s8
	s_add_u32 s8, s10, 0x48800
	s_addc_u32 s9, s11, 0
	s_add_i32 s20, s22, 0xa000
	s_add_u32 s10, s10, 0x48880
	v_lshl_add_u64 v[18:19], s[8:9], 0, v[0:1]
	s_mov_b32 s21, m0
	s_mov_b32 m0, s20
	s_nop 0
	global_load_lds_dwordx4 v[18:19], off
	s_mov_b32 m0, s21
	s_addc_u32 s11, s11, 0
	v_lshl_add_u64 v[18:19], s[10:11], 0, v[0:1]
	s_add_i32 s20, s22, 0xc000
	s_mov_b32 s21, m0
	s_mov_b32 m0, s20
	s_nop 0
	global_load_lds_dwordx4 v[18:19], off
	s_mov_b32 m0, s21
	ds_read_b128 v[114:117], v240 offset:8192
	ds_read_b128 v[198:201], v240 offset:8704
	ds_read_b128 v[202:205], v240 offset:10240
	ds_read_b128 v[194:197], v240 offset:10752
	ds_read_b128 v[158:161], v240 offset:12288
	ds_read_b128 v[154:157], v240 offset:12800
	ds_read_b128 v[150:153], v240 offset:14336
	ds_read_b128 v[146:149], v240 offset:14848
	v_sub_f32_e32 v20, v20, v52
	v_sub_f32_e32 v37, v37, v52
	v_sub_f32_e32 v21, v21, v52
	v_sub_f32_e32 v38, v38, v52
	v_sub_f32_e32 v22, v22, v52
	v_sub_f32_e32 v39, v39, v52
	v_sub_f32_e32 v23, v23, v52
	v_sub_f32_e32 v40, v40, v52
	v_sub_f32_e32 v24, v24, v52
	v_sub_f32_e32 v41, v41, v52
	v_sub_f32_e32 v25, v25, v52
	v_sub_f32_e32 v42, v42, v52
	v_sub_f32_e32 v26, v26, v52
	v_sub_f32_e32 v43, v43, v52
	v_sub_f32_e32 v27, v27, v52
	v_sub_f32_e32 v44, v44, v52
	v_sub_f32_e32 v28, v28, v52
	v_sub_f32_e32 v45, v45, v52
	v_sub_f32_e32 v29, v29, v52
	v_sub_f32_e32 v46, v46, v52
	v_sub_f32_e32 v30, v30, v52
	v_sub_f32_e32 v47, v47, v52
	v_sub_f32_e32 v31, v31, v52
	v_sub_f32_e32 v48, v48, v52
	v_sub_f32_e32 v32, v32, v52
	v_sub_f32_e32 v49, v49, v52
	v_sub_f32_e32 v33, v33, v52
	v_exp_f32_e32 v98, v34
	v_exp_f32_e32 v99, v35
	v_exp_f32_e32 v100, v36
	v_exp_f32_e32 v101, v37
	v_exp_f32_e32 v102, v38
	v_exp_f32_e32 v103, v39
	v_exp_f32_e32 v104, v40
	v_exp_f32_e32 v105, v41
	v_exp_f32_e32 v106, v42
	v_exp_f32_e32 v107, v43
	v_exp_f32_e32 v108, v44
	v_exp_f32_e32 v109, v45
	v_exp_f32_e32 v110, v46
	v_exp_f32_e32 v111, v47
	v_exp_f32_e32 v112, v48
	v_exp_f32_e32 v113, v49
	v_exp_f32_e32 v84, v20
	v_exp_f32_e32 v85, v21
	v_exp_f32_e32 v86, v22
	v_exp_f32_e32 v87, v23
	v_exp_f32_e32 v88, v24
	v_exp_f32_e32 v89, v25
	v_exp_f32_e32 v90, v26
	v_exp_f32_e32 v91, v27
	v_exp_f32_e32 v92, v28
	v_exp_f32_e32 v93, v29
	v_exp_f32_e32 v94, v30
	v_exp_f32_e32 v95, v31
	v_exp_f32_e32 v96, v32
	v_exp_f32_e32 v97, v33
	s_waitcnt vmcnt(3) lgkmcnt(0)
	s_barrier
	s_or_b32 s17, s17, s19
	s_mov_b32 s19, s54
	v_readlane_b32 s52, v255, 12
	v_readlane_b32 s53, v255, 13
	v_readlane_b32 s54, v255, 14
	s_add_u32 s27, s52, s17
	v_mov_b64_e32 v[64:65], v[16:17]
	v_mov_b64_e32 v[48:49], v[16:17]
	v_mov_b64_e32 v[32:33], v[16:17]
	s_mov_b32 s54, s19
	s_addc_u32 s35, s53, s16
	s_mov_b64 s[16:17], 0
	v_mov_b64_e32 v[62:63], v[14:15]
	v_mov_b64_e32 v[60:61], v[12:13]
	v_mov_b64_e32 v[58:59], v[10:11]
	v_mov_b64_e32 v[56:57], v[8:9]
	v_mov_b64_e32 v[54:55], v[6:7]
	v_mov_b64_e32 v[52:53], v[4:5]
	v_mov_b64_e32 v[50:51], v[2:3]
	v_mov_b64_e32 v[46:47], v[14:15]
	v_mov_b64_e32 v[44:45], v[12:13]
	v_mov_b64_e32 v[42:43], v[10:11]
	v_mov_b64_e32 v[40:41], v[8:9]
	v_mov_b64_e32 v[38:39], v[6:7]
	v_mov_b64_e32 v[36:37], v[4:5]
	v_mov_b64_e32 v[34:35], v[2:3]
	v_mov_b64_e32 v[30:31], v[14:15]
	v_mov_b64_e32 v[28:29], v[12:13]
	v_mov_b64_e32 v[26:27], v[10:11]
	v_mov_b64_e32 v[24:25], v[8:9]
	v_mov_b64_e32 v[22:23], v[6:7]
	v_mov_b64_e32 v[20:21], v[4:5]
	v_mov_b64_e32 v[18:19], v[2:3]
	v_readlane_b32 s55, v255, 15
	v_readfirstlane_b32 s100, v212
	v_readfirstlane_b32 s101, v213
.LBB0_541:
	v_mfma_f32_32x32x16_bf16 v[130:145], v[114:117], v[190:193], v[66:81]
	v_add_f32_e32 v118, v98, v99
	v_add_f32_e32 v118, v100, v118
	v_add_f32_e32 v118, v101, v118
	s_lshl_b32 s18, s18, 1
	v_add_f32_e32 v118, v102, v118
	v_add_u32_e32 v243, s18, v238
	v_add_f32_e32 v114, v103, v118
	v_cvt_pk_bf16_f32 v174, v98, v99
	v_cvt_pk_bf16_f32 v175, v100, v101
	s_nop 0
	v_add_f32_e32 v98, v104, v114
	v_mfma_f32_32x32x16_bf16 v[114:129], v[198:201], v[190:193], v[66:81]
	v_add_f32_e32 v98, v105, v98
	v_add_f32_e32 v98, v106, v98
	v_add_f32_e32 v98, v107, v98
	v_cvt_pk_bf16_f32 v176, v102, v103
	v_cvt_pk_bf16_f32 v177, v104, v105
	v_mfma_f32_32x32x16_bf16 v[130:145], v[202:205], v[186:189], v[130:145]
	v_add_f32_e32 v98, v108, v98
	v_add_f32_e32 v98, v109, v98
	v_add_f32_e32 v98, v110, v98
	v_add_f32_e32 v98, v111, v98
	v_cvt_pk_bf16_f32 v170, v106, v107
	v_cvt_pk_bf16_f32 v171, v108, v109
	v_mfma_f32_32x32x16_bf16 v[114:129], v[194:197], v[186:189], v[114:129]
	v_add_f32_e32 v98, v112, v98
	v_add_f32_e32 v98, v113, v98
	v_add_f32_e32 v98, v82, v98
	v_add_f32_e32 v98, v83, v98
	v_cvt_pk_bf16_f32 v172, v110, v111
	v_cvt_pk_bf16_f32 v173, v112, v113
	v_mfma_f32_32x32x16_bf16 v[130:145], v[158:161], v[182:185], v[130:145]
	v_add_f32_e32 v98, v84, v98
	v_add_f32_e32 v98, v85, v98
	v_add_f32_e32 v98, v86, v98
	v_add_f32_e32 v98, v87, v98
	v_cvt_pk_bf16_f32 v166, v82, v83
	v_cvt_pk_bf16_f32 v167, v84, v85
	v_mfma_f32_32x32x16_bf16 v[114:129], v[154:157], v[182:185], v[114:129]
	v_add_f32_e32 v82, v88, v98
	v_add_f32_e32 v82, v89, v82
	v_add_f32_e32 v82, v90, v82
	v_add_f32_e32 v82, v91, v82
	v_cvt_pk_bf16_f32 v168, v86, v87
	v_cvt_pk_bf16_f32 v169, v88, v89
	v_mfma_f32_32x32x16_bf16 v[130:145], v[150:153], v[178:181], v[130:145]
	v_add_f32_e32 v82, v92, v82
	v_add_f32_e32 v82, v93, v82
	v_add_f32_e32 v82, v94, v82
	v_add_f32_e32 v82, v95, v82
	v_cvt_pk_bf16_f32 v162, v90, v91
	v_cvt_pk_bf16_f32 v163, v92, v93
	v_mfma_f32_32x32x16_bf16 v[114:129], v[146:149], v[178:181], v[114:129]
	v_add_f32_e32 v82, v96, v82
	v_add_f32_e32 v82, v97, v82
	v_add_f32_e32 v242, v242, v82
	v_cvt_pk_bf16_f32 v164, v94, v95
	v_cvt_pk_bf16_f32 v165, v96, v97
	ds_read_b64_tr_b16 v[110:111], v243 offset:24576
	ds_read_b64_tr_b16 v[112:113], v243 offset:25088
	ds_read_b64_tr_b16 v[102:103], v243 offset:25600
	ds_read_b64_tr_b16 v[104:105], v243 offset:26112
	ds_read_b64_tr_b16 v[106:107], v243 offset:28672
	ds_read_b64_tr_b16 v[108:109], v243 offset:29184
	ds_read_b64_tr_b16 v[98:99], v243 offset:29696
	ds_read_b64_tr_b16 v[100:101], v243 offset:30208
	ds_read_b64_tr_b16 v[94:95], v243 offset:26624
	ds_read_b64_tr_b16 v[96:97], v243 offset:27136
	ds_read_b64_tr_b16 v[86:87], v243 offset:27648
	ds_read_b64_tr_b16 v[88:89], v243 offset:28160
	ds_read_b64_tr_b16 v[90:91], v243 offset:30720
	ds_read_b64_tr_b16 v[92:93], v243 offset:31232
	ds_read_b64_tr_b16 v[82:83], v243 offset:31744
	ds_read_b64_tr_b16 v[84:85], v243 offset:32256
	v_subrev_u32_e32 v216, s100, v212
	s_add_u32 s18, s100, s16
	s_addc_u32 s19, s101, s17
	s_add_u32 s18, s18, 0x120000
	s_addc_u32 s19, s19, 0
	s_add_i32 m0, s43, s22
	s_nop 0
	global_load_lds_dwordx4 v216, s[18:19]
	s_add_u32 s18, s27, s16
	s_addc_u32 s19, s35, s17
	s_add_u32 s18, s18, 0x6290800
	s_addc_u32 s19, s19, 0
	s_lshl_b32 s45, s33, 1
	s_add_i32 s20, s45, s24
	s_mov_b32 m0, s20
	s_nop 0
	global_load_lds_dwordx4 v0, s[18:19]
	s_addk_i32 s20, 0x1f80
	s_mov_b32 m0, s20
	s_nop 0
	global_load_lds_dwordx4 v0, s[18:19] offset:128
	v_max3_f32 v146, v130, v131, v132
	v_max3_f32 v147, v133, v134, v135
	v_max3_f32 v146, v146, v136, v137
	v_max3_f32 v147, v147, v138, v139
	v_max3_f32 v146, v146, v140, v141
	v_max3_f32 v147, v147, v142, v143
	v_max3_f32 v146, v146, v144, v145
	v_max3_f32 v147, v147, v114, v115
	v_max3_f32 v146, v146, v116, v117
	v_max3_f32 v147, v147, v118, v119
	v_max3_f32 v146, v146, v120, v121
	v_max3_f32 v147, v147, v122, v123
	v_max3_f32 v146, v146, v124, v125
	v_max3_f32 v147, v147, v126, v127
	v_max3_f32 v146, v146, v128, v129
	v_max_f32_e32 v146, v146, v147
	v_mov_b32_e32 v147, v146
	s_nop 1
	v_permlane32_swap_b32_e32 v146, v147
	v_max_f32_e32 v146, v146, v147
	v_cmp_lt_f32_e32 vcc, s15, v146
	s_cmp_lg_u64 vcc, 0
	s_cselect_b64 s[18:19], -1, 0
	s_cbranch_vccnz .LBB0_549

.LBB0_544:
	s_add_i32 s18, s33, 0x2000
	s_cmpk_lg_i32 s33, 0x4000
	s_cselect_b32 s46, s18, 0
	v_mfma_f32_32x32x16_bf16 v[98:113], v[82:85], v[190:193], v[66:81]
	v_add_f32_e32 v86, v130, v131
	v_add_f32_e32 v86, v132, v86
	v_add_f32_e32 v86, v133, v86
	s_lshl_b32 s18, s43, 1
	v_add_f32_e32 v86, v134, v86
	v_add_u32_e32 v243, s18, v238
	v_add_f32_e32 v82, v135, v86
	v_cvt_pk_bf16_f32 v174, v130, v131
	v_cvt_pk_bf16_f32 v175, v132, v133
	s_nop 0
	v_add_f32_e32 v82, v136, v82
	v_add_f32_e32 v82, v137, v82
	v_add_f32_e32 v82, v138, v82
	v_add_f32_e32 v130, v139, v82
	v_mfma_f32_32x32x16_bf16 v[82:97], v[198:201], v[190:193], v[66:81]
	v_cvt_pk_bf16_f32 v176, v134, v135
	v_cvt_pk_bf16_f32 v177, v136, v137
	v_mfma_f32_32x32x16_bf16 v[98:113], v[202:205], v[186:189], v[98:113]
	v_add_f32_e32 v130, v140, v130
	v_add_f32_e32 v130, v141, v130
	v_add_f32_e32 v130, v142, v130
	v_add_f32_e32 v130, v143, v130
	v_cvt_pk_bf16_f32 v170, v138, v139
	v_cvt_pk_bf16_f32 v171, v140, v141
	v_mfma_f32_32x32x16_bf16 v[82:97], v[194:197], v[186:189], v[82:97]
	v_add_f32_e32 v130, v144, v130
	v_add_f32_e32 v130, v145, v130
	v_add_f32_e32 v130, v114, v130
	v_add_f32_e32 v130, v115, v130
	v_cvt_pk_bf16_f32 v172, v142, v143
	v_cvt_pk_bf16_f32 v173, v144, v145
	v_mfma_f32_32x32x16_bf16 v[98:113], v[158:161], v[182:185], v[98:113]
	v_add_f32_e32 v130, v116, v130
	v_add_f32_e32 v130, v117, v130
	v_add_f32_e32 v130, v118, v130
	v_add_f32_e32 v130, v119, v130
	v_cvt_pk_bf16_f32 v166, v114, v115
	v_cvt_pk_bf16_f32 v167, v116, v117
	v_mfma_f32_32x32x16_bf16 v[82:97], v[154:157], v[182:185], v[82:97]
	v_add_f32_e32 v114, v120, v130
	v_add_f32_e32 v114, v121, v114
	v_add_f32_e32 v114, v122, v114
	v_add_f32_e32 v114, v123, v114
	v_cvt_pk_bf16_f32 v168, v118, v119
	v_cvt_pk_bf16_f32 v169, v120, v121
	v_mfma_f32_32x32x16_bf16 v[98:113], v[150:153], v[178:181], v[98:113]
	v_add_f32_e32 v114, v124, v114
	v_add_f32_e32 v114, v125, v114
	v_add_f32_e32 v114, v126, v114
	v_add_f32_e32 v114, v127, v114
	v_cvt_pk_bf16_f32 v162, v122, v123
	v_cvt_pk_bf16_f32 v163, v124, v125
	v_mfma_f32_32x32x16_bf16 v[82:97], v[146:149], v[178:181], v[82:97]
	v_add_f32_e32 v114, v128, v114
	v_add_f32_e32 v114, v129, v114
	v_add_f32_e32 v242, v242, v114
	v_cvt_pk_bf16_f32 v164, v126, v127
	v_cvt_pk_bf16_f32 v165, v128, v129
	ds_read_b64_tr_b16 v[142:143], v243 offset:24576
	ds_read_b64_tr_b16 v[144:145], v243 offset:25088
	ds_read_b64_tr_b16 v[134:135], v243 offset:25600
	ds_read_b64_tr_b16 v[136:137], v243 offset:26112
	ds_read_b64_tr_b16 v[138:139], v243 offset:28672
	ds_read_b64_tr_b16 v[140:141], v243 offset:29184
	ds_read_b64_tr_b16 v[130:131], v243 offset:29696
	ds_read_b64_tr_b16 v[132:133], v243 offset:30208
	ds_read_b64_tr_b16 v[126:127], v243 offset:26624
	ds_read_b64_tr_b16 v[128:129], v243 offset:27136
	ds_read_b64_tr_b16 v[118:119], v243 offset:27648
	ds_read_b64_tr_b16 v[120:121], v243 offset:28160
	ds_read_b64_tr_b16 v[122:123], v243 offset:30720
	ds_read_b64_tr_b16 v[124:125], v243 offset:31232
	ds_read_b64_tr_b16 v[114:115], v243 offset:31744
	ds_read_b64_tr_b16 v[116:117], v243 offset:32256
	s_add_u32 s18, s100, s16
	s_addc_u32 s19, s101, s17
	s_add_u32 s18, s18, 0x168000
	s_addc_u32 s19, s19, 0
	s_add_i32 m0, s33, s22
	s_nop 0
	global_load_lds_dwordx4 v216, s[18:19]
	s_add_u32 s18, s27, s16
	s_addc_u32 s19, s35, s17
	s_add_u32 s18, s18, 0x62d8800
	s_addc_u32 s19, s19, 0
	s_lshl_b32 s43, s46, 1
	s_add_i32 s20, s43, s24
	s_mov_b32 m0, s20
	s_nop 0
	global_load_lds_dwordx4 v0, s[18:19]
	s_addk_i32 s20, 0x1f80
	s_mov_b32 m0, s20
	s_nop 0
	global_load_lds_dwordx4 v0, s[18:19] offset:128
	v_max3_f32 v146, v98, v99, v100
	v_max3_f32 v147, v101, v102, v103
	v_max3_f32 v146, v146, v104, v105
	v_max3_f32 v147, v147, v106, v107
	v_max3_f32 v146, v146, v108, v109
	v_max3_f32 v147, v147, v110, v111
	v_max3_f32 v146, v146, v112, v113
	v_max3_f32 v147, v147, v82, v83
	v_max3_f32 v146, v146, v84, v85
	v_max3_f32 v147, v147, v86, v87
	v_max3_f32 v146, v146, v88, v89
	v_max3_f32 v147, v147, v90, v91
	v_max3_f32 v146, v146, v92, v93
	v_max3_f32 v147, v147, v94, v95
	v_max3_f32 v146, v146, v96, v97
	v_max_f32_e32 v146, v146, v147
	v_mov_b32_e32 v147, v146
	s_nop 1
	v_permlane32_swap_b32_e32 v146, v147
	v_max_f32_e32 v146, v146, v147
	v_cmp_lt_f32_e32 vcc, s15, v146
	s_cmp_lg_u64 vcc, 0
	s_cselect_b64 s[18:19], -1, 0
	s_cbranch_vccnz .LBB0_552

; __device__ __forceinline__ int crow(int r,int hi){return (r&3)+8*(r>>2)+4*hi;}
; #define SBAR() __builtin_amdgcn_sched_barrier(0)
;   #define RESC() do{ if(resc){ asm volatile("s_waitcnt lgkmcnt(0)":::"memory"); \
;       _Pragma("unroll") for(int d_=0;d_<2;++d_) _Pragma("unroll") for(int r=0;r<16;++r)o[d_][r]*=wsf[crow(r,hi)]; } }while(0)
; __device__ __forceinline__ void pv(f32x16*o,int vb,bf16x8 pa0,bf16x8 pa1,bf16x8 pa2,bf16x8 pa3){
;   #pragma unroll
;   for(int d0=0;d0<2;++d0){s16x4 lo[4],hi[4];
;     #pragma unroll
;     for(int ks=0;ks<4;++ks){
;       asm volatile("ds_read_b64_tr_b16 %0,%1 offset:%c2":"=&v"(lo[ks]):"v"(vb),"i"(d0*4096+ks*1024):"memory");
;       asm volatile("ds_read_b64_tr_b16 %0,%1 offset:%c2":"=&v"(hi[ks]):"v"(vb),"i"(d0*4096+ks*1024+512):"memory");}
;     asm volatile("s_waitcnt lgkmcnt(0)":::"memory");SBAR();
;     ...
;     o[d0]=__builtin_amdgcn_mfma_f32_32x32x16_bf16(pa0,PK(0),o[d0],0,0,0);
;     o[d0]=__builtin_amdgcn_mfma_f32_32x32x16_bf16(pa1,PK(1),o[d0],0,0,0);
;     o[d0]=__builtin_amdgcn_mfma_f32_32x32x16_bf16(pa2,PK(2),o[d0],0,0,0);
;     o[d0]=__builtin_amdgcn_mfma_f32_32x32x16_bf16(pa3,PK(3),o[d0],0,0,0);
;     ...
;   }
; template<int THRL,int MODE> __device__ __forceinline__ void attn_unit128(const bf16*Qblk,const bf16*__restrict__ Kh,const bf16*__restrict__ Vh,bf16*Oblk,const int NT,char*shm,const bf16*O1blk,bf16*AOblk,const float lam,const float*sln,const float omli){
;     ...
;   STEP(pB0,pB1,pA0,pA1,NT-1,false,false,false); RESC();
;   { float sacc=pB0[0]+pB0[1]; _Pragma("unroll") for(int r=2;r<16;++r)sacc+=pB0[r]; _Pragma("unroll") for(int r=0;r<16;++r)sacc+=pB1[r]; l_reg+=sacc;
;     pw0=(u32x4){PKW(pB0,0),PKW(pB0,2),PKW(pB0,4),PKW(pB0,6)};pw1=(u32x4){PKW(pB0,8),PKW(pB0,10),PKW(pB0,12),PKW(pB0,14)};pw2=(u32x4){PKW(pB1,0),PKW(pB1,2),PKW(pB1,4),PKW(pB1,6)};pw3=(u32x4){PKW(pB1,8),PKW(pB1,10),PKW(pB1,12),PKW(pB1,14)};
;     SBAR(); { const int vb0=(int)(unsigned)(size_t)vp0; pv(o,vb0+2*sl_cur,PAF(0),PAF(1),PAF(2),PAF(3)); pv(o+2,vb0+2*sl_cur+8192,PAF(0),PAF(1),PAF(2),PAF(3)); } }
;     ...
;   {auto rr=__builtin_amdgcn_permlane32_swap(__float_as_uint(l_reg),__float_as_uint(l_reg),false,false);l_reg=__uint_as_float(rr[0])+__uint_as_float(rr[1]);}
;   if(hi==0)wsf[32+r32]=l_reg;asm volatile("s_waitcnt lgkmcnt(0)":::"memory");
;   float rli[16];
;   #pragma unroll
;   for(int r=0;r<16;++r)rli[r]=__builtin_amdgcn_rcpf(wsf[32+crow(r,hi)]);
.LBB0_570:
	v_add_f32_e32 v82, v98, v99
	v_add_f32_e32 v82, v100, v82
	v_add_f32_e32 v82, v101, v82
	v_add_f32_e32 v82, v102, v82
	v_add_f32_e32 v82, v103, v82
	v_add_f32_e32 v82, v104, v82
	v_add_f32_e32 v82, v105, v82
	v_add_f32_e32 v82, v106, v82
	v_add_f32_e32 v82, v107, v82
	v_add_f32_e32 v82, v108, v82
	v_add_f32_e32 v82, v109, v82
	v_add_f32_e32 v82, v110, v82
	v_add_f32_e32 v82, v111, v82
	v_add_f32_e32 v82, v112, v82
	v_add_f32_e32 v82, v113, v82
	v_add_f32_e32 v82, v82, v66
	v_add_f32_e32 v82, v67, v82
	v_add_f32_e32 v82, v68, v82
	v_add_f32_e32 v82, v69, v82
	v_add_f32_e32 v82, v70, v82
	v_add_f32_e32 v82, v71, v82
	v_add_f32_e32 v82, v72, v82
	v_add_f32_e32 v82, v73, v82
	v_add_f32_e32 v82, v74, v82
	v_add_f32_e32 v82, v75, v82
	v_add_f32_e32 v82, v76, v82
	v_add_f32_e32 v82, v77, v82
	v_add_f32_e32 v82, v78, v82
	v_add_f32_e32 v82, v79, v82
	v_add_f32_e32 v82, v80, v82
	v_add_f32_e32 v82, v81, v82
	v_add_f32_e32 v0, v0, v82
	v_cvt_pk_bf16_f32 v66, v66, v67
	v_add_u32_e32 v114, s43, v238
	v_cvt_pk_bf16_f32 v82, v98, v99
	v_cvt_pk_bf16_f32 v83, v100, v101
	v_cvt_pk_bf16_f32 v84, v102, v103
	v_cvt_pk_bf16_f32 v85, v104, v105
	v_cvt_pk_bf16_f32 v86, v106, v107
	v_cvt_pk_bf16_f32 v87, v108, v109
	v_cvt_pk_bf16_f32 v88, v110, v111
	v_cvt_pk_bf16_f32 v89, v112, v113
	v_cvt_pk_bf16_f32 v67, v68, v69
	v_cvt_pk_bf16_f32 v68, v70, v71
	v_cvt_pk_bf16_f32 v69, v72, v73
	v_cvt_pk_bf16_f32 v70, v74, v75
	v_cvt_pk_bf16_f32 v71, v76, v77
	v_cvt_pk_bf16_f32 v72, v78, v79
	v_cvt_pk_bf16_f32 v73, v80, v81
	v_add_u32_e32 v98, 0x6000, v114
	ds_read_b64_tr_b16 v[74:75],v98 offset:0
	ds_read_b64_tr_b16 v[76:77],v98 offset:512
	ds_read_b64_tr_b16 v[78:79],v98 offset:1024
	ds_read_b64_tr_b16 v[80:81],v98 offset:1536
	ds_read_b64_tr_b16 v[90:91],v98 offset:2048
	ds_read_b64_tr_b16 v[92:93],v98 offset:2560
	ds_read_b64_tr_b16 v[94:95],v98 offset:3072
	ds_read_b64_tr_b16 v[96:97],v98 offset:3584
	s_waitcnt lgkmcnt(0)
	s_nop 0
	v_mfma_f32_32x32x16_bf16 v[2:17], v[82:85], v[74:77], v[2:17]
	ds_read_b64_tr_b16 v[74:75],v98 offset:4096
	ds_read_b64_tr_b16 v[76:77],v98 offset:4608
	v_mfma_f32_32x32x16_bf16 v[2:17], v[86:89], v[78:81], v[2:17]
	ds_read_b64_tr_b16 v[78:79],v98 offset:5120
	ds_read_b64_tr_b16 v[80:81],v98 offset:5632
	v_mfma_f32_32x32x16_bf16 v[2:17], v[66:69], v[90:93], v[2:17]
	ds_read_b64_tr_b16 v[90:91],v98 offset:6144
	ds_read_b64_tr_b16 v[92:93],v98 offset:6656
	v_mfma_f32_32x32x16_bf16 v[2:17], v[70:73], v[94:97], v[2:17]
	ds_read_b64_tr_b16 v[94:95],v98 offset:7168
	ds_read_b64_tr_b16 v[96:97],v98 offset:7680
	s_waitcnt lgkmcnt(0)
	v_mfma_f32_32x32x16_bf16 v[50:65], v[82:85], v[74:77], v[50:65]
	v_add_u32_e32 v98, 0x8000, v114
	ds_read_b64_tr_b16 v[74:75],v98 offset:0
	ds_read_b64_tr_b16 v[76:77],v98 offset:512
	v_mfma_f32_32x32x16_bf16 v[50:65], v[86:89], v[78:81], v[50:65]
	ds_read_b64_tr_b16 v[78:79],v98 offset:1024
	ds_read_b64_tr_b16 v[80:81],v98 offset:1536
	v_mfma_f32_32x32x16_bf16 v[50:65], v[66:69], v[90:93], v[50:65]
	ds_read_b64_tr_b16 v[90:91],v98 offset:2048
	ds_read_b64_tr_b16 v[92:93],v98 offset:2560
	v_mfma_f32_32x32x16_bf16 v[50:65], v[70:73], v[94:97], v[50:65]
	ds_read_b64_tr_b16 v[94:95],v98 offset:3072
	ds_read_b64_tr_b16 v[96:97],v98 offset:3584
	s_waitcnt lgkmcnt(0)
	v_mfma_f32_32x32x16_bf16 v[34:49], v[82:85], v[74:77], v[34:49]
	ds_read_b64_tr_b16 v[74:75],v98 offset:4096
	ds_read_b64_tr_b16 v[76:77],v98 offset:4608
	v_mfma_f32_32x32x16_bf16 v[34:49], v[86:89], v[78:81], v[34:49]
	ds_read_b64_tr_b16 v[78:79],v98 offset:5120
	ds_read_b64_tr_b16 v[80:81],v98 offset:5632
	v_mfma_f32_32x32x16_bf16 v[34:49], v[66:69], v[90:93], v[34:49]
	ds_read_b64_tr_b16 v[90:91],v98 offset:6144
	ds_read_b64_tr_b16 v[92:93],v98 offset:6656
	v_mfma_f32_32x32x16_bf16 v[34:49], v[70:73], v[94:97], v[34:49]
	ds_read_b64_tr_b16 v[94:95],v98 offset:7168
	ds_read_b64_tr_b16 v[96:97],v98 offset:7680
	s_waitcnt lgkmcnt(0)
	v_mfma_f32_32x32x16_bf16 v[18:33], v[82:85], v[74:77], v[18:33]
	v_mfma_f32_32x32x16_bf16 v[18:33], v[86:89], v[78:81], v[18:33]
	v_mfma_f32_32x32x16_bf16 v[18:33], v[66:69], v[90:93], v[18:33]
	v_mov_b32_e32 v66, v0
	s_nop 1
	v_permlane32_swap_b32_e32 v0, v66
	v_mfma_f32_32x32x16_bf16 v[18:33], v[70:73], v[94:97], v[18:33]
	s_and_saveexec_b64 s[24:25], s[40:41]
	v_add_f32_e32 v0, v0, v66
	ds_write_b32 v237, v0 offset:128
	s_or_b64 exec, exec, s[24:25]
	s_waitcnt lgkmcnt(0)
	ds_read_b128 v[66:69], v214 offset:128
	ds_read_b128 v[70:73], v214 offset:160
	s_mul_i32 s24, s1, 0xc00
	s_mul_hi_u32 s25, s0, 0xc00
	s_add_i32 s25, s25, s24
	s_mul_i32 s24, s0, 0xc00
	v_readlane_b32 s30, v254, 63
	s_add_u32 s24, s30, s24
	v_readlane_b32 s30, v255, 0
	s_addc_u32 s25, s30, s25
	s_lshl_b32 s31, s42, 9
	s_add_u32 s42, s24, s31
	s_waitcnt lgkmcnt(1)
	v_rcp_f32_e32 v74, v66
	v_rcp_f32_e32 v75, v67
	v_rcp_f32_e32 v76, v68
	v_rcp_f32_e32 v77, v69
	ds_read_b128 v[66:69], v214 offset:192
	s_addc_u32 s43, s25, 0
	s_mul_i32 s24, s80, 0x18000
	s_mul_hi_i32 s25, s80, 0x18000
	s_add_u32 s24, s42, s24
	s_addc_u32 s25, s43, s25
	s_lshl_b32 s31, s80, 12
	s_add_i32 s31, s31, 0
	s_waitcnt lgkmcnt(1)
	v_rcp_f32_e32 v78, v70
	v_rcp_f32_e32 v79, v71
	v_rcp_f32_e32 v80, v72
	v_rcp_f32_e32 v81, v73
	ds_read_b128 v[70:73], v214 offset:224
	s_waitcnt lgkmcnt(1)
; __device__ __forceinline__ int crow(int r,int hi){return (r&3)+8*(r>>2)+4*hi;}
; template<int THRL,int MODE> __device__ __forceinline__ void attn_unit128(const bf16*Qblk,const bf16*__restrict__ Kh,const bf16*__restrict__ Vh,bf16*Oblk,const int NT,char*shm,const bf16*O1blk,bf16*AOblk,const float lam,const float*sln,const float omli){
;     ...
;   for(int r=0;r<16;++r)rli[r]=__builtin_amdgcn_rcpf(wsf[32+crow(r,hi)]);
;   bf16*Ow=Oblk+(long)wid*QBLK*PO;
;   if constexpr(MODE==0)
;   { bf16*stg=(bf16*)(shm+LDS_OST8)+wid*2048;
;     #pragma unroll
;     for(int h2=0;h2<2;++h2){
;       #pragma unroll
;       for(int r=0;r<16;++r){const int orow=crow(r,hi);
;         #pragma unroll
;         for(int d0=0;d0<2;++d0)stg[orow*64+d0*32+r32]=__float2bfloat16(o[2*h2+d0][r]*rli[r]);}
;       asm volatile("s_waitcnt lgkmcnt(0)":::"memory");
;       #pragma unroll
;       for(int i=0;i<4;++i){const int row=i*8+(lane>>3),ch=lane&7; const u32x4 v=*(const u32x4*)(stg+row*64+ch*8); ATTN_STORE16(Ow+(long)row*PO+h2*64+ch*8,v);}
;       asm volatile("s_waitcnt lgkmcnt(0)":::"memory");
	v_rcp_f32_e32 v82, v66
	s_add_i32 s31, s31, 0x12800
	v_lshlrev_b32_e32 v0, 9, v235
	v_lshlrev_b32_e32 v66, 1, v234
	v_add3_u32 v84, s31, v0, v66
	v_lshrrev_b32_e32 v85, 3, v233
	v_lshlrev_b32_e32 v0, 1, v236
	v_and_b32_e32 v0, 0x70, v0
	v_lshlrev_b32_e32 v86, 7, v85
	v_rcp_f32_e32 v83, v67
	v_lshl_add_u64 v[66:67], s[24:25], 0, v[0:1]
	v_add3_u32 v86, s31, v0, v86
	v_mul_f32_e32 v0, v2, v74
	v_cvt_pk_bf16_f32 v0, v0, s0
	ds_write_b16 v84, v0
	v_mul_f32_e32 v0, v50, v74
	v_cvt_pk_bf16_f32 v0, v0, s0
	ds_write_b16 v84, v0 offset:64
	v_mul_f32_e32 v0, v3, v75
	v_cvt_pk_bf16_f32 v0, v0, s0
	ds_write_b16 v84, v0 offset:128
	v_mul_f32_e32 v0, v51, v75
	v_cvt_pk_bf16_f32 v0, v0, s0
	ds_write_b16 v84, v0 offset:192
	v_mul_f32_e32 v0, v4, v76
	v_cvt_pk_bf16_f32 v0, v0, s0
	ds_write_b16 v84, v0 offset:256
	v_mul_f32_e32 v0, v52, v76
	v_cvt_pk_bf16_f32 v0, v0, s0
	ds_write_b16 v84, v0 offset:320
	v_mul_f32_e32 v0, v5, v77
	v_cvt_pk_bf16_f32 v0, v0, s0
	ds_write_b16 v84, v0 offset:384
	v_mul_f32_e32 v0, v53, v77
	v_cvt_pk_bf16_f32 v0, v0, s0
	ds_write_b16 v84, v0 offset:448
	v_mul_f32_e32 v0, v6, v78
	v_cvt_pk_bf16_f32 v0, v0, s0
	ds_write_b16 v84, v0 offset:1024
	v_mul_f32_e32 v0, v54, v78
	v_cvt_pk_bf16_f32 v0, v0, s0
	ds_write_b16 v84, v0 offset:1088
	v_mul_f32_e32 v0, v7, v79
	v_cvt_pk_bf16_f32 v0, v0, s0
	ds_write_b16 v84, v0 offset:1152
	v_mul_f32_e32 v0, v55, v79
	v_cvt_pk_bf16_f32 v0, v0, s0
	ds_write_b16 v84, v0 offset:1216
	v_mul_f32_e32 v0, v8, v80
	v_cvt_pk_bf16_f32 v0, v0, s0
	ds_write_b16 v84, v0 offset:1280
	v_mul_f32_e32 v0, v56, v80
	v_cvt_pk_bf16_f32 v0, v0, s0
	ds_write_b16 v84, v0 offset:1344
	v_mul_f32_e32 v0, v9, v81
	v_cvt_pk_bf16_f32 v0, v0, s0
	ds_write_b16 v84, v0 offset:1408
	v_mul_f32_e32 v0, v57, v81
	v_cvt_pk_bf16_f32 v0, v0, s0
	ds_write_b16 v84, v0 offset:1472
	v_mul_f32_e32 v0, v10, v82
	v_cvt_pk_bf16_f32 v0, v0, s0
	ds_write_b16 v84, v0 offset:2048
	v_mul_f32_e32 v0, v58, v82
	v_cvt_pk_bf16_f32 v0, v0, s0
	v_rcp_f32_e32 v68, v68
	ds_write_b16 v84, v0 offset:2112
	v_mul_f32_e32 v0, v11, v83
	v_cvt_pk_bf16_f32 v0, v0, s0
	ds_write_b16 v84, v0 offset:2176
	v_mul_f32_e32 v0, v59, v83
	v_cvt_pk_bf16_f32 v0, v0, s0
	v_rcp_f32_e32 v69, v69
	ds_write_b16 v84, v0 offset:2240
	v_mul_f32_e32 v0, v12, v68
	v_cvt_pk_bf16_f32 v0, v0, s0
	ds_write_b16 v84, v0 offset:2304
	v_mul_f32_e32 v0, v60, v68
	v_cvt_pk_bf16_f32 v0, v0, s0
	s_waitcnt lgkmcnt(14)
	v_rcp_f32_e32 v70, v70
	ds_write_b16 v84, v0 offset:2368
	v_mul_f32_e32 v0, v13, v69
	v_cvt_pk_bf16_f32 v0, v0, s0
	ds_write_b16 v84, v0 offset:2432
	v_mul_f32_e32 v0, v61, v69
	v_cvt_pk_bf16_f32 v0, v0, s0
	v_rcp_f32_e32 v71, v71
	ds_write_b16 v84, v0 offset:2496
	v_mul_f32_e32 v0, v14, v70
	v_cvt_pk_bf16_f32 v0, v0, s0
	ds_write_b16 v84, v0 offset:3072
	v_mul_f32_e32 v0, v62, v70
	v_cvt_pk_bf16_f32 v0, v0, s0
	v_rcp_f32_e32 v72, v72
	ds_write_b16 v84, v0 offset:3136
	v_mul_f32_e32 v0, v15, v71
	v_cvt_pk_bf16_f32 v0, v0, s0
	ds_write_b16 v84, v0 offset:3200
	v_mul_f32_e32 v0, v63, v71
	v_cvt_pk_bf16_f32 v0, v0, s0
	v_rcp_f32_e32 v73, v73
	ds_write_b16 v84, v0 offset:3264
	v_mul_f32_e32 v0, v16, v72
	v_cvt_pk_bf16_f32 v0, v0, s0
	ds_write_b16 v84, v0 offset:3328
	v_mul_f32_e32 v0, v64, v72
	v_cvt_pk_bf16_f32 v0, v0, s0
	ds_write_b16 v84, v0 offset:3392
	v_mul_f32_e32 v0, v17, v73
	v_cvt_pk_bf16_f32 v0, v0, s0
	ds_write_b16 v84, v0 offset:3456
	v_mul_f32_e32 v0, v65, v73
	v_cvt_pk_bf16_f32 v0, v0, s0
	ds_write_b16 v84, v0 offset:3520
	s_waitcnt lgkmcnt(0)
	ds_read_b128 v[2:5], v86
	ds_read_b128 v[6:9], v86 offset:1024
	v_mul_u32_u24_e32 v0, 0x600, v85
	v_lshlrev_b32_e32 v0, 1, v0
	v_lshl_add_u64 v[50:51], v[66:67], 0, v[0:1]
	s_mov_b64 s[24:25], 0x6000
	v_lshl_add_u64 v[52:53], v[50:51], 0, s[24:25]
	s_movk_i32 s24, 0x6000
	s_waitcnt lgkmcnt(1)
	global_store_dwordx4 v[50:51], v[2:5], off
	v_mul_f32_e32 v0, v34, v74
	v_cvt_pk_bf16_f32 v0, v0, s0
	v_add_co_u32_e32 v2, vcc, s24, v50
	s_mov_b64 s[24:25], 0xc000
	s_nop 0
	v_addc_co_u32_e32 v3, vcc, 0, v51, vcc
	s_waitcnt lgkmcnt(0)
	global_store_dwordx4 v[2:3], v[6:9], off
	ds_read_b128 v[2:5], v86 offset:2048
	ds_read_b128 v[6:9], v86 offset:3072
	v_lshl_add_u64 v[54:55], v[50:51], 0, s[24:25]
	s_mov_b32 s24, 0xc000
	v_add_co_u32_e32 v10, vcc, s24, v50
	s_mov_b32 s24, 0x12000
	s_nop 0
	v_addc_co_u32_e32 v11, vcc, 0, v51, vcc
	s_waitcnt lgkmcnt(1)
	global_store_dwordx4 v[10:11], v[2:5], off
	s_movk_i32 s56, 0x2000
	s_movk_i32 s45, 0x4000
	v_add_co_u32_e32 v2, vcc, s24, v50
	s_mov_b64 s[24:25], 0x12000
	s_nop 0
	v_addc_co_u32_e32 v3, vcc, 0, v51, vcc
	s_waitcnt lgkmcnt(0)
	global_store_dwordx4 v[2:3], v[6:9], off
	s_waitcnt lgkmcnt(0)
; __device__ __forceinline__ int crow(int r,int hi){return (r&3)+8*(r>>2)+4*hi;}
;   #define DMA_K(t,slot) glds16(ksrc+(long)(t)*KVBLK*PQ,(unsigned)__builtin_amdgcn_readfirstlane(kdst+(slot)))
;   #define DMA_V(t,slot) glds16(vsrc+(long)(t)*KVBLK*PQ,(unsigned)__builtin_amdgcn_readfirstlane(vdst+(slot)))
;   #define DMA_K(t,slot) glds16((const char*)Kh+(size_t)(t)*(KVBLK*PQ*2)+koff,(unsigned)__builtin_amdgcn_readfirstlane(kdst+(slot)))
; template<int THRL,int MODE> __device__ __forceinline__ void attn_unit128(const bf16*Qblk,const bf16*__restrict__ Kh,const bf16*__restrict__ Vh,bf16*Oblk,const int NT,char*shm,const bf16*O1blk,bf16*AOblk,const float lam,const float*sln,const float omli){
;   int tid_=threadIdx.x; asm volatile("":"+v"(tid_));
;   const int tid=tid_,lane=tid&63,r32=lane&31,hi=lane>>5; const int wid=__builtin_amdgcn_readfirstlane(tid>>6);
;   const bf16*Qw=Qblk+(long)wid*QBLK*PQ;
;   const unsigned lds0=(unsigned)(uintptr_t)shm;
;   float*wsf=(float*)(shm+LDS_WS8)+wid*64;
;   const unsigned koff=(unsigned)(lane*PQ+wid*8)*2u;
;   const unsigned voff=(unsigned)((16*(wid&3)+(lane>>2))*PQ+(wid>>2)*32+(lane&3)*8)*2u;
;   const unsigned kdst=lds0+LDS_K+wid*1024, vdst=lds0+LDS_V+wid*1024;
;     ...
;   const char*Kbase=shm+LDS_K; bf16x8 kf[8];
;   const lds_cptr shm3=(lds_cptr)shm; const lds_cptr kp0=shm3+LDS_K+hi*1024+r32*16; const lds_cptr vp0=shm3+LDS_V+((lane>>4)&1)*32+(lane&3)*8+(4*hi+((lane&15)>>2))*64;
;   DMA_K(0,0);DMA_V(0,0);DMA_K(1,SLOTB);
;   bf16x8 qr[4];
;   #pragma unroll
;   for(int d0=0;d0<4;++d0)qr[d0]=*reinterpret_cast<const bf16x8*>(&Qw[(long)r32*PQ+d0*16+hi*8]);
;     ...
;     for(int h2=0;h2<2;++h2){
;       #pragma unroll
;       for(int r=0;r<16;++r){const int orow=crow(r,hi);
;         #pragma unroll
;         for(int d0=0;d0<2;++d0)stg[orow*64+d0*32+r32]=__float2bfloat16(o[2*h2+d0][r]*rli[r]);}
;       asm volatile("s_waitcnt lgkmcnt(0)":::"memory");
;       #pragma unroll
;       for(int i=0;i<4;++i){const int row=i*8+(lane>>3),ch=lane&7; const u32x4 v=*(const u32x4*)(stg+row*64+ch*8); ATTN_STORE16(Ow+(long)row*PO+h2*64+ch*8,v);}
;       asm volatile("s_waitcnt lgkmcnt(0)":::"memory");
	ds_write_b16 v84, v0
	v_mul_f32_e32 v0, v18, v74
	v_cvt_pk_bf16_f32 v0, v0, s0
	ds_write_b16 v84, v0 offset:64
	v_mul_f32_e32 v0, v35, v75
	v_cvt_pk_bf16_f32 v0, v0, s0
	ds_write_b16 v84, v0 offset:128
	v_mul_f32_e32 v0, v19, v75
	v_cvt_pk_bf16_f32 v0, v0, s0
	ds_write_b16 v84, v0 offset:192
	v_mul_f32_e32 v0, v36, v76
	v_cvt_pk_bf16_f32 v0, v0, s0
	ds_write_b16 v84, v0 offset:256
	v_mul_f32_e32 v0, v20, v76
	v_cvt_pk_bf16_f32 v0, v0, s0
	ds_write_b16 v84, v0 offset:320
	v_mul_f32_e32 v0, v37, v77
	v_cvt_pk_bf16_f32 v0, v0, s0
	ds_write_b16 v84, v0 offset:384
	v_mul_f32_e32 v0, v21, v77
	v_cvt_pk_bf16_f32 v0, v0, s0
	ds_write_b16 v84, v0 offset:448
	v_mul_f32_e32 v0, v38, v78
	v_cvt_pk_bf16_f32 v0, v0, s0
	ds_write_b16 v84, v0 offset:1024
	v_mul_f32_e32 v0, v22, v78
	v_cvt_pk_bf16_f32 v0, v0, s0
	ds_write_b16 v84, v0 offset:1088
	v_mul_f32_e32 v0, v39, v79
	v_cvt_pk_bf16_f32 v0, v0, s0
	ds_write_b16 v84, v0 offset:1152
	v_mul_f32_e32 v0, v23, v79
	v_cvt_pk_bf16_f32 v0, v0, s0
	ds_write_b16 v84, v0 offset:1216
	v_mul_f32_e32 v0, v40, v80
	v_cvt_pk_bf16_f32 v0, v0, s0
	ds_write_b16 v84, v0 offset:1280
	v_mul_f32_e32 v0, v24, v80
	v_cvt_pk_bf16_f32 v0, v0, s0
	ds_write_b16 v84, v0 offset:1344
	v_mul_f32_e32 v0, v41, v81
	v_cvt_pk_bf16_f32 v0, v0, s0
	ds_write_b16 v84, v0 offset:1408
	v_mul_f32_e32 v0, v25, v81
	v_cvt_pk_bf16_f32 v0, v0, s0
	ds_write_b16 v84, v0 offset:1472
	v_mul_f32_e32 v0, v42, v82
	v_cvt_pk_bf16_f32 v0, v0, s0
	ds_write_b16 v84, v0 offset:2048
	v_mul_f32_e32 v0, v26, v82
	v_cvt_pk_bf16_f32 v0, v0, s0
	ds_write_b16 v84, v0 offset:2112
	v_mul_f32_e32 v0, v43, v83
	v_cvt_pk_bf16_f32 v0, v0, s0
	ds_write_b16 v84, v0 offset:2176
	v_mul_f32_e32 v0, v27, v83
	v_cvt_pk_bf16_f32 v0, v0, s0
	ds_write_b16 v84, v0 offset:2240
	v_mul_f32_e32 v0, v44, v68
	v_cvt_pk_bf16_f32 v0, v0, s0
	ds_write_b16 v84, v0 offset:2304
	v_mul_f32_e32 v0, v28, v68
	v_cvt_pk_bf16_f32 v0, v0, s0
	ds_write_b16 v84, v0 offset:2368
	v_mul_f32_e32 v0, v45, v69
	v_cvt_pk_bf16_f32 v0, v0, s0
	ds_write_b16 v84, v0 offset:2432
	v_mul_f32_e32 v0, v29, v69
	v_cvt_pk_bf16_f32 v0, v0, s0
	ds_write_b16 v84, v0 offset:2496
	v_mul_f32_e32 v0, v46, v70
	v_cvt_pk_bf16_f32 v0, v0, s0
	ds_write_b16 v84, v0 offset:3072
	v_mul_f32_e32 v0, v30, v70
	v_cvt_pk_bf16_f32 v0, v0, s0
	ds_write_b16 v84, v0 offset:3136
	v_mul_f32_e32 v0, v47, v71
	v_cvt_pk_bf16_f32 v0, v0, s0
	ds_write_b16 v84, v0 offset:3200
	v_mul_f32_e32 v0, v31, v71
	v_cvt_pk_bf16_f32 v0, v0, s0
	ds_write_b16 v84, v0 offset:3264
	v_mul_f32_e32 v0, v48, v72
	v_cvt_pk_bf16_f32 v0, v0, s0
	ds_write_b16 v84, v0 offset:3328
	v_mul_f32_e32 v0, v32, v72
	v_cvt_pk_bf16_f32 v0, v0, s0
	ds_write_b16 v84, v0 offset:3392
	v_mul_f32_e32 v0, v49, v73
	v_cvt_pk_bf16_f32 v0, v0, s0
	ds_write_b16 v84, v0 offset:3456
	v_mul_f32_e32 v0, v33, v73
	v_cvt_pk_bf16_f32 v0, v0, s0
	ds_write_b16 v84, v0 offset:3520
	s_waitcnt lgkmcnt(0)
	ds_read_b128 v[2:5], v86
	ds_read_b128 v[6:9], v86 offset:1024
	ds_read_b128 v[10:13], v86 offset:2048
	ds_read_b128 v[14:17], v86 offset:3072
	v_lshl_add_u64 v[18:19], v[50:51], 0, s[24:25]
	s_waitcnt lgkmcnt(3)
	global_store_dwordx4 v[50:51], v[2:5], off offset:128
	s_waitcnt lgkmcnt(2)
	global_store_dwordx4 v[52:53], v[6:9], off offset:128
	s_waitcnt lgkmcnt(1)
	global_store_dwordx4 v[54:55], v[10:13], off offset:128
	s_waitcnt lgkmcnt(0)
	global_store_dwordx4 v[18:19], v[14:17], off offset:128
	s_waitcnt lgkmcnt(0)
	s_nop 1
	v_mov_b32_e32 v14, v220
	s_waitcnt lgkmcnt(0)
	s_barrier
	v_mov_b32_e32 v18, v1
	v_readfirstlane_b32 s33, v14
	s_ashr_i32 s24, s33, 6
	s_ashr_i32 s25, s24, 31
	s_mul_i32 s40, s24, 0x24000
	s_mul_hi_i32 s31, s24, 0x24000
	s_add_u32 s40, s28, s40
	s_addc_u32 s41, s92, s31
	s_lshl_b32 s28, s24, 4
	v_bfe_u32 v2, v14, 2, 4
	v_mov_b32_e32 v0, s28
	v_and_or_b32 v2, s28, 48, v2
	s_ashr_i32 s28, s33, 3
	s_and_b32 s28, s28, 0x7fffffe0
	v_mov_b32_e32 v3, s28
	s_movk_i32 s28, 0x900
	v_mad_u32_u24 v2, v2, s28, v3
	v_lshlrev_b32_e32 v3, 3, v14
	v_and_b32_e32 v56, 63, v14
	s_and_b32 s31, s33, 0x3fffffc0
	v_and_b32_e32 v16, 24, v3
	s_lshl_b32 s28, s24, 10
	v_mad_u32_u24 v0, v56, s81, v0
	v_or_b32_e32 v2, v2, v16
	s_cmp_lg_u32 0, -1
	v_lshlrev_b32_e32 v2, 1, v2
	s_cselect_b32 s33, 0, 0
	v_lshl_add_u64 v[50:51], s[4:5], 0, v[0:1]
	s_mov_b64 s[4:5], 0x600
	s_add_i32 s33, s28, s33
	v_lshl_add_u64 v[212:213], v[50:51], 0, s[4:5]
	s_mov_b32 s4, m0
	s_mov_b32 m0, s33
	s_nop 0
	global_load_lds_dwordx4 v[212:213], off
	s_mov_b32 m0, s4
	v_mov_b32_e32 v0, v2
	s_add_i32 s28, s33, 0x6000
	v_lshl_add_u64 v[2:3], s[36:37], 0, v[0:1]
	s_mov_b32 s4, m0
	s_mov_b32 m0, s28
	s_nop 0
	global_load_lds_dwordx4 v[2:3], off
	s_mov_b32 m0, s4
	v_lshl_add_u64 v[2:3], s[6:7], 0, v[0:1]
	s_add_i32 s4, s33, 0x8000
	s_mov_b32 s5, m0
	s_mov_b32 m0, s4
	s_nop 0
	global_load_lds_dwordx4 v[2:3], off
	s_mov_b32 m0, s5
	s_mov_b64 s[4:5], 0x48600
	v_and_b32_e32 v235, 31, v14
	v_bfe_u32 v15, v14, 5, 1
	v_lshl_add_u64 v[2:3], v[50:51], 0, s[4:5]
	s_add_i32 s4, s33, 0x2000
	s_mov_b32 s5, m0
	s_mov_b32 m0, s4
	s_nop 0
	global_load_lds_dwordx4 v[2:3], off
	s_mov_b32 m0, s5
	v_mul_u32_u24_e32 v2, 0x900, v235
	v_lshlrev_b32_e32 v241, 4, v15
	v_lshl_or_b32 v2, v2, 1, v241
	global_load_dwordx4 v[190:193], v2, s[40:41] offset:512
	global_load_dwordx4 v[186:189], v2, s[40:41] offset:544
	global_load_dwordx4 v[182:185], v2, s[40:41] offset:576
	global_load_dwordx4 v[178:181], v2, s[40:41] offset:608
	v_lshlrev_b32_e32 v236, 10, v15
	v_lshlrev_b32_e32 v3, 4, v235
	v_mov_b32_e32 v19, v1
	v_mov_b32_e32 v20, v1
	v_mov_b32_e32 v21, v1
	v_mov_b32_e32 v22, v1
	v_mov_b32_e32 v23, v1
	v_mov_b32_e32 v24, v1
	v_mov_b32_e32 v25, v1
	v_mov_b32_e32 v26, v1
	v_mov_b32_e32 v27, v1
	v_mov_b32_e32 v28, v1
	v_mov_b32_e32 v29, v1
	v_mov_b32_e32 v30, v1
	v_mov_b32_e32 v31, v1
	v_mov_b32_e32 v32, v1
	v_mov_b32_e32 v33, v1
	s_mov_b64 s[4:5], 0x90600
	v_add3_u32 v240, 0, v236, v3
	v_lshl_add_u64 v[2:3], v[50:51], 0, s[4:5]
	s_add_i32 s4, s33, 0x4000
	s_mov_b32 s5, m0
	s_mov_b32 m0, s4
	s_nop 0
	global_load_lds_dwordx4 v[2:3], off
	s_mov_b32 m0, s5
	s_waitcnt vmcnt(4) lgkmcnt(0)
	s_barrier
; #define WAIT_BAR(N) asm volatile("s_waitcnt vmcnt(" #N ") lgkmcnt(0)\n\ts_barrier":::"memory")
;   #define DMA_K(t,slot) glds16(ksrc+(long)(t)*KVBLK*PQ,(unsigned)__builtin_amdgcn_readfirstlane(kdst+(slot)))
;   #define DMA_V(t,slot) glds16(vsrc+(long)(t)*KVBLK*PQ,(unsigned)__builtin_amdgcn_readfirstlane(vdst+(slot)))
;   #define CMASK(P0,P1,t) do{}while(0)
;   #define START(P0,P1) do{ const float rm=rowmax(P0,P1); resc=false; \
;     { const float dl=rm; mhat=fadd_s(mhat,dl); \
;       _Pragma("unroll") for(int r=0;r<16;++r){P0[r]=fsub_s(P0[r],dl);P1[r]=fsub_s(P1[r],dl);} \
;       _Pragma("unroll") for(int r=0;r<16;++r)negm[r]=-mhat; asm volatile("":"+v"(negm)); } \
;     _Pragma("unroll") for(int r=0;r<16;++r)P0[r]=__builtin_amdgcn_exp2f(P0[r]); }while(0)
;   #define ROT() do{sl_prev=sl_cur;sl_cur=sl_next;sl_next=(sl_next==(NSLOT-1)*SLOTB)?0:sl_next+SLOTB;}while(0)
;   #define CMASK(P0,P1,t) do{}while(0)
;   #define CMASK(P0,P1,t) do{}while(0)
;   #define DMA_K(t,slot) glds16((const char*)Kh+(size_t)(t)*(KVBLK*PQ*2)+koff,(unsigned)__builtin_amdgcn_readfirstlane(kdst+(slot)))
;   #define DMA_V(t,slot) do{ glds16((const char*)Vh+(size_t)(t)*(KVBLK*PQ*2)+voff,(unsigned)__builtin_amdgcn_readfirstlane(vdst+2*(slot))); glds16((const char*)Vh+(size_t)(t)*(KVBLK*PQ*2)+128+voff,(unsigned)__builtin_amdgcn_readfirstlane(vdst+2*(slot)+8192)); }while(0)
;   #define CMASK(P0,P1,t) do{}while(0)
;   #define ROT() do{sl_prev=sl_cur;sl_cur=sl_next;sl_next=(sl_next==(NSLOT-1)*SLOTB)?0:sl_next+SLOTB;}while(0)
;   #define CMASK(P0,P1,t) do{}while(0)
;   #define CMASK(P0,P1,t) do{}while(0)
; template<int THRL,int MODE> __device__ __forceinline__ void attn_unit128(const bf16*Qblk,const bf16*__restrict__ Kh,const bf16*__restrict__ Vh,bf16*Oblk,const int NT,char*shm,const bf16*O1blk,bf16*AOblk,const float lam,const float*sln,const float omli){
;     ...
;   DMA_K(2,2*SLOTB);
;   WAIT_BAR(4);
;   qkt(pA0,pA1,Kbase,qr,negm,r32,hi);asm volatile("s_nop 15\n\ts_nop 7":"+v"(pA0),"+v"(pA1));CMASK(pA0,pA1,0);
;   START(pA0,pA1);
;   _Pragma("unroll") for(int r=0;r<16;++r)pA1[r]=__builtin_amdgcn_exp2f(pA1[r]);
;   WAIT_BAR(0);
;   DMA_K(3,0);DMA_V(1,SLOTB);
;   ROT();
;   kload8(kf,kp0+sl_cur);
;   WAIT_BAR(3);
;   s16x4 vlo[8],vhi[8]; u32x4 pw0,pw1,pw2,pw3;
	ds_read_b128 v[2:5], v240
	ds_read_b128 v[6:9], v240 offset:512
	s_waitcnt vmcnt(3) lgkmcnt(1)
	v_mfma_f32_32x32x16_bf16 v[34:49], v[2:5], v[190:193], v[18:33]
	v_bfe_u32 v233, v14, 4, 2
	v_and_b32_e32 v234, 15, v14
	v_lshlrev_b32_e32 v58, 8, v15
	s_lshl_b32 s4, s31, 2
	s_add_i32 s36, s4, 0
	s_mov_b64 s[4:5], 0xd8600
	s_add_i32 s36, s36, 0x12000
	s_waitcnt lgkmcnt(0)
	v_mfma_f32_32x32x16_bf16 v[18:33], v[6:9], v[190:193], v[18:33]
	ds_read_b128 v[2:5], v240 offset:2048
	ds_read_b128 v[6:9], v240 offset:2560
	v_cmp_gt_u32_e64 s[40:41], 32, v56
	s_mov_b32 s6, 0
	s_mov_b32 s37, -1
	v_lshl_add_u32 v237, v235, 2, s36
	v_mov_b32_e32 v242, 0
	s_waitcnt vmcnt(2) lgkmcnt(1)
	v_mfma_f32_32x32x16_bf16 v[34:49], v[2:5], v[186:189], v[34:49]
	ds_read_b128 v[10:13], v240 offset:4608
	ds_read_b128 v[2:5], v240 offset:4096
	s_waitcnt lgkmcnt(2)
	v_mfma_f32_32x32x16_bf16 v[18:33], v[6:9], v[186:189], v[18:33]
	v_lshlrev_b32_e32 v6, 1, v14
	v_and_b32_e32 v6, 32, v6
	v_add3_u32 v57, 0, v6, v16
	v_lshlrev_b32_e32 v6, 4, v14
	ds_read_b128 v[52:55], v240 offset:6656
	ds_read_b128 v[14:17], v240 offset:6144
	v_and_b32_e32 v59, 0xc0, v6
	v_mov_b32_e32 v6, v1
	s_waitcnt vmcnt(1) lgkmcnt(2)
	v_mfma_f32_32x32x16_bf16 v[34:49], v[2:5], v[182:185], v[34:49]
	v_mov_b32_e32 v2, v1
	v_mov_b32_e32 v3, v1
	v_mov_b32_e32 v4, v1
	v_mov_b32_e32 v5, v1
	v_mov_b32_e32 v7, v1
	v_mov_b32_e32 v8, v1
	v_mov_b32_e32 v9, v1
	v_mfma_f32_32x32x16_bf16 v[18:33], v[10:13], v[182:185], v[18:33]
	v_mov_b32_e32 v10, v1
	v_mov_b32_e32 v11, v1
	v_mov_b32_e32 v12, v1
	v_mov_b32_e32 v13, v1
	v_add3_u32 v238, v57, v58, v59
	s_waitcnt vmcnt(0) lgkmcnt(0)
	v_mfma_f32_32x32x16_bf16 v[34:49], v[14:17], v[178:181], v[34:49]
	v_mov_b32_e32 v16, v1
	v_mov_b32_e32 v17, v1
	v_mov_b32_e32 v14, v1
	v_mov_b32_e32 v15, v1
	v_mfma_f32_32x32x16_bf16 v[18:33], v[52:55], v[178:181], v[18:33]
	s_nop 15
	s_nop 7
	s_nop 0
	v_max3_f32 v52, v34, v35, v18
	v_max3_f32 v53, v36, v37, v19
	s_nop 0
	v_max3_f32 v52, v52, v20, v21
	v_max3_f32 v53, v53, v40, v41
	s_nop 0
	v_max3_f32 v52, v52, v38, v39
	v_max3_f32 v53, v53, v24, v25
	s_nop 0
	v_max3_f32 v52, v52, v22, v23
	v_max3_f32 v53, v53, v44, v45
	s_nop 0
	v_max3_f32 v52, v52, v42, v43
	v_max3_f32 v53, v53, v28, v29
	s_nop 0
	v_max3_f32 v52, v52, v26, v27
	v_max3_f32 v53, v53, v48, v49
	s_nop 0
	v_max3_f32 v52, v52, v46, v47
	v_max3_f32 v53, v53, v32, v33
	s_nop 0
	v_max3_f32 v52, v52, v30, v31
	s_nop 0
	v_max_f32_e32 v52, v52, v53
	s_nop 0
	v_mov_b32_e32 v53, v52
	s_nop 1
	v_permlane32_swap_b32_e32 v52, v53
	v_max_f32_e32 v52, v52, v53
	s_nop 0
	v_add_f32_e32 v239, v1, v52
	v_sub_f32_e32 v18, v18, v52
	v_sub_f32_e32 v19, v19, v52
	v_sub_f32_e32 v34, v34, v52
	v_sub_f32_e32 v35, v35, v52
	v_sub_f32_e32 v36, v36, v52
	s_nop 0
	v_xor_b32_e32 v66, 0x80000000, v239
	v_mov_b32_e32 v67, v66
	v_mov_b32_e32 v68, v66
	v_mov_b32_e32 v69, v66
	v_mov_b32_e32 v70, v66
	v_mov_b32_e32 v71, v66
	v_mov_b32_e32 v72, v66
	v_mov_b32_e32 v73, v66
	v_mov_b32_e32 v74, v66
	v_mov_b32_e32 v75, v66
	v_mov_b32_e32 v76, v66
	v_mov_b32_e32 v77, v66
	v_mov_b32_e32 v78, v66
	v_mov_b32_e32 v79, v66
	v_mov_b32_e32 v80, v66
	v_mov_b32_e32 v81, v66
	s_waitcnt vmcnt(0) lgkmcnt(0)
	s_barrier
	v_exp_f32_e32 v82, v18
	v_exp_f32_e32 v83, v19
	v_lshl_add_u64 v[18:19], v[50:51], 0, s[4:5]
	s_mov_b32 s4, m0
	s_mov_b32 m0, s33
	s_nop 0
	global_load_lds_dwordx4 v[18:19], off
	s_mov_b32 m0, s4
	v_lshl_add_u64 v[18:19], s[8:9], 0, v[0:1]
	s_add_i32 s4, s33, 0xa000
	s_mov_b32 s5, m0
	s_mov_b32 m0, s4
	s_nop 0
	global_load_lds_dwordx4 v[18:19], off
	s_mov_b32 m0, s5
	v_lshl_add_u64 v[18:19], s[10:11], 0, v[0:1]
	s_add_i32 s4, s33, 0xc000
	s_mov_b32 s5, m0
	s_mov_b32 m0, s4
	s_nop 0
	global_load_lds_dwordx4 v[18:19], off
	s_mov_b32 m0, s5
	ds_read_b128 v[114:117], v240 offset:8192
	ds_read_b128 v[198:201], v240 offset:8704
	ds_read_b128 v[202:205], v240 offset:10240
	ds_read_b128 v[194:197], v240 offset:10752
	ds_read_b128 v[158:161], v240 offset:12288
	ds_read_b128 v[154:157], v240 offset:12800
	ds_read_b128 v[150:153], v240 offset:14336
	ds_read_b128 v[146:149], v240 offset:14848
	v_sub_f32_e32 v20, v20, v52
	v_sub_f32_e32 v37, v37, v52
	v_sub_f32_e32 v21, v21, v52
	v_sub_f32_e32 v38, v38, v52
	v_sub_f32_e32 v22, v22, v52
	v_sub_f32_e32 v39, v39, v52
	v_sub_f32_e32 v23, v23, v52
	v_sub_f32_e32 v40, v40, v52
	v_sub_f32_e32 v24, v24, v52
	v_sub_f32_e32 v41, v41, v52
	v_sub_f32_e32 v25, v25, v52
	v_sub_f32_e32 v42, v42, v52
	v_sub_f32_e32 v26, v26, v52
	v_sub_f32_e32 v43, v43, v52
	v_sub_f32_e32 v27, v27, v52
	v_sub_f32_e32 v44, v44, v52
	v_sub_f32_e32 v28, v28, v52
	v_sub_f32_e32 v45, v45, v52
	v_sub_f32_e32 v29, v29, v52
	v_sub_f32_e32 v46, v46, v52
	v_sub_f32_e32 v30, v30, v52
	v_sub_f32_e32 v47, v47, v52
	v_sub_f32_e32 v31, v31, v52
	v_sub_f32_e32 v48, v48, v52
	v_sub_f32_e32 v32, v32, v52
	v_sub_f32_e32 v49, v49, v52
	v_sub_f32_e32 v33, v33, v52
	v_exp_f32_e32 v98, v34
	v_exp_f32_e32 v99, v35
	v_exp_f32_e32 v100, v36
	v_exp_f32_e32 v101, v37
	v_exp_f32_e32 v102, v38
	v_exp_f32_e32 v103, v39
	v_exp_f32_e32 v104, v40
	v_exp_f32_e32 v105, v41
	v_exp_f32_e32 v106, v42
	v_exp_f32_e32 v107, v43
	v_exp_f32_e32 v108, v44
	v_exp_f32_e32 v109, v45
	v_exp_f32_e32 v110, v46
	v_exp_f32_e32 v111, v47
	v_exp_f32_e32 v112, v48
	v_exp_f32_e32 v113, v49
	v_exp_f32_e32 v84, v20
	v_exp_f32_e32 v85, v21
	v_exp_f32_e32 v86, v22
	v_exp_f32_e32 v87, v23
	v_exp_f32_e32 v88, v24
	v_exp_f32_e32 v89, v25
	v_exp_f32_e32 v90, v26
	v_exp_f32_e32 v91, v27
	v_exp_f32_e32 v92, v28
	v_exp_f32_e32 v93, v29
	v_exp_f32_e32 v94, v30
	v_exp_f32_e32 v95, v31
	v_exp_f32_e32 v96, v32
	v_exp_f32_e32 v97, v33
	s_waitcnt vmcnt(3) lgkmcnt(0)
	s_barrier
	v_mov_b64_e32 v[64:65], v[16:17]
	v_mov_b64_e32 v[48:49], v[16:17]
	v_mov_b64_e32 v[32:33], v[16:17]
	s_mov_b64 s[4:5], 0
	v_mov_b64_e32 v[62:63], v[14:15]
	v_mov_b64_e32 v[60:61], v[12:13]
	v_mov_b64_e32 v[58:59], v[10:11]
	v_mov_b64_e32 v[56:57], v[8:9]
	v_mov_b64_e32 v[54:55], v[6:7]
	v_mov_b64_e32 v[52:53], v[4:5]
	v_mov_b64_e32 v[50:51], v[2:3]
	v_mov_b64_e32 v[46:47], v[14:15]
	v_mov_b64_e32 v[44:45], v[12:13]
	v_mov_b64_e32 v[42:43], v[10:11]
	v_mov_b64_e32 v[40:41], v[8:9]
	v_mov_b64_e32 v[38:39], v[6:7]
	v_mov_b64_e32 v[36:37], v[4:5]
	v_mov_b64_e32 v[34:35], v[2:3]
	v_mov_b64_e32 v[30:31], v[14:15]
	v_mov_b64_e32 v[28:29], v[12:13]
	v_mov_b64_e32 v[26:27], v[10:11]
	v_mov_b64_e32 v[24:25], v[8:9]
	v_mov_b64_e32 v[22:23], v[6:7]
	v_mov_b64_e32 v[20:21], v[4:5]
	v_mov_b64_e32 v[18:19], v[2:3]
	v_readfirstlane_b32 s100, v212
	v_readfirstlane_b32 s101, v213
.LBB0_573:
	v_mfma_f32_32x32x16_bf16 v[130:145], v[114:117], v[190:193], v[66:81]
	v_add_f32_e32 v118, v98, v99
	v_add_f32_e32 v118, v100, v118
	v_add_f32_e32 v118, v101, v118
	s_lshl_b32 s6, s6, 1
	v_add_f32_e32 v118, v102, v118
	v_add_u32_e32 v243, s6, v238
	v_add_f32_e32 v114, v103, v118
	v_cvt_pk_bf16_f32 v174, v98, v99
	v_cvt_pk_bf16_f32 v175, v100, v101
	s_nop 0
	v_add_f32_e32 v98, v104, v114
	v_mfma_f32_32x32x16_bf16 v[114:129], v[198:201], v[190:193], v[66:81]
	v_add_f32_e32 v98, v105, v98
	v_add_f32_e32 v98, v106, v98
	v_add_f32_e32 v98, v107, v98
	v_cvt_pk_bf16_f32 v176, v102, v103
	v_cvt_pk_bf16_f32 v177, v104, v105
	v_mfma_f32_32x32x16_bf16 v[130:145], v[202:205], v[186:189], v[130:145]
	v_add_f32_e32 v98, v108, v98
	v_add_f32_e32 v98, v109, v98
	v_add_f32_e32 v98, v110, v98
	v_add_f32_e32 v98, v111, v98
	v_cvt_pk_bf16_f32 v170, v106, v107
	v_cvt_pk_bf16_f32 v171, v108, v109
	v_mfma_f32_32x32x16_bf16 v[114:129], v[194:197], v[186:189], v[114:129]
	v_add_f32_e32 v98, v112, v98
	v_add_f32_e32 v98, v113, v98
	v_add_f32_e32 v98, v82, v98
	v_add_f32_e32 v98, v83, v98
	v_cvt_pk_bf16_f32 v172, v110, v111
	v_cvt_pk_bf16_f32 v173, v112, v113
	v_mfma_f32_32x32x16_bf16 v[130:145], v[158:161], v[182:185], v[130:145]
	v_add_f32_e32 v98, v84, v98
	v_add_f32_e32 v98, v85, v98
	v_add_f32_e32 v98, v86, v98
	v_add_f32_e32 v98, v87, v98
	v_cvt_pk_bf16_f32 v166, v82, v83
	v_cvt_pk_bf16_f32 v167, v84, v85
	v_mfma_f32_32x32x16_bf16 v[114:129], v[154:157], v[182:185], v[114:129]
	v_add_f32_e32 v82, v88, v98
	v_add_f32_e32 v82, v89, v82
	v_add_f32_e32 v82, v90, v82
	v_add_f32_e32 v82, v91, v82
	v_cvt_pk_bf16_f32 v168, v86, v87
	v_cvt_pk_bf16_f32 v169, v88, v89
	v_mfma_f32_32x32x16_bf16 v[130:145], v[150:153], v[178:181], v[130:145]
	v_add_f32_e32 v82, v92, v82
	v_add_f32_e32 v82, v93, v82
	v_add_f32_e32 v82, v94, v82
	v_add_f32_e32 v82, v95, v82
	v_cvt_pk_bf16_f32 v162, v90, v91
	v_cvt_pk_bf16_f32 v163, v92, v93
	v_mfma_f32_32x32x16_bf16 v[114:129], v[146:149], v[178:181], v[114:129]
	v_add_f32_e32 v82, v96, v82
	v_add_f32_e32 v82, v97, v82
	v_add_f32_e32 v242, v242, v82
	v_cvt_pk_bf16_f32 v164, v94, v95
	v_cvt_pk_bf16_f32 v165, v96, v97
	ds_read_b64_tr_b16 v[110:111], v243 offset:24576
	ds_read_b64_tr_b16 v[112:113], v243 offset:25088
	ds_read_b64_tr_b16 v[102:103], v243 offset:25600
	ds_read_b64_tr_b16 v[104:105], v243 offset:26112
	ds_read_b64_tr_b16 v[106:107], v243 offset:28672
	ds_read_b64_tr_b16 v[108:109], v243 offset:29184
	ds_read_b64_tr_b16 v[98:99], v243 offset:29696
	ds_read_b64_tr_b16 v[100:101], v243 offset:30208
	ds_read_b64_tr_b16 v[94:95], v243 offset:26624
	ds_read_b64_tr_b16 v[96:97], v243 offset:27136
	ds_read_b64_tr_b16 v[86:87], v243 offset:27648
	ds_read_b64_tr_b16 v[88:89], v243 offset:28160
	ds_read_b64_tr_b16 v[90:91], v243 offset:30720
	ds_read_b64_tr_b16 v[92:93], v243 offset:31232
	ds_read_b64_tr_b16 v[82:83], v243 offset:31744
	ds_read_b64_tr_b16 v[84:85], v243 offset:32256
	v_subrev_u32_e32 v216, s100, v212
	s_add_u32 s6, s100, s4
	s_addc_u32 s7, s101, s5
	s_add_u32 s6, s6, 0x120000
	s_addc_u32 s7, s7, 0
	s_add_i32 m0, s56, s33
	s_nop 0
	global_load_lds_dwordx4 v216, s[6:7]
	s_add_u32 s6, s27, s4
	s_addc_u32 s7, s35, s5
	s_add_u32 s6, s6, 0x6290800
	s_addc_u32 s7, s7, 0
	s_lshl_b32 s11, s45, 1
	s_add_i32 s8, s11, s28
	s_mov_b32 m0, s8
	s_nop 0
	global_load_lds_dwordx4 v0, s[6:7]
	s_addk_i32 s8, 0x1f80
	s_mov_b32 m0, s8
	s_nop 0
	global_load_lds_dwordx4 v0, s[6:7] offset:128
	v_max3_f32 v146, v130, v131, v132
	v_max3_f32 v147, v133, v134, v135
	v_max3_f32 v146, v146, v136, v137
	v_max3_f32 v147, v147, v138, v139
	v_max3_f32 v146, v146, v140, v141
	v_max3_f32 v147, v147, v142, v143
	v_max3_f32 v146, v146, v144, v145
	v_max3_f32 v147, v147, v114, v115
	v_max3_f32 v146, v146, v116, v117
	v_max3_f32 v147, v147, v118, v119
	v_max3_f32 v146, v146, v120, v121
	v_max3_f32 v147, v147, v122, v123
	v_max3_f32 v146, v146, v124, v125
	v_max3_f32 v147, v147, v126, v127
	v_max3_f32 v146, v146, v128, v129
	v_max_f32_e32 v146, v146, v147
	v_mov_b32_e32 v147, v146
	s_nop 1
	v_permlane32_swap_b32_e32 v146, v147
	v_max_f32_e32 v146, v146, v147
	v_cmp_lt_f32_e32 vcc, s15, v146
	s_cmp_lg_u64 vcc, 0
	s_cselect_b64 s[6:7], -1, 0
	s_cbranch_vccnz .LBB0_581

.LBB0_576:
	s_add_i32 s6, s45, 0x2000
	s_cmpk_lg_i32 s45, 0x4000
	s_cselect_b32 s57, s6, 0
	v_mfma_f32_32x32x16_bf16 v[98:113], v[82:85], v[190:193], v[66:81]
	v_add_f32_e32 v86, v130, v131
	v_add_f32_e32 v86, v132, v86
	v_add_f32_e32 v86, v133, v86
	s_lshl_b32 s6, s56, 1
	v_add_f32_e32 v86, v134, v86
	v_add_u32_e32 v243, s6, v238
	v_add_f32_e32 v82, v135, v86
	v_cvt_pk_bf16_f32 v174, v130, v131
	v_cvt_pk_bf16_f32 v175, v132, v133
	s_nop 0
	v_add_f32_e32 v82, v136, v82
	v_add_f32_e32 v82, v137, v82
	v_add_f32_e32 v82, v138, v82
	v_add_f32_e32 v130, v139, v82
	v_mfma_f32_32x32x16_bf16 v[82:97], v[198:201], v[190:193], v[66:81]
	v_cvt_pk_bf16_f32 v176, v134, v135
	v_cvt_pk_bf16_f32 v177, v136, v137
	v_mfma_f32_32x32x16_bf16 v[98:113], v[202:205], v[186:189], v[98:113]
	v_add_f32_e32 v130, v140, v130
	v_add_f32_e32 v130, v141, v130
	v_add_f32_e32 v130, v142, v130
	v_add_f32_e32 v130, v143, v130
	v_cvt_pk_bf16_f32 v170, v138, v139
	v_cvt_pk_bf16_f32 v171, v140, v141
	v_mfma_f32_32x32x16_bf16 v[82:97], v[194:197], v[186:189], v[82:97]
	v_add_f32_e32 v130, v144, v130
	v_add_f32_e32 v130, v145, v130
	v_add_f32_e32 v130, v114, v130
	v_add_f32_e32 v130, v115, v130
	v_cvt_pk_bf16_f32 v172, v142, v143
	v_cvt_pk_bf16_f32 v173, v144, v145
	v_mfma_f32_32x32x16_bf16 v[98:113], v[158:161], v[182:185], v[98:113]
	v_add_f32_e32 v130, v116, v130
	v_add_f32_e32 v130, v117, v130
	v_add_f32_e32 v130, v118, v130
	v_add_f32_e32 v130, v119, v130
	v_cvt_pk_bf16_f32 v166, v114, v115
	v_cvt_pk_bf16_f32 v167, v116, v117
	v_mfma_f32_32x32x16_bf16 v[82:97], v[154:157], v[182:185], v[82:97]
	v_add_f32_e32 v114, v120, v130
	v_add_f32_e32 v114, v121, v114
	v_add_f32_e32 v114, v122, v114
	v_add_f32_e32 v114, v123, v114
	v_cvt_pk_bf16_f32 v168, v118, v119
	v_cvt_pk_bf16_f32 v169, v120, v121
	v_mfma_f32_32x32x16_bf16 v[98:113], v[150:153], v[178:181], v[98:113]
	v_add_f32_e32 v114, v124, v114
	v_add_f32_e32 v114, v125, v114
	v_add_f32_e32 v114, v126, v114
	v_add_f32_e32 v114, v127, v114
	v_cvt_pk_bf16_f32 v162, v122, v123
	v_cvt_pk_bf16_f32 v163, v124, v125
	v_mfma_f32_32x32x16_bf16 v[82:97], v[146:149], v[178:181], v[82:97]
	v_add_f32_e32 v114, v128, v114
	v_add_f32_e32 v114, v129, v114
	v_add_f32_e32 v242, v242, v114
	v_cvt_pk_bf16_f32 v164, v126, v127
	v_cvt_pk_bf16_f32 v165, v128, v129
	ds_read_b64_tr_b16 v[142:143], v243 offset:24576
	ds_read_b64_tr_b16 v[144:145], v243 offset:25088
	ds_read_b64_tr_b16 v[134:135], v243 offset:25600
	ds_read_b64_tr_b16 v[136:137], v243 offset:26112
	ds_read_b64_tr_b16 v[138:139], v243 offset:28672
	ds_read_b64_tr_b16 v[140:141], v243 offset:29184
	ds_read_b64_tr_b16 v[130:131], v243 offset:29696
	ds_read_b64_tr_b16 v[132:133], v243 offset:30208
	ds_read_b64_tr_b16 v[126:127], v243 offset:26624
	ds_read_b64_tr_b16 v[128:129], v243 offset:27136
	ds_read_b64_tr_b16 v[118:119], v243 offset:27648
	ds_read_b64_tr_b16 v[120:121], v243 offset:28160
	ds_read_b64_tr_b16 v[122:123], v243 offset:30720
	ds_read_b64_tr_b16 v[124:125], v243 offset:31232
	ds_read_b64_tr_b16 v[114:115], v243 offset:31744
	ds_read_b64_tr_b16 v[116:117], v243 offset:32256
	s_add_u32 s6, s100, s4
	s_addc_u32 s7, s101, s5
	s_add_u32 s6, s6, 0x168000
	s_addc_u32 s7, s7, 0
	s_add_i32 m0, s45, s33
	s_nop 0
	global_load_lds_dwordx4 v216, s[6:7]
	s_add_u32 s6, s27, s4
	s_addc_u32 s7, s35, s5
	s_add_u32 s6, s6, 0x62d8800
	s_addc_u32 s7, s7, 0
	s_lshl_b32 s10, s57, 1
	s_add_i32 s8, s10, s28
	s_mov_b32 m0, s8
	s_nop 0
	global_load_lds_dwordx4 v0, s[6:7]
	s_addk_i32 s8, 0x1f80
	s_mov_b32 m0, s8
	s_nop 0
	global_load_lds_dwordx4 v0, s[6:7] offset:128
	v_max3_f32 v146, v98, v99, v100
	v_max3_f32 v147, v101, v102, v103
	v_max3_f32 v146, v146, v104, v105
	v_max3_f32 v147, v147, v106, v107
	v_max3_f32 v146, v146, v108, v109
	v_max3_f32 v147, v147, v110, v111
	v_max3_f32 v146, v146, v112, v113
	v_max3_f32 v147, v147, v82, v83
	v_max3_f32 v146, v146, v84, v85
	v_max3_f32 v147, v147, v86, v87
	v_max3_f32 v146, v146, v88, v89
	v_max3_f32 v147, v147, v90, v91
	v_max3_f32 v146, v146, v92, v93
	v_max3_f32 v147, v147, v94, v95
	v_max3_f32 v146, v146, v96, v97
	v_max_f32_e32 v146, v146, v147
	v_mov_b32_e32 v147, v146
	s_nop 1
	v_permlane32_swap_b32_e32 v146, v147
	v_max_f32_e32 v146, v146, v147
	v_cmp_lt_f32_e32 vcc, s15, v146
	s_cmp_lg_u64 vcc, 0
	s_cselect_b64 s[6:7], -1, 0
	s_cbranch_vccnz .LBB0_584

; #define WAIT_BAR(N) asm volatile("s_waitcnt vmcnt(" #N ") lgkmcnt(0)\n\ts_barrier":::"memory")
;   #define DMA_K(t,slot) glds16(ksrc+(long)(t)*KVBLK*PQ,(unsigned)__builtin_amdgcn_readfirstlane(kdst+(slot)))
;   #define DMA_V(t,slot) glds16(vsrc+(long)(t)*KVBLK*PQ,(unsigned)__builtin_amdgcn_readfirstlane(vdst+(slot)))
;   #define CMASK(P0,P1,t) do{}while(0)
;   #define CMASK(P0,P1,t) do{}while(0)
;   #define CMASK(P0,P1,t) do{}while(0)
;   #define DMA_K(t,slot) glds16((const char*)Kh+(size_t)(t)*(KVBLK*PQ*2)+koff,(unsigned)__builtin_amdgcn_readfirstlane(kdst+(slot)))
;   #define DMA_V(t,slot) do{ glds16((const char*)Vh+(size_t)(t)*(KVBLK*PQ*2)+voff,(unsigned)__builtin_amdgcn_readfirstlane(vdst+2*(slot))); glds16((const char*)Vh+(size_t)(t)*(KVBLK*PQ*2)+128+voff,(unsigned)__builtin_amdgcn_readfirstlane(vdst+2*(slot)+8192)); }while(0)
; template<int THRL> __device__ __forceinline__ void attn_unit(const bf16*Qblk,const bf16*__restrict__ Kh,const bf16*__restrict__ Vh,bf16*Oblk,const int po,const int NT,char*shm){
;   int tid_=threadIdx.x; asm volatile("":"+v"(tid_));
;   const int tid=tid_,lane=tid&63,r32=lane&31,hi=lane>>5; const int wid=__builtin_amdgcn_readfirstlane(tid>>6);
;   const bf16*Qw=Qblk+(long)wid*QBLK*PQ;
;   const unsigned lds0=(unsigned)(uintptr_t)shm;
;   float*wsf=(float*)(shm+LDS_WS)+wid*64;
;   const bf16*ksrc=Kh+(long)lane*PQ+wid*8;
;   const bf16*vsrc=Vh+(long)(16*(wid&3)+(lane>>2))*PQ+(wid>>2)*32+(lane&3)*8;
;   const unsigned kdst=lds0+LDS_K+wid*1024, vdst=lds0+LDS_V+wid*1024;
;     ...
;   const int vb0=(int)(lds0+LDS_V)+((lane>>4)&1)*32+(lane&3)*8+(4*hi+((lane&15)>>2))*64;
;   const char*Kbase=shm+LDS_K; bf16x8 kf[8];
;   const lds_cptr shm3=(lds_cptr)shm; const lds_cptr kp0=shm3+LDS_K+hi*1024+r32*16; const lds_cptr vp0=shm3+LDS_V+((lane>>4)&1)*32+(lane&3)*8+(4*hi+((lane&15)>>2))*64;
;   DMA_K(0,0);DMA_V(0,0);DMA_K(1,SLOTB);
;   bf16x8 qr[4];
;   #pragma unroll
;   for(int d0=0;d0<4;++d0)qr[d0]=*reinterpret_cast<const bf16x8*>(&Qw[(long)r32*PQ+d0*16+hi*8]);
;   float mhat=0.f,l_reg=0.f;f32x16 o[2];o[0]=f32x16{};o[1]=f32x16{};f32x16 negm=f32x16{};asm volatile("":"+v"(negm));
;     ...
;   bool resc=false;
;     ...
;   f32x16 pA0,pA1,pB0,pB1;
;   int sl_prev=0,sl_cur=0,sl_next=SLOTB;
;     ...
;   DMA_K(2,2*SLOTB);
;   WAIT_BAR(3);
;   qkt(pA0,pA1,Kbase,qr,negm,r32,hi);asm volatile("s_nop 15\n\ts_nop 7":"+v"(pA0),"+v"(pA1));CMASK(pA0,pA1,0);
.LBB0_680:
	s_and_b64 vcc, exec, s[2:3]
	s_cbranch_vccz .LBB0_656
	s_lshl_b32 s3, s8, 8
	s_ashr_i32 s2, s8, 9
	s_and_b32 s3, s3, 0x3f00
	s_addk_i32 s3, 0x100
	s_mul_i32 s4, s2, 0x4100
	s_mul_hi_i32 s5, s2, 0x4100
	s_add_u32 s4, s4, s3
	s_addc_u32 s5, s5, 0
	s_mul_i32 s3, s5, 0x1200
	s_mul_hi_u32 s6, s4, 0x1200
	s_add_i32 s6, s6, s3
	s_mul_i32 s3, s4, 0x1200
	s_add_u32 s3, s58, s3
	s_addc_u32 s6, s59, s6
	s_and_b32 s18, s8, 0x1c0
	s_lshl_b32 s7, s18, 1
	s_add_u32 s7, s3, s7
	s_addc_u32 s6, s6, 0
	s_mul_hi_i32 s3, s2, 0x4920000
	s_mul_i32 s2, s2, 0x4920000
	s_add_u32 s2, s58, s2
	s_addc_u32 s3, s59, s3
	s_lshr_b32 s8, s8, 1
	s_and_b32 s8, s8, 0x80
	v_mov_b32_e32 v42, v220
	s_add_u32 s8, s2, s8
	s_addc_u32 s9, s3, 0
	v_readfirstlane_b32 s19, v42
	v_and_b32_e32 v198, 63, v42
	s_ashr_i32 s2, s19, 6
	s_ashr_i32 s3, s2, 31
	s_mul_i32 s21, s2, 0x24000
	v_mul_u32_u24_e32 v0, 0x900, v198
	s_mul_hi_i32 s20, s2, 0x24000
	s_add_u32 s22, s7, s21
	v_lshlrev_b32_e32 v0, 1, v0
	s_addc_u32 s23, s6, s20
	v_lshl_add_u64 v[2:3], s[8:9], 0, v[0:1]
	s_lshl_b32 s6, s2, 4
	v_bfe_u32 v0, v42, 2, 4
	v_and_or_b32 v0, s6, 48, v0
	s_lshl_b32 s20, s2, 3
	v_mul_u32_u24_e32 v0, 0x900, v0
	s_ashr_i32 s21, s20, 31
	v_lshlrev_b32_e32 v0, 1, v0
	s_ashr_i32 s6, s19, 3
	v_lshl_add_u64 v[86:87], s[20:21], 1, v[2:3]
	v_lshl_add_u64 v[2:3], s[8:9], 0, v[0:1]
	s_and_b32 s8, s6, 0xffffffe0
	v_lshlrev_b32_e32 v199, 3, v42
	s_ashr_i32 s9, s8, 31
	v_and_b32_e32 v202, 24, v199
	s_and_b32 s7, s19, 0x3fffffc0
	v_lshl_add_u64 v[2:3], s[8:9], 1, v[2:3]
	v_lshlrev_b32_e32 v0, 1, v202
	s_lshl_b32 s6, s2, 10
	v_lshl_add_u64 v[88:89], v[2:3], 0, v[0:1]
	s_mov_b64 s[8:9], 0x1100
	s_cmp_lg_u32 0, -1
	s_mov_b64 s[20:21], 0x1000
	v_lshl_add_u64 v[194:195], v[88:89], 0, s[8:9]
	s_cselect_b32 s8, 0, 0
	v_and_b32_e32 v200, 31, v42
	v_bfe_u32 v201, v42, 5, 1
	v_lshl_add_u64 v[196:197], v[86:87], 0, s[20:21]
	s_add_i32 s20, s6, s8
	s_mov_b32 s6, m0
	s_mov_b32 m0, s20
	s_nop 0
	global_load_lds_dwordx4 v[196:197], off
	s_mov_b32 m0, s6
	s_add_i32 s19, s20, 0x6000
	s_mov_b32 s6, m0
	s_mov_b32 m0, s19
	s_nop 0
	global_load_lds_dwordx4 v[194:195], off
	s_mov_b32 m0, s6
	s_mov_b64 s[8:9], 0x49000
	v_mul_u32_u24_e32 v0, 0x900, v200
	v_lshlrev_b32_e32 v212, 4, v201
	v_lshl_add_u64 v[2:3], v[86:87], 0, s[8:9]
	s_add_i32 s6, s20, 0x2000
	s_mov_b32 s8, m0
	s_mov_b32 m0, s6
	s_nop 0
	global_load_lds_dwordx4 v[2:3], off
	s_mov_b32 m0, s8
	v_lshl_or_b32 v0, v0, 1, v212
	global_load_dwordx4 v[158:161], v0, s[22:23] offset:3072
	global_load_dwordx4 v[154:157], v0, s[22:23] offset:3104
	global_load_dwordx4 v[146:149], v0, s[22:23] offset:3136
	global_load_dwordx4 v[138:141], v0, s[22:23] offset:3168
	v_lshlrev_b32_e32 v2, 10, v201
	v_lshlrev_b32_e32 v3, 4, v200
	v_add3_u32 v210, 0, v2, v3
	v_mov_b32_e32 v2, v1
	v_mov_b32_e32 v3, v1
	v_mov_b32_e32 v4, v1
	v_mov_b32_e32 v5, v1
	v_mov_b32_e32 v6, v1
	v_mov_b32_e32 v7, v1
	v_mov_b32_e32 v8, v1
	v_mov_b32_e32 v9, v1
	v_mov_b32_e32 v10, v1
	v_mov_b32_e32 v11, v1
	v_mov_b32_e32 v12, v1
	v_mov_b32_e32 v13, v1
	v_mov_b32_e32 v14, v1
	v_mov_b32_e32 v15, v1
	v_mov_b32_e32 v0, v1
	v_mov_b64_e32 v[16:17], v[14:15]
	v_mov_b64_e32 v[14:15], v[12:13]
	v_mov_b64_e32 v[12:13], v[10:11]
	v_mov_b64_e32 v[10:11], v[8:9]
	v_mov_b64_e32 v[8:9], v[6:7]
	v_mov_b64_e32 v[6:7], v[4:5]
	v_mov_b64_e32 v[4:5], v[2:3]
	v_mov_b64_e32 v[2:3], v[0:1]
	s_mov_b64 s[8:9], 0x91000
	v_lshl_add_u64 v[18:19], v[86:87], 0, s[8:9]
	s_add_i32 s6, s20, 0x4000
	s_mov_b32 s8, m0
	s_mov_b32 m0, s6
	s_nop 0
	global_load_lds_dwordx4 v[18:19], off
	s_mov_b32 m0, s8
	s_waitcnt vmcnt(3) lgkmcnt(0)
	s_barrier
	ds_read_b128 v[34:37], v210
	ds_read_b128 v[38:41], v210 offset:512
	s_waitcnt vmcnt(3) lgkmcnt(1)
	v_mfma_f32_32x32x16_bf16 v[18:33], v[34:37], v[158:161], v[2:17]
	v_lshlrev_b32_e32 v0, 1, v42
	v_and_b32_e32 v203, 32, v0
	s_lshl_b32 s7, s7, 2
	s_mov_b64 s[8:9], 0xd9000
	s_add_i32 s21, s7, 0
	v_add_u32_e32 v82, 0, v203
	v_mov_b32_e32 v186, 0
	s_waitcnt lgkmcnt(0)
	v_mfma_f32_32x32x16_bf16 v[2:17], v[38:41], v[158:161], v[2:17]
	ds_read_b128 v[34:37], v210 offset:2048
	ds_read_b128 v[38:41], v210 offset:2560
	s_mov_b32 s22, -1
	s_mov_b32 s6, 0
	s_movk_i32 s26, 0x2000
	s_movk_i32 s23, 0x4000
	v_cmp_gt_u32_e64 s[40:41], 32, v198
	v_lshl_add_u32 v204, v200, 2, s21
	s_waitcnt vmcnt(2) lgkmcnt(1)
	v_mfma_f32_32x32x16_bf16 v[18:33], v[34:37], v[154:157], v[18:33]
	s_waitcnt lgkmcnt(0)
	v_mfma_f32_32x32x16_bf16 v[2:17], v[38:41], v[154:157], v[2:17]
	ds_read_b128 v[34:37], v210 offset:4096
	ds_read_b128 v[38:41], v210 offset:4608
	s_waitcnt vmcnt(1) lgkmcnt(1)
	v_mfma_f32_32x32x16_bf16 v[18:33], v[34:37], v[146:149], v[18:33]
	ds_read_b128 v[34:37], v210 offset:6144
	s_waitcnt lgkmcnt(1)
	v_mfma_f32_32x32x16_bf16 v[2:17], v[38:41], v[146:149], v[2:17]
	ds_read_b128 v[38:41], v210 offset:6656
	s_waitcnt vmcnt(0) lgkmcnt(1)
	v_mfma_f32_32x32x16_bf16 v[18:33], v[34:37], v[138:141], v[18:33]
	v_lshlrev_b32_e32 v34, 4, v42
	v_and_b32_e32 v0, 0xc0, v34
	v_lshl_or_b32 v0, v201, 8, v0
	v_add3_u32 v211, v82, v202, v0
	s_waitcnt lgkmcnt(0)
; #define WAIT_BAR(N) asm volatile("s_waitcnt vmcnt(" #N ") lgkmcnt(0)\n\ts_barrier":::"memory")
;   #define DMA_K(t,slot) glds16(ksrc+(long)(t)*KVBLK*PQ,(unsigned)__builtin_amdgcn_readfirstlane(kdst+(slot)))
;   #define DMA_V(t,slot) glds16(vsrc+(long)(t)*KVBLK*PQ,(unsigned)__builtin_amdgcn_readfirstlane(vdst+(slot)))
;   #define CMASK(P0,P1,t) do{}while(0)
;   #define START(P0,P1) do{ const float rm=rowmax(P0,P1); resc=false; \
;     { const float dl=rm; mhat=fadd_s(mhat,dl); \
;       _Pragma("unroll") for(int r=0;r<16;++r){P0[r]=fsub_s(P0[r],dl);P1[r]=fsub_s(P1[r],dl);} \
;       _Pragma("unroll") for(int r=0;r<16;++r)negm[r]=-mhat; asm volatile("":"+v"(negm)); } \
;     _Pragma("unroll") for(int r=0;r<16;++r)P0[r]=__builtin_amdgcn_exp2f(P0[r]); }while(0)
;   #define ROT() do{sl_prev=sl_cur;sl_cur=sl_next;sl_next=(sl_next==(NSLOT-1)*SLOTB)?0:sl_next+SLOTB;}while(0)
;   #define CMASK(P0,P1,t) do{}while(0)
;   #define CMASK(P0,P1,t) do{}while(0)
;   #define DMA_K(t,slot) glds16((const char*)Kh+(size_t)(t)*(KVBLK*PQ*2)+koff,(unsigned)__builtin_amdgcn_readfirstlane(kdst+(slot)))
;   #define DMA_V(t,slot) do{ glds16((const char*)Vh+(size_t)(t)*(KVBLK*PQ*2)+voff,(unsigned)__builtin_amdgcn_readfirstlane(vdst+2*(slot))); glds16((const char*)Vh+(size_t)(t)*(KVBLK*PQ*2)+128+voff,(unsigned)__builtin_amdgcn_readfirstlane(vdst+2*(slot)+8192)); }while(0)
;   #define CMASK(P0,P1,t) do{}while(0)
;   #define ROT() do{sl_prev=sl_cur;sl_cur=sl_next;sl_next=(sl_next==(NSLOT-1)*SLOTB)?0:sl_next+SLOTB;}while(0)
;   #define CMASK(P0,P1,t) do{}while(0)
;   #define CMASK(P0,P1,t) do{}while(0)
; template<int THRL> __device__ __forceinline__ void attn_unit(const bf16*Qblk,const bf16*__restrict__ Kh,const bf16*__restrict__ Vh,bf16*Oblk,const int po,const int NT,char*shm){
;     ...
;   f32x16 pA0,pA1,pB0,pB1;
;   int sl_prev=0,sl_cur=0,sl_next=SLOTB;
;     ...
;   DMA_K(2,2*SLOTB);
;   WAIT_BAR(3);
;   qkt(pA0,pA1,Kbase,qr,negm,r32,hi);asm volatile("s_nop 15\n\ts_nop 7":"+v"(pA0),"+v"(pA1));CMASK(pA0,pA1,0);
;   START(pA0,pA1);
;   _Pragma("unroll") for(int r=0;r<16;++r)pA1[r]=__builtin_amdgcn_exp2f(pA1[r]);
;   WAIT_BAR(0);
;   DMA_K(3,0);DMA_V(1,SLOTB);
;   ROT();
;   kload8(kf,kp0+sl_cur);
;   WAIT_BAR(2);
;   s16x4 vlo[8],vhi[8]; u32x4 pw0,pw1,pw2,pw3;
	v_mfma_f32_32x32x16_bf16 v[2:17], v[38:41], v[138:141], v[2:17]
	s_nop 15
	s_nop 7
	s_nop 0
	v_max3_f32 v34, v18, v19, v2
	v_max3_f32 v35, v20, v21, v3
	s_nop 0
	v_max3_f32 v34, v34, v4, v5
	v_max3_f32 v35, v35, v24, v25
	s_nop 0
	v_max3_f32 v34, v34, v22, v23
	v_max3_f32 v35, v35, v8, v9
	s_nop 0
	v_max3_f32 v34, v34, v6, v7
	v_max3_f32 v35, v35, v28, v29
	s_nop 0
	v_max3_f32 v34, v34, v26, v27
	v_max3_f32 v35, v35, v12, v13
	s_nop 0
	v_max3_f32 v34, v34, v10, v11
	v_max3_f32 v35, v35, v32, v33
	s_nop 0
	v_max3_f32 v34, v34, v30, v31
	v_max3_f32 v35, v35, v16, v17
	s_nop 0
	v_max3_f32 v34, v34, v14, v15
	s_nop 0
	v_max_f32_e32 v34, v34, v35
	s_nop 0
	v_mov_b32_e32 v35, v34
	s_nop 1
	v_permlane32_swap_b32_e32 v34, v35
	v_max_f32_e32 v34, v34, v35
	s_nop 0
	v_add_f32_e32 v205, v1, v34
	v_sub_f32_e32 v18, v18, v34
	v_sub_f32_e32 v2, v2, v34
	v_sub_f32_e32 v19, v19, v34
	v_sub_f32_e32 v3, v3, v34
	v_sub_f32_e32 v20, v20, v34
	v_sub_f32_e32 v4, v4, v34
	v_sub_f32_e32 v21, v21, v34
	v_sub_f32_e32 v5, v5, v34
	v_sub_f32_e32 v22, v22, v34
	v_sub_f32_e32 v6, v6, v34
	v_sub_f32_e32 v23, v23, v34
	v_sub_f32_e32 v7, v7, v34
	v_sub_f32_e32 v24, v24, v34
	v_sub_f32_e32 v8, v8, v34
	v_sub_f32_e32 v25, v25, v34
	v_sub_f32_e32 v9, v9, v34
	v_sub_f32_e32 v26, v26, v34
	v_sub_f32_e32 v10, v10, v34
	v_sub_f32_e32 v27, v27, v34
	v_sub_f32_e32 v11, v11, v34
	v_sub_f32_e32 v28, v28, v34
	v_sub_f32_e32 v12, v12, v34
	v_sub_f32_e32 v29, v29, v34
	v_sub_f32_e32 v13, v13, v34
	v_sub_f32_e32 v30, v30, v34
	v_sub_f32_e32 v14, v14, v34
	v_sub_f32_e32 v31, v31, v34
	v_sub_f32_e32 v15, v15, v34
	v_sub_f32_e32 v32, v32, v34
	v_sub_f32_e32 v16, v16, v34
	v_sub_f32_e32 v33, v33, v34
	v_sub_f32_e32 v17, v17, v34
	s_nop 0
	v_xor_b32_e32 v34, 0x80000000, v205
	v_mov_b32_e32 v35, v34
	v_mov_b32_e32 v36, v34
	v_mov_b32_e32 v37, v34
	v_mov_b32_e32 v38, v34
	v_mov_b32_e32 v39, v34
	v_mov_b32_e32 v40, v34
	v_mov_b32_e32 v41, v34
	v_mov_b32_e32 v42, v34
	v_mov_b32_e32 v43, v34
	v_mov_b32_e32 v44, v34
	v_mov_b32_e32 v45, v34
	v_mov_b32_e32 v46, v34
	v_mov_b32_e32 v47, v34
	v_mov_b32_e32 v48, v34
	v_mov_b32_e32 v49, v34
	s_waitcnt vmcnt(0) lgkmcnt(0)
	s_barrier
	v_exp_f32_e32 v50, v2
	v_exp_f32_e32 v51, v3
	v_lshl_add_u64 v[2:3], v[86:87], 0, s[8:9]
	s_mov_b32 s7, m0
	s_mov_b32 m0, s20
	s_nop 0
	global_load_lds_dwordx4 v[2:3], off
	s_mov_b32 m0, s7
	s_mov_b64 s[8:9], 0x49100
	v_lshl_add_u64 v[2:3], v[88:89], 0, s[8:9]
	s_add_i32 s7, s20, 0x8000
	s_mov_b32 s8, m0
	s_mov_b32 m0, s7
	s_nop 0
	global_load_lds_dwordx4 v[2:3], off
	s_mov_b32 m0, s8
	ds_read_b128 v[82:85], v210 offset:8192
	ds_read_b128 v[166:169], v210 offset:8704
	ds_read_b128 v[170:173], v210 offset:10240
	ds_read_b128 v[162:165], v210 offset:10752
	ds_read_b128 v[126:129], v210 offset:12288
	ds_read_b128 v[122:125], v210 offset:12800
	ds_read_b128 v[118:121], v210 offset:14336
	ds_read_b128 v[114:117], v210 offset:14848
	v_exp_f32_e32 v66, v18
	v_exp_f32_e32 v67, v19
	v_exp_f32_e32 v68, v20
	v_exp_f32_e32 v69, v21
	v_exp_f32_e32 v70, v22
	v_exp_f32_e32 v71, v23
	v_exp_f32_e32 v72, v24
	v_exp_f32_e32 v73, v25
	v_exp_f32_e32 v74, v26
	v_exp_f32_e32 v75, v27
	v_exp_f32_e32 v76, v28
	v_exp_f32_e32 v77, v29
	v_exp_f32_e32 v78, v30
	v_exp_f32_e32 v79, v31
	v_exp_f32_e32 v80, v32
	v_exp_f32_e32 v81, v33
	v_exp_f32_e32 v52, v4
	v_exp_f32_e32 v53, v5
	v_exp_f32_e32 v54, v6
	v_exp_f32_e32 v55, v7
	v_exp_f32_e32 v56, v8
	v_exp_f32_e32 v57, v9
	v_exp_f32_e32 v58, v10
	v_exp_f32_e32 v59, v11
	v_exp_f32_e32 v60, v12
	v_exp_f32_e32 v61, v13
	v_exp_f32_e32 v62, v14
	v_exp_f32_e32 v63, v15
	v_exp_f32_e32 v64, v16
	v_exp_f32_e32 v65, v17
	s_waitcnt vmcnt(2) lgkmcnt(0)
	s_barrier
	s_mov_b64 s[8:9], 0xd9100
	v_lshl_add_u64 v[182:183], v[88:89], 0, s[8:9]
	s_mov_b64 s[8:9], 0x169000
	v_lshl_add_u64 v[184:185], v[86:87], 0, s[8:9]
	v_mov_b32_e32 v2, 0
	v_mov_b32_e32 v3, v186
	v_mov_b32_e32 v4, v186
	v_mov_b32_e32 v5, v186
	v_mov_b32_e32 v6, v186
	v_mov_b32_e32 v7, v186
	v_mov_b32_e32 v8, v186
	v_mov_b32_e32 v9, v186
	v_mov_b32_e32 v10, v186
	v_mov_b32_e32 v11, v186
	v_mov_b32_e32 v12, v186
	v_mov_b32_e32 v13, v186
	v_mov_b32_e32 v14, v186
	v_mov_b32_e32 v15, v186
	v_mov_b32_e32 v16, v186
	v_mov_b32_e32 v17, v186
	v_mov_b32_e32 v18, 0
	v_mov_b32_e32 v19, v186
	v_mov_b32_e32 v20, v186
	v_mov_b32_e32 v21, v186
	v_mov_b32_e32 v22, v186
	v_mov_b32_e32 v23, v186
	v_mov_b32_e32 v24, v186
	v_mov_b32_e32 v25, v186
	v_mov_b32_e32 v26, v186
	v_mov_b32_e32 v27, v186
	v_mov_b32_e32 v28, v186
	v_mov_b32_e32 v29, v186
	v_mov_b32_e32 v30, v186
	v_mov_b32_e32 v31, v186
	v_mov_b32_e32 v32, v186
	v_mov_b32_e32 v33, v186
	v_readfirstlane_b32 s100, v184
	v_readfirstlane_b32 s101, v185
	v_readfirstlane_b32 s66, v182
	v_readfirstlane_b32 s67, v183
	s_nop 1
	v_subrev_u32_e32 v184, s100, v184
	v_subrev_u32_e32 v182, s66, v182
.LBB0_682:
	v_add_u32_e32 v187, s6, v211
	ds_read_b64_tr_b16 v[178:179], v187 offset:24576
	ds_read_b64_tr_b16 v[180:181], v187 offset:25088
	v_mfma_f32_32x32x16_bf16 v[98:113], v[82:85], v[158:161], v[34:49]
	v_add_f32_e32 v86, v66, v67
	v_add_f32_e32 v86, v68, v86
	v_add_f32_e32 v86, v69, v86
	v_add_f32_e32 v86, v70, v86
	v_add_f32_e32 v86, v71, v86
	v_cvt_pk_bf16_f32 v150, v66, v67
	v_cvt_pk_bf16_f32 v151, v68, v69
	ds_read_b64_tr_b16 v[174:175], v187 offset:28672
	ds_read_b64_tr_b16 v[176:177], v187 offset:29184
	v_add_f32_e32 v66, v72, v86
	v_mfma_f32_32x32x16_bf16 v[82:97], v[166:169], v[158:161], v[34:49]
	v_add_f32_e32 v66, v73, v66
	v_add_f32_e32 v66, v74, v66
	v_add_f32_e32 v130, v75, v66
	v_cvt_pk_bf16_f32 v152, v70, v71
	v_cvt_pk_bf16_f32 v153, v72, v73
	ds_read_b64_tr_b16 v[66:67], v187 offset:25600
	ds_read_b64_tr_b16 v[68:69], v187 offset:26112
	v_mfma_f32_32x32x16_bf16 v[98:113], v[170:173], v[154:157], v[98:113]
	v_add_f32_e32 v70, v76, v130
	v_add_f32_e32 v70, v77, v70
	v_add_f32_e32 v70, v78, v70
	v_add_f32_e32 v130, v79, v70
	v_cvt_pk_bf16_f32 v142, v74, v75
	v_cvt_pk_bf16_f32 v143, v76, v77
	ds_read_b64_tr_b16 v[70:71], v187 offset:29696
	ds_read_b64_tr_b16 v[72:73], v187 offset:30208
	v_mfma_f32_32x32x16_bf16 v[82:97], v[162:165], v[154:157], v[82:97]
	v_add_f32_e32 v74, v80, v130
	v_add_f32_e32 v74, v81, v74
	v_add_f32_e32 v74, v50, v74
	v_add_f32_e32 v130, v51, v74
	v_cvt_pk_bf16_f32 v144, v78, v79
	v_cvt_pk_bf16_f32 v145, v80, v81
	ds_read_b64_tr_b16 v[74:75], v187 offset:26624
	ds_read_b64_tr_b16 v[76:77], v187 offset:27136
	v_mfma_f32_32x32x16_bf16 v[98:113], v[126:129], v[146:149], v[98:113]
	v_add_f32_e32 v78, v52, v130
	v_add_f32_e32 v78, v53, v78
	v_add_f32_e32 v78, v54, v78
	v_add_f32_e32 v78, v55, v78
	v_cvt_pk_bf16_f32 v134, v50, v51
	v_cvt_pk_bf16_f32 v135, v52, v53
	ds_read_b64_tr_b16 v[50:51], v187 offset:30720
	ds_read_b64_tr_b16 v[52:53], v187 offset:31232
	v_mfma_f32_32x32x16_bf16 v[82:97], v[122:125], v[146:149], v[82:97]
	v_add_f32_e32 v78, v56, v78
	v_add_f32_e32 v78, v57, v78
	v_add_f32_e32 v78, v58, v78
	v_add_f32_e32 v78, v59, v78
	v_cvt_pk_bf16_f32 v136, v54, v55
	v_cvt_pk_bf16_f32 v137, v56, v57
	ds_read_b64_tr_b16 v[54:55], v187 offset:27648
	ds_read_b64_tr_b16 v[56:57], v187 offset:28160
	v_mfma_f32_32x32x16_bf16 v[98:113], v[118:121], v[138:141], v[98:113]
	v_add_f32_e32 v78, v60, v78
	v_add_f32_e32 v78, v61, v78
	v_add_f32_e32 v78, v62, v78
	v_add_f32_e32 v78, v63, v78
	v_cvt_pk_bf16_f32 v130, v58, v59
	v_cvt_pk_bf16_f32 v131, v60, v61
	ds_read_b64_tr_b16 v[58:59], v187 offset:31744
	ds_read_b64_tr_b16 v[60:61], v187 offset:32256
	v_mfma_f32_32x32x16_bf16 v[82:97], v[114:117], v[138:141], v[82:97]
	v_add_f32_e32 v78, v64, v78
	v_add_f32_e32 v78, v65, v78
	v_cvt_pk_bf16_f32 v132, v62, v63
	v_cvt_pk_bf16_f32 v133, v64, v65
	s_add_i32 m0, s26, s20
	s_add_u32 s6, s100, 0xfffb8000
	s_addc_u32 s7, s101, -1
	global_load_lds_dwordx4 v184, s[6:7]
	s_add_i32 m0, s23, s19
	s_add_u32 s6, s66, 0xfffb8000
	s_addc_u32 s7, s67, -1
	global_load_lds_dwordx4 v182, s[6:7]
	v_max3_f32 v62, v98, v99, v100
	v_max3_f32 v63, v101, v102, v103
	v_max3_f32 v62, v62, v104, v105
	v_max3_f32 v63, v63, v106, v107
	v_max3_f32 v62, v62, v108, v109
	v_max3_f32 v63, v63, v110, v111
	v_max3_f32 v62, v62, v112, v113
	v_max3_f32 v63, v63, v82, v83
	v_max3_f32 v62, v62, v84, v85
	v_max3_f32 v63, v63, v86, v87
	v_max3_f32 v62, v62, v88, v89
	v_max3_f32 v63, v63, v90, v91
	v_max3_f32 v62, v62, v92, v93
	v_max3_f32 v63, v63, v94, v95
	v_max3_f32 v62, v62, v96, v97
	v_max_f32_e32 v62, v62, v63
	v_mov_b32_e32 v63, v62
	s_nop 1
	v_permlane32_swap_b32_e32 v62, v63
	v_max_f32_e32 v62, v62, v63
	v_cmp_lt_f32_e32 vcc, s15, v62
	s_cmp_lg_u64 vcc, 0
	v_add_f32_e32 v186, v186, v78
	s_cselect_b64 s[6:7], -1, 0
	s_cbranch_vccnz .LBB0_690

.LBB0_685:
	s_add_i32 s6, s23, 0x2000
	s_cmpk_lg_i32 s23, 0x4000
	s_cselect_b32 s24, s6, 0
	v_add_u32_e32 v187, s26, v211
	ds_read_b64_tr_b16 v[118:119], v187 offset:24576
	ds_read_b64_tr_b16 v[120:121], v187 offset:25088
	v_mfma_f32_32x32x16_bf16 v[66:81], v[62:65], v[158:161], v[34:49]
	v_add_f32_e32 v50, v98, v99
	v_add_f32_e32 v50, v100, v50
	v_add_f32_e32 v50, v101, v50
	v_add_f32_e32 v50, v102, v50
	v_add_f32_e32 v50, v103, v50
	v_cvt_pk_bf16_f32 v150, v98, v99
	v_cvt_pk_bf16_f32 v151, v100, v101
	ds_read_b64_tr_b16 v[114:115], v187 offset:28672
	ds_read_b64_tr_b16 v[116:117], v187 offset:29184
	v_add_f32_e32 v50, v104, v50
	v_add_f32_e32 v50, v105, v50
	v_add_f32_e32 v50, v106, v50
	v_add_f32_e32 v130, v107, v50
	v_mfma_f32_32x32x16_bf16 v[50:65], v[174:177], v[158:161], v[34:49]
	v_cvt_pk_bf16_f32 v152, v102, v103
	v_cvt_pk_bf16_f32 v153, v104, v105
	ds_read_b64_tr_b16 v[98:99], v187 offset:25600
	ds_read_b64_tr_b16 v[100:101], v187 offset:26112
	v_mfma_f32_32x32x16_bf16 v[66:81], v[178:181], v[154:157], v[66:81]
	v_add_f32_e32 v102, v108, v130
	v_add_f32_e32 v102, v109, v102
	v_add_f32_e32 v102, v110, v102
	v_add_f32_e32 v130, v111, v102
	v_cvt_pk_bf16_f32 v142, v106, v107
	v_cvt_pk_bf16_f32 v143, v108, v109
	ds_read_b64_tr_b16 v[102:103], v187 offset:29696
	ds_read_b64_tr_b16 v[104:105], v187 offset:30208
	v_mfma_f32_32x32x16_bf16 v[50:65], v[170:173], v[154:157], v[50:65]
	v_add_f32_e32 v106, v112, v130
	v_add_f32_e32 v106, v113, v106
	v_add_f32_e32 v106, v82, v106
	v_add_f32_e32 v130, v83, v106
	v_cvt_pk_bf16_f32 v144, v110, v111
	v_cvt_pk_bf16_f32 v145, v112, v113
	ds_read_b64_tr_b16 v[106:107], v187 offset:26624
	ds_read_b64_tr_b16 v[108:109], v187 offset:27136
	v_mfma_f32_32x32x16_bf16 v[66:81], v[166:169], v[146:149], v[66:81]
	v_add_f32_e32 v110, v84, v130
	v_add_f32_e32 v110, v85, v110
	v_add_f32_e32 v110, v86, v110
	v_add_f32_e32 v130, v87, v110
	v_cvt_pk_bf16_f32 v134, v82, v83
	v_cvt_pk_bf16_f32 v135, v84, v85
	ds_read_b64_tr_b16 v[110:111], v187 offset:30720
	ds_read_b64_tr_b16 v[112:113], v187 offset:31232
	v_mfma_f32_32x32x16_bf16 v[50:65], v[162:165], v[146:149], v[50:65]
	v_add_f32_e32 v82, v88, v130
	v_add_f32_e32 v82, v89, v82
	v_add_f32_e32 v82, v90, v82
	v_add_f32_e32 v82, v91, v82
	v_cvt_pk_bf16_f32 v136, v86, v87
	v_cvt_pk_bf16_f32 v137, v88, v89
	ds_read_b64_tr_b16 v[86:87], v187 offset:27648
	ds_read_b64_tr_b16 v[88:89], v187 offset:28160
	v_mfma_f32_32x32x16_bf16 v[66:81], v[126:129], v[138:141], v[66:81]
	v_add_f32_e32 v82, v92, v82
	v_add_f32_e32 v82, v93, v82
	v_add_f32_e32 v82, v94, v82
	v_add_f32_e32 v82, v95, v82
	v_cvt_pk_bf16_f32 v130, v90, v91
	v_cvt_pk_bf16_f32 v131, v92, v93
	ds_read_b64_tr_b16 v[90:91], v187 offset:31744
	ds_read_b64_tr_b16 v[92:93], v187 offset:32256
	v_mfma_f32_32x32x16_bf16 v[50:65], v[122:125], v[138:141], v[50:65]
	v_add_f32_e32 v82, v96, v82
	v_add_f32_e32 v82, v97, v82
	v_cvt_pk_bf16_f32 v132, v94, v95
	v_cvt_pk_bf16_f32 v133, v96, v97
	v_add_f32_e32 v186, v186, v82
	s_add_i32 m0, s23, s20
	s_nop 0
	global_load_lds_dwordx4 v184, s[100:101]
	s_add_i32 m0, s24, s19
	s_nop 0
	global_load_lds_dwordx4 v182, s[66:67]
	v_max3_f32 v82, v66, v67, v68
	v_max3_f32 v83, v69, v70, v71
	v_max3_f32 v82, v82, v72, v73
	v_max3_f32 v83, v83, v74, v75
	v_max3_f32 v82, v82, v76, v77
	v_max3_f32 v83, v83, v78, v79
	v_max3_f32 v82, v82, v80, v81
	v_max3_f32 v83, v83, v50, v51
	v_max3_f32 v82, v82, v52, v53
	v_max3_f32 v83, v83, v54, v55
	v_max3_f32 v82, v82, v56, v57
	v_max3_f32 v83, v83, v58, v59
	v_max3_f32 v82, v82, v60, v61
	v_max3_f32 v83, v83, v62, v63
	v_max3_f32 v82, v82, v64, v65
	v_max_f32_e32 v82, v82, v83
	v_mov_b32_e32 v83, v82
	s_nop 1
	v_permlane32_swap_b32_e32 v82, v83
	v_max_f32_e32 v82, v82, v83
	v_cmp_lt_f32_e32 vcc, s15, v82
	s_cmp_lg_u64 vcc, 0
	s_cselect_b64 s[6:7], -1, 0
	s_cbranch_vccnz .LBB0_693

; #define WAIT_BAR(N) asm volatile("s_waitcnt vmcnt(" #N ") lgkmcnt(0)\n\ts_barrier":::"memory")
;   #define RESC() do{ if(resc){ asm volatile("s_waitcnt lgkmcnt(0)":::"memory"); \
;       _Pragma("unroll") for(int d_=0;d_<2;++d_) _Pragma("unroll") for(int r=0;r<16;++r)o[d_][r]*=wsf[crow(r,hi)]; } }while(0)
;   #define ROT() do{sl_prev=sl_cur;sl_cur=sl_next;sl_next=(sl_next==(NSLOT-1)*SLOTB)?0:sl_next+SLOTB;}while(0)
;   #define RESC() do{ if(resc){ asm volatile("s_waitcnt lgkmcnt(0)":::"memory"); \
;       _Pragma("unroll") for(int d_=0;d_<4;++d_) _Pragma("unroll") for(int r=0;r<16;++r)o[d_][r]*=wsf[crow(r,hi)]; } }while(0)
;   #define ROT() do{sl_prev=sl_cur;sl_cur=sl_next;sl_next=(sl_next==(NSLOT-1)*SLOTB)?0:sl_next+SLOTB;}while(0)
; template<int THRL> __device__ __forceinline__ void attn_unit(const bf16*Qblk,const bf16*__restrict__ Kh,const bf16*__restrict__ Vh,bf16*Oblk,const int po,const int NT,char*shm){
;     ...
;   for(;t+5<NT;t+=2){
;     STEP(pB0,pB1,pA0,pA1,t,true,true,true);     WAIT_BAR(2); RESC(); ROT();
;     STEP(pA0,pA1,pB0,pB1,t+1,true,true,true);   WAIT_BAR(2); RESC(); ROT();
;   }
.LBB0_688:
	s_add_i32 s6, s24, 0x2000
	s_cmpk_lg_i32 s24, 0x4000
	s_cselect_b32 s25, s6, 0
	s_add_i32 s22, s22, 2
	s_add_u32 s66, s66, 0x90000
	s_addc_u32 s67, s67, 0
	s_add_u32 s100, s100, 0x90000
	s_addc_u32 s101, s101, 0
	s_cmpk_gt_u32 s22, 0xfc
	s_cbranch_scc1 .LBB0_696
	s_mov_b32 s6, s23
	s_mov_b32 s26, s24
	s_mov_b32 s23, s25
	s_branch .LBB0_682

; #define PG8_STAGE(bufoff, gbase, voff) do { _Pragma("unroll") for (int _i = 0; _i < 2; ++_i) \
;         __builtin_amdgcn_global_load_lds((const unsigned*)((const char*)(gbase) + (voff)[_i]), (PG8_LAS unsigned*)(lds + (bufoff) + ldsw + _i * 8192), 16, 0, 0); } while (0)
; #define PG8_LDA(dst, b, h) do { _Pragma("unroll") for (int m = 0; m < 4; ++m) _Pragma("unroll") for (int k = 0; k < 2; ++k) dst[m][k] = *(const PG8_LAS bf16x8*)(lds + PG8_SA(b, h) + aoff + m * 2048 + k * 1024); } while (0)
; #define PG8_LDB(dst, b, h) do { _Pragma("unroll") for (int n = 0; n < 2; ++n) _Pragma("unroll") for (int k = 0; k < 2; ++k) dst[n][k] = *(const PG8_LAS bf16x8*)(lds + PG8_SB(b, h) + boff + n * 2048 + k * 1024); } while (0)
; #define PG8_MMA(ai, bj, At, Bt) do { __builtin_amdgcn_s_setprio(1); _Pragma("unroll") for (int m = 0; m < 4; ++m) _Pragma("unroll") for (int n = 0; n < 2; ++n) _Pragma("unroll") for (int k = 0; k < 2; ++k) \
;         acc[ai][bj][m][n] = __builtin_amdgcn_mfma_f32_16x16x32_bf16(Bt[n][k], At[m][k], acc[ai][bj][m][n], 0, 0, 0); __builtin_amdgcn_s_setprio(0); } while (0)
; #define PG8_WAIT_V(n) asm volatile("s_waitcnt vmcnt(" #n ")" ::: "memory")
; #define PG8_WAIT_L(n) asm volatile("s_waitcnt lgkmcnt(" #n ")" ::: "memory")
; #define PG8_BAR __builtin_amdgcn_s_barrier()
; #define PG8_SCHED __builtin_amdgcn_sched_barrier(0)
; template <class Epi, class Sched, bool ALIGN_EPI = false, bool SP2 = false>
; __device__ __forceinline__ void gemm_phase(PG8_LAS unsigned char* lds, const Gemm g, const Sched& S, const Epi& E) {
;     ...
;             const bool last = (t == nt - 2);
;             const char* a1 = cA + (size_t)(t + 1) * kstep;
;             const char* a2 = last ? nA : cA + (size_t)(t + 2) * kstep; const char* b2 = last ? nB : cB + (size_t)(t + 2) * kstep;
;             const char* a3 = a2 + kstep; const char* b3 = b2 + kstep;
;             if (last && has_next) S.a_ready(nxt);
;             if constexpr (SP2) {
;             PG8_LDB(B0, 0, 0); PG8_LDB(B1, 0, 1); PG8_SCHED; PG8_LDA(At, 0, 0); PG8_STAGE(PG8_SA(1, 1), a1 + hstep, voffA);
;             PG8_WAIT_V(8); PG8_WAIT_L(0); PG8_BAR; PG8_MMA(0, 0, At, B0); PG8_MMA(0, 1, At, B1); PG8_BAR; PG8_SCHED;
;             PG8_LDA(At, 0, 1); PG8_STAGE(PG8_SB(0, 0), b2, voffB); PG8_STAGE(PG8_SB(0, 1), b2 + hstep, voffB); PG8_STAGE(PG8_SA(0, 0), a2, voffA);
.LBB0_814:
	s_add_u32 s24, s48, 0x100
	s_addc_u32 s25, s49, 0
	s_add_i32 s41, 0, 0x10000
	s_cmp_eq_u32 s40, 12
	s_cselect_b32 s29, s1, s25
	s_cselect_b32 s28, s17, s24
	s_cselect_b32 s27, s11, s39
	s_cselect_b32 s26, s31, s38
	s_add_i32 s54, 0, 0x14000
	v_add_u32_e32 v142, s41, v188
	v_add_u32_e32 v158, s54, v188
	ds_read_b128 v[126:129], v142
	ds_read_b128 v[130:133], v142 offset:1024
	ds_read_b128 v[134:137], v142 offset:2048
	ds_read_b128 v[142:145], v142 offset:3072
	ds_read_b128 v[146:149], v158
	ds_read_b128 v[150:153], v158 offset:1024
	ds_read_b128 v[154:157], v158 offset:2048
	ds_read_b128 v[158:161], v158 offset:3072
	s_add_i32 m0, s45, 0xc000
	ds_read_b128 v[184:187], v190
	ds_read_b128 v[192:195], v190 offset:1024
	ds_read_b128 v[196:199], v190 offset:2048
	ds_read_b128 v[200:203], v190 offset:3072
	ds_read_b128 v[210:213], v190 offset:4096
	ds_read_b128 v[214:217], v190 offset:5120
	ds_read_b128 v[230:233], v190 offset:6144
	ds_read_b128 v[234:237], v190 offset:7168
	global_load_lds_dwordx4 v180, s[48:49]
	s_add_i32 m0, s45, 0xe000
	s_nop 0
	global_load_lds_dwordx4 v182, s[48:49]
	s_waitcnt vmcnt(8)
	s_waitcnt lgkmcnt(0)
	s_barrier
	s_setprio 1
	s_waitcnt lgkmcnt(0)
	v_mfma_f32_16x16x32_bf16 v[138:141], v[126:129], v[184:187], v[138:141]
	v_mfma_f32_16x16x32_bf16 v[122:125], v[134:137], v[184:187], v[122:125]
	v_mfma_f32_16x16x32_bf16 v[110:113], v[126:129], v[196:199], v[110:113]
	v_mfma_f32_16x16x32_bf16 v[106:109], v[134:137], v[196:199], v[106:109]
	v_mfma_f32_16x16x32_bf16 v[94:97], v[126:129], v[210:213], v[94:97]
	v_mfma_f32_16x16x32_bf16 v[90:93], v[134:137], v[210:213], v[90:93]
	v_mfma_f32_16x16x32_bf16 v[78:81], v[126:129], v[230:233], v[78:81]
	v_mfma_f32_16x16x32_bf16 v[74:77], v[134:137], v[230:233], v[74:77]
	v_mfma_f32_16x16x32_bf16 v[138:141], v[130:133], v[192:195], v[138:141]
	v_mfma_f32_16x16x32_bf16 v[122:125], v[142:145], v[192:195], v[122:125]
	v_mfma_f32_16x16x32_bf16 v[110:113], v[130:133], v[200:203], v[110:113]
	v_mfma_f32_16x16x32_bf16 v[106:109], v[142:145], v[200:203], v[106:109]
	v_mfma_f32_16x16x32_bf16 v[94:97], v[130:133], v[214:217], v[94:97]
	v_mfma_f32_16x16x32_bf16 v[90:93], v[142:145], v[214:217], v[90:93]
	v_mfma_f32_16x16x32_bf16 v[78:81], v[130:133], v[234:237], v[78:81]
	v_mfma_f32_16x16x32_bf16 v[74:77], v[142:145], v[234:237], v[74:77]
	s_setprio 0
	s_setprio 1
	v_mfma_f32_16x16x32_bf16 v[118:121], v[146:149], v[184:187], v[118:121]
	v_mfma_f32_16x16x32_bf16 v[114:117], v[154:157], v[184:187], v[114:117]
	v_mfma_f32_16x16x32_bf16 v[102:105], v[146:149], v[196:199], v[102:105]
	v_mfma_f32_16x16x32_bf16 v[98:101], v[154:157], v[196:199], v[98:101]
	v_mfma_f32_16x16x32_bf16 v[86:89], v[146:149], v[210:213], v[86:89]
	v_mfma_f32_16x16x32_bf16 v[82:85], v[154:157], v[210:213], v[82:85]
	v_mfma_f32_16x16x32_bf16 v[70:73], v[146:149], v[230:233], v[70:73]
	v_mfma_f32_16x16x32_bf16 v[66:69], v[154:157], v[230:233], v[66:69]
	v_mfma_f32_16x16x32_bf16 v[118:121], v[150:153], v[192:195], v[118:121]
	v_mfma_f32_16x16x32_bf16 v[114:117], v[158:161], v[192:195], v[114:117]
	v_mfma_f32_16x16x32_bf16 v[102:105], v[150:153], v[200:203], v[102:105]
	v_mfma_f32_16x16x32_bf16 v[98:101], v[158:161], v[200:203], v[98:101]
	v_mfma_f32_16x16x32_bf16 v[86:89], v[150:153], v[214:217], v[86:89]
	v_mfma_f32_16x16x32_bf16 v[82:85], v[158:161], v[214:217], v[82:85]
	v_mfma_f32_16x16x32_bf16 v[70:73], v[150:153], v[234:237], v[70:73]
	v_mfma_f32_16x16x32_bf16 v[66:69], v[158:161], v[234:237], v[66:69]
	s_setprio 0
	s_barrier
	s_add_i32 s22, s41, s43
	v_lshl_add_u64 v[204:205], s[26:27], 0, v[0:1]
	s_mov_b32 m0, s22
	ds_read_b128 v[184:187], v190 offset:16384
	ds_read_b128 v[192:195], v190 offset:17408
	ds_read_b128 v[196:199], v190 offset:18432
	ds_read_b128 v[200:203], v190 offset:19456
	ds_read_b128 v[210:213], v190 offset:20480
	ds_read_b128 v[214:217], v190 offset:21504
	ds_read_b128 v[230:233], v190 offset:22528
	ds_read_b128 v[234:237], v190 offset:23552
	global_load_lds_dwordx4 v[204:205], off
	s_add_i32 m0, s22, 0x2000
	s_add_u32 s22, s26, 0x40000
	v_lshl_add_u64 v[206:207], s[26:27], 0, v[162:163]
	s_addc_u32 s23, s27, 0
	s_add_i32 s41, s54, s43
	global_load_lds_dwordx4 v[206:207], off
	s_mov_b32 m0, s41
	v_lshl_add_u64 v[222:223], s[28:29], 0, v[162:163]
	global_load_lds_dwordx4 v0, s[22:23]
	s_add_i32 m0, s41, 0x2000
	s_nop 0
	global_load_lds_dwordx4 v162, s[22:23]
	v_lshl_add_u64 v[218:219], s[28:29], 0, v[0:1]
	s_mov_b32 m0, s45
	s_nop 0
	global_load_lds_dwordx4 v[218:219], off
	s_mov_b32 m0, s46
	s_nop 0
	global_load_lds_dwordx4 v[222:223], off
	s_waitcnt vmcnt(8)
	s_waitcnt lgkmcnt(0)
	s_barrier
; #define PG8_STAGE(bufoff, gbase, voff) do { _Pragma("unroll") for (int _i = 0; _i < 2; ++_i) \
;         __builtin_amdgcn_global_load_lds((const unsigned*)((const char*)(gbase) + (voff)[_i]), (PG8_LAS unsigned*)(lds + (bufoff) + ldsw + _i * 8192), 16, 0, 0); } while (0)
; #define PG8_LDA(dst, b, h) do { _Pragma("unroll") for (int m = 0; m < 4; ++m) _Pragma("unroll") for (int k = 0; k < 2; ++k) dst[m][k] = *(const PG8_LAS bf16x8*)(lds + PG8_SA(b, h) + aoff + m * 2048 + k * 1024); } while (0)
; #define PG8_LDB(dst, b, h) do { _Pragma("unroll") for (int n = 0; n < 2; ++n) _Pragma("unroll") for (int k = 0; k < 2; ++k) dst[n][k] = *(const PG8_LAS bf16x8*)(lds + PG8_SB(b, h) + boff + n * 2048 + k * 1024); } while (0)
; #define PG8_MMA(ai, bj, At, Bt) do { __builtin_amdgcn_s_setprio(1); _Pragma("unroll") for (int m = 0; m < 4; ++m) _Pragma("unroll") for (int n = 0; n < 2; ++n) _Pragma("unroll") for (int k = 0; k < 2; ++k) \
;         acc[ai][bj][m][n] = __builtin_amdgcn_mfma_f32_16x16x32_bf16(Bt[n][k], At[m][k], acc[ai][bj][m][n], 0, 0, 0); __builtin_amdgcn_s_setprio(0); } while (0)
; #define PG8_WAIT_V(n) asm volatile("s_waitcnt vmcnt(" #n ")" ::: "memory")
; #define PG8_WAIT_L(n) asm volatile("s_waitcnt lgkmcnt(" #n ")" ::: "memory")
; #define PG8_BAR __builtin_amdgcn_s_barrier()
; #define PG8_SCHED __builtin_amdgcn_sched_barrier(0)
; template <class Epi, class Sched, bool ALIGN_EPI = false, bool SP2 = false>
; __device__ __forceinline__ void gemm_phase(PG8_LAS unsigned char* lds, const Gemm g, const Sched& S, const Epi& E) {
;     ...
;             PG8_WAIT_V(8); PG8_WAIT_L(0); PG8_BAR; PG8_MMA(1, 0, At, B0); PG8_MMA(1, 1, At, B1); PG8_BAR; PG8_SCHED;
;             PG8_LDB(B0, 1, 0); PG8_LDB(B1, 1, 1); PG8_SCHED; PG8_LDA(At, 1, 0); PG8_STAGE(PG8_SA(0, 1), a2 + hstep, voffA);
;             PG8_WAIT_V(8); PG8_WAIT_L(0); PG8_BAR; PG8_MMA(0, 0, At, B0); PG8_MMA(0, 1, At, B1); PG8_BAR; PG8_SCHED;
	s_setprio 1
	s_waitcnt lgkmcnt(0)
	v_mfma_f32_16x16x32_bf16 v[62:65], v[126:129], v[184:187], v[62:65]
	v_mfma_f32_16x16x32_bf16 v[58:61], v[134:137], v[184:187], v[58:61]
	v_mfma_f32_16x16x32_bf16 v[46:49], v[126:129], v[196:199], v[46:49]
	v_mfma_f32_16x16x32_bf16 v[42:45], v[134:137], v[196:199], v[42:45]
	v_mfma_f32_16x16x32_bf16 v[30:33], v[126:129], v[210:213], v[30:33]
	v_mfma_f32_16x16x32_bf16 v[26:29], v[134:137], v[210:213], v[26:29]
	v_mfma_f32_16x16x32_bf16 v[14:17], v[126:129], v[230:233], v[14:17]
	v_mfma_f32_16x16x32_bf16 v[10:13], v[134:137], v[230:233], v[10:13]
	v_mfma_f32_16x16x32_bf16 v[62:65], v[130:133], v[192:195], v[62:65]
	v_mfma_f32_16x16x32_bf16 v[58:61], v[142:145], v[192:195], v[58:61]
	v_mfma_f32_16x16x32_bf16 v[46:49], v[130:133], v[200:203], v[46:49]
	v_mfma_f32_16x16x32_bf16 v[42:45], v[142:145], v[200:203], v[42:45]
	v_mfma_f32_16x16x32_bf16 v[30:33], v[130:133], v[214:217], v[30:33]
	v_mfma_f32_16x16x32_bf16 v[26:29], v[142:145], v[214:217], v[26:29]
	v_mfma_f32_16x16x32_bf16 v[14:17], v[130:133], v[234:237], v[14:17]
	v_mfma_f32_16x16x32_bf16 v[10:13], v[142:145], v[234:237], v[10:13]
	s_setprio 0
	s_setprio 1
	v_mfma_f32_16x16x32_bf16 v[54:57], v[146:149], v[184:187], v[54:57]
	v_mfma_f32_16x16x32_bf16 v[50:53], v[154:157], v[184:187], v[50:53]
	v_mfma_f32_16x16x32_bf16 v[38:41], v[146:149], v[196:199], v[38:41]
	v_mfma_f32_16x16x32_bf16 v[34:37], v[154:157], v[196:199], v[34:37]
	v_mfma_f32_16x16x32_bf16 v[22:25], v[146:149], v[210:213], v[22:25]
	v_mfma_f32_16x16x32_bf16 v[18:21], v[154:157], v[210:213], v[18:21]
	v_mfma_f32_16x16x32_bf16 v[6:9], v[146:149], v[230:233], v[6:9]
	v_mfma_f32_16x16x32_bf16 v[2:5], v[154:157], v[230:233], v[2:5]
	v_mfma_f32_16x16x32_bf16 v[54:57], v[150:153], v[192:195], v[54:57]
	v_mfma_f32_16x16x32_bf16 v[50:53], v[158:161], v[192:195], v[50:53]
	v_mfma_f32_16x16x32_bf16 v[38:41], v[150:153], v[200:203], v[38:41]
	v_mfma_f32_16x16x32_bf16 v[34:37], v[158:161], v[200:203], v[34:37]
	v_mfma_f32_16x16x32_bf16 v[22:25], v[150:153], v[214:217], v[22:25]
	v_mfma_f32_16x16x32_bf16 v[18:21], v[158:161], v[214:217], v[18:21]
	v_mfma_f32_16x16x32_bf16 v[6:9], v[150:153], v[234:237], v[6:9]
	v_mfma_f32_16x16x32_bf16 v[2:5], v[158:161], v[234:237], v[2:5]
	s_setprio 0
	s_barrier
	s_add_i32 s41, 0, 0x18000
	s_add_i32 s54, 0, 0x1c000
	v_add_u32_e32 v142, s41, v188
	v_add_u32_e32 v158, s54, v188
	ds_read_b128 v[126:129], v142
	ds_read_b128 v[130:133], v142 offset:1024
	ds_read_b128 v[134:137], v142 offset:2048
	ds_read_b128 v[142:145], v142 offset:3072
	ds_read_b128 v[146:149], v158
	ds_read_b128 v[150:153], v158 offset:1024
	ds_read_b128 v[154:157], v158 offset:2048
	ds_read_b128 v[158:161], v158 offset:3072
	s_add_u32 s22, s28, 0x40000
	s_addc_u32 s23, s29, 0
	s_mov_b32 m0, s47
	ds_read_b128 v[184:187], v190 offset:32768
	ds_read_b128 v[192:195], v190 offset:33792
	ds_read_b128 v[196:199], v190 offset:34816
	ds_read_b128 v[200:203], v190 offset:35840
	ds_read_b128 v[210:213], v190 offset:36864
	ds_read_b128 v[214:217], v190 offset:37888
	ds_read_b128 v[230:233], v190 offset:38912
	ds_read_b128 v[234:237], v190 offset:39936
	global_load_lds_dwordx4 v0, s[22:23]
	s_mov_b32 m0, s52
	s_nop 0
	global_load_lds_dwordx4 v162, s[22:23]
	s_waitcnt vmcnt(8)
	s_waitcnt lgkmcnt(0)
	s_barrier
	s_setprio 1
	s_waitcnt lgkmcnt(0)
	v_mfma_f32_16x16x32_bf16 v[138:141], v[126:129], v[184:187], v[138:141]
	v_mfma_f32_16x16x32_bf16 v[122:125], v[134:137], v[184:187], v[122:125]
	v_mfma_f32_16x16x32_bf16 v[110:113], v[126:129], v[196:199], v[110:113]
	v_mfma_f32_16x16x32_bf16 v[106:109], v[134:137], v[196:199], v[106:109]
	v_mfma_f32_16x16x32_bf16 v[94:97], v[126:129], v[210:213], v[94:97]
	v_mfma_f32_16x16x32_bf16 v[90:93], v[134:137], v[210:213], v[90:93]
	v_mfma_f32_16x16x32_bf16 v[78:81], v[126:129], v[230:233], v[78:81]
	v_mfma_f32_16x16x32_bf16 v[74:77], v[134:137], v[230:233], v[74:77]
	v_mfma_f32_16x16x32_bf16 v[138:141], v[130:133], v[192:195], v[138:141]
	v_mfma_f32_16x16x32_bf16 v[122:125], v[142:145], v[192:195], v[122:125]
	v_mfma_f32_16x16x32_bf16 v[110:113], v[130:133], v[200:203], v[110:113]
	v_mfma_f32_16x16x32_bf16 v[106:109], v[142:145], v[200:203], v[106:109]
	v_mfma_f32_16x16x32_bf16 v[94:97], v[130:133], v[214:217], v[94:97]
	v_mfma_f32_16x16x32_bf16 v[90:93], v[142:145], v[214:217], v[90:93]
	v_mfma_f32_16x16x32_bf16 v[78:81], v[130:133], v[234:237], v[78:81]
	v_mfma_f32_16x16x32_bf16 v[74:77], v[142:145], v[234:237], v[74:77]
	s_setprio 0
	s_setprio 1
	v_mfma_f32_16x16x32_bf16 v[118:121], v[146:149], v[184:187], v[118:121]
	v_mfma_f32_16x16x32_bf16 v[114:117], v[154:157], v[184:187], v[114:117]
	v_mfma_f32_16x16x32_bf16 v[102:105], v[146:149], v[196:199], v[102:105]
	v_mfma_f32_16x16x32_bf16 v[98:101], v[154:157], v[196:199], v[98:101]
	v_mfma_f32_16x16x32_bf16 v[86:89], v[146:149], v[210:213], v[86:89]
	v_mfma_f32_16x16x32_bf16 v[82:85], v[154:157], v[210:213], v[82:85]
	v_mfma_f32_16x16x32_bf16 v[70:73], v[146:149], v[230:233], v[70:73]
	v_mfma_f32_16x16x32_bf16 v[66:69], v[154:157], v[230:233], v[66:69]
	v_mfma_f32_16x16x32_bf16 v[118:121], v[150:153], v[192:195], v[118:121]
	v_mfma_f32_16x16x32_bf16 v[114:117], v[158:161], v[192:195], v[114:117]
	v_mfma_f32_16x16x32_bf16 v[102:105], v[150:153], v[200:203], v[102:105]
	v_mfma_f32_16x16x32_bf16 v[98:101], v[158:161], v[200:203], v[98:101]
	v_mfma_f32_16x16x32_bf16 v[86:89], v[150:153], v[214:217], v[86:89]
	v_mfma_f32_16x16x32_bf16 v[82:85], v[158:161], v[214:217], v[82:85]
	v_mfma_f32_16x16x32_bf16 v[70:73], v[150:153], v[234:237], v[70:73]
	v_mfma_f32_16x16x32_bf16 v[66:69], v[158:161], v[234:237], v[66:69]
	s_setprio 0
	s_barrier
; #define PG8_STAGE(bufoff, gbase, voff) do { _Pragma("unroll") for (int _i = 0; _i < 2; ++_i) \
;         __builtin_amdgcn_global_load_lds((const unsigned*)((const char*)(gbase) + (voff)[_i]), (PG8_LAS unsigned*)(lds + (bufoff) + ldsw + _i * 8192), 16, 0, 0); } while (0)
; #define PG8_LDA(dst, b, h) do { _Pragma("unroll") for (int m = 0; m < 4; ++m) _Pragma("unroll") for (int k = 0; k < 2; ++k) dst[m][k] = *(const PG8_LAS bf16x8*)(lds + PG8_SA(b, h) + aoff + m * 2048 + k * 1024); } while (0)
; #define PG8_MMA(ai, bj, At, Bt) do { __builtin_amdgcn_s_setprio(1); _Pragma("unroll") for (int m = 0; m < 4; ++m) _Pragma("unroll") for (int n = 0; n < 2; ++n) _Pragma("unroll") for (int k = 0; k < 2; ++k) \
;         acc[ai][bj][m][n] = __builtin_amdgcn_mfma_f32_16x16x32_bf16(Bt[n][k], At[m][k], acc[ai][bj][m][n], 0, 0, 0); __builtin_amdgcn_s_setprio(0); } while (0)
; #define PG8_WAIT_V(n) asm volatile("s_waitcnt vmcnt(" #n ")" ::: "memory")
; #define PG8_WAIT_L(n) asm volatile("s_waitcnt lgkmcnt(" #n ")" ::: "memory")
; #define PG8_BAR __builtin_amdgcn_s_barrier()
; #define PG8_SCHED __builtin_amdgcn_sched_barrier(0)
; template <class Epi, class Sched, bool ALIGN_EPI = false, bool SP2 = false>
; __device__ __forceinline__ void gemm_phase(PG8_LAS unsigned char* lds, const Gemm g, const Sched& S, const Epi& E) {
;     ...
;             PG8_LDA(At, 1, 1); PG8_STAGE(PG8_SB(1, 0), b3, voffB); PG8_STAGE(PG8_SB(1, 1), b3 + hstep, voffB); PG8_STAGE(PG8_SA(1, 0), a3, voffA);
;             PG8_WAIT_V(8); PG8_WAIT_L(0); PG8_BAR; PG8_MMA(1, 0, At, B0); PG8_MMA(1, 1, At, B1); PG8_BAR; PG8_SCHED;
	s_add_i32 s22, s41, s43
	v_lshl_add_u64 v[204:205], v[204:205], 0, s[60:61]
	s_mov_b32 m0, s22
	ds_read_b128 v[184:187], v190 offset:49152
	ds_read_b128 v[192:195], v190 offset:50176
	ds_read_b128 v[196:199], v190 offset:51200
	ds_read_b128 v[200:203], v190 offset:52224
	ds_read_b128 v[210:213], v190 offset:53248
	ds_read_b128 v[214:217], v190 offset:54272
	ds_read_b128 v[230:233], v190 offset:55296
	ds_read_b128 v[234:237], v190 offset:56320
	global_load_lds_dwordx4 v[204:205], off
	s_add_i32 m0, s22, 0x2000
	s_add_u32 s22, s26, 0x40080
	v_lshl_add_u64 v[204:205], v[206:207], 0, s[60:61]
	s_addc_u32 s23, s27, 0
	s_add_i32 s26, s54, s43
	global_load_lds_dwordx4 v[204:205], off
	s_mov_b32 m0, s26
	s_nop 0
	global_load_lds_dwordx4 v0, s[22:23]
	s_add_i32 m0, s26, 0x2000
	s_nop 0
	global_load_lds_dwordx4 v162, s[22:23]
	v_lshl_add_u64 v[204:205], v[218:219], 0, s[60:61]
	s_mov_b32 m0, s57
	s_nop 0
	global_load_lds_dwordx4 v[204:205], off
	v_lshl_add_u64 v[204:205], v[222:223], 0, s[60:61]
	s_mov_b32 m0, s74
	s_nop 0
	global_load_lds_dwordx4 v[204:205], off
	s_waitcnt vmcnt(8)
	s_waitcnt lgkmcnt(0)
	s_barrier
	s_setprio 1
	s_waitcnt lgkmcnt(0)
	v_mfma_f32_16x16x32_bf16 v[62:65], v[126:129], v[184:187], v[62:65]
	v_mfma_f32_16x16x32_bf16 v[58:61], v[134:137], v[184:187], v[58:61]
	v_mfma_f32_16x16x32_bf16 v[46:49], v[126:129], v[196:199], v[46:49]
	v_mfma_f32_16x16x32_bf16 v[42:45], v[134:137], v[196:199], v[42:45]
	v_mfma_f32_16x16x32_bf16 v[30:33], v[126:129], v[210:213], v[30:33]
	v_mfma_f32_16x16x32_bf16 v[26:29], v[134:137], v[210:213], v[26:29]
	v_mfma_f32_16x16x32_bf16 v[14:17], v[126:129], v[230:233], v[14:17]
	v_mfma_f32_16x16x32_bf16 v[10:13], v[134:137], v[230:233], v[10:13]
	v_mfma_f32_16x16x32_bf16 v[62:65], v[130:133], v[192:195], v[62:65]
	v_mfma_f32_16x16x32_bf16 v[58:61], v[142:145], v[192:195], v[58:61]
	v_mfma_f32_16x16x32_bf16 v[46:49], v[130:133], v[200:203], v[46:49]
	v_mfma_f32_16x16x32_bf16 v[42:45], v[142:145], v[200:203], v[42:45]
	v_mfma_f32_16x16x32_bf16 v[30:33], v[130:133], v[214:217], v[30:33]
	v_mfma_f32_16x16x32_bf16 v[26:29], v[142:145], v[214:217], v[26:29]
	v_mfma_f32_16x16x32_bf16 v[14:17], v[130:133], v[234:237], v[14:17]
	v_mfma_f32_16x16x32_bf16 v[10:13], v[142:145], v[234:237], v[10:13]
	s_setprio 0
	s_setprio 1
	v_mfma_f32_16x16x32_bf16 v[54:57], v[146:149], v[184:187], v[54:57]
	v_mfma_f32_16x16x32_bf16 v[50:53], v[154:157], v[184:187], v[50:53]
	v_mfma_f32_16x16x32_bf16 v[38:41], v[146:149], v[196:199], v[38:41]
	v_mfma_f32_16x16x32_bf16 v[34:37], v[154:157], v[196:199], v[34:37]
	v_mfma_f32_16x16x32_bf16 v[22:25], v[146:149], v[210:213], v[22:25]
	v_mfma_f32_16x16x32_bf16 v[18:21], v[154:157], v[210:213], v[18:21]
	v_mfma_f32_16x16x32_bf16 v[6:9], v[146:149], v[230:233], v[6:9]
	v_mfma_f32_16x16x32_bf16 v[2:5], v[154:157], v[230:233], v[2:5]
	v_mfma_f32_16x16x32_bf16 v[54:57], v[150:153], v[192:195], v[54:57]
	v_mfma_f32_16x16x32_bf16 v[50:53], v[158:161], v[192:195], v[50:53]
	v_mfma_f32_16x16x32_bf16 v[38:41], v[150:153], v[200:203], v[38:41]
	v_mfma_f32_16x16x32_bf16 v[34:37], v[158:161], v[200:203], v[34:37]
	v_mfma_f32_16x16x32_bf16 v[22:25], v[150:153], v[214:217], v[22:25]
	v_mfma_f32_16x16x32_bf16 v[18:21], v[158:161], v[214:217], v[18:21]
	v_mfma_f32_16x16x32_bf16 v[6:9], v[150:153], v[234:237], v[6:9]
	v_mfma_f32_16x16x32_bf16 v[2:5], v[158:161], v[234:237], v[2:5]
	s_setprio 0
	s_barrier
	s_add_i32 s40, s40, 2
	s_add_u32 s38, s38, 0x100
	s_addc_u32 s39, s39, 0
	s_cmp_gt_u32 s40, 13
	s_mov_b64 s[48:49], s[24:25]
	s_cbranch_scc0 .LBB0_814
	s_and_b64 vcc, exec, s[8:9]
	s_cbranch_vccz .LBB0_817
	s_barrier

; #define PG8_STAGE(bufoff, gbase, voff) do { _Pragma("unroll") for (int _i = 0; _i < 2; ++_i) \
;         __builtin_amdgcn_global_load_lds((const unsigned*)((const char*)(gbase) + (voff)[_i]), (PG8_LAS unsigned*)(lds + (bufoff) + ldsw + _i * 8192), 16, 0, 0); } while (0)
; #define PG8_LDA(dst, b, h) do { _Pragma("unroll") for (int m = 0; m < 4; ++m) _Pragma("unroll") for (int k = 0; k < 2; ++k) dst[m][k] = *(const PG8_LAS bf16x8*)(lds + PG8_SA(b, h) + aoff + m * 2048 + k * 1024); } while (0)
; #define PG8_LDB(dst, b, h) do { _Pragma("unroll") for (int n = 0; n < 2; ++n) _Pragma("unroll") for (int k = 0; k < 2; ++k) dst[n][k] = *(const PG8_LAS bf16x8*)(lds + PG8_SB(b, h) + boff + n * 2048 + k * 1024); } while (0)
; #define PG8_MMA(ai, bj, At, Bt) do { __builtin_amdgcn_s_setprio(1); _Pragma("unroll") for (int m = 0; m < 4; ++m) _Pragma("unroll") for (int n = 0; n < 2; ++n) _Pragma("unroll") for (int k = 0; k < 2; ++k) \
;         acc[ai][bj][m][n] = __builtin_amdgcn_mfma_f32_16x16x32_bf16(Bt[n][k], At[m][k], acc[ai][bj][m][n], 0, 0, 0); __builtin_amdgcn_s_setprio(0); } while (0)
; #define PG8_WAIT_V(n) asm volatile("s_waitcnt vmcnt(" #n ")" ::: "memory")
; #define PG8_WAIT_L(n) asm volatile("s_waitcnt lgkmcnt(" #n ")" ::: "memory")
; #define PG8_BAR __builtin_amdgcn_s_barrier()
; #define PG8_SCHED __builtin_amdgcn_sched_barrier(0)
; template <class Epi, class Sched, bool ALIGN_EPI = false, bool SP2 = false>
; __device__ __forceinline__ void gemm_phase(PG8_LAS unsigned char* lds, const Gemm g, const Sched& S, const Epi& E) {
;     ...
;             const bool last = (t == nt - 2);
;             const char* a1 = cA + (size_t)(t + 1) * kstep;
;             const char* a2 = last ? nA : cA + (size_t)(t + 2) * kstep; const char* b2 = last ? nB : cB + (size_t)(t + 2) * kstep;
;             const char* a3 = a2 + kstep; const char* b3 = b2 + kstep;
;             if (last && has_next) S.a_ready(nxt);
;             if constexpr (SP2) {
;             PG8_LDB(B0, 0, 0); PG8_LDB(B1, 0, 1); PG8_SCHED; PG8_LDA(At, 0, 0); PG8_STAGE(PG8_SA(1, 1), a1 + hstep, voffA);
;             PG8_WAIT_V(8); PG8_WAIT_L(0); PG8_BAR; PG8_MMA(0, 0, At, B0); PG8_MMA(0, 1, At, B1); PG8_BAR; PG8_SCHED;
;             PG8_LDA(At, 0, 1); PG8_STAGE(PG8_SB(0, 0), b2, voffB); PG8_STAGE(PG8_SB(0, 1), b2 + hstep, voffB); PG8_STAGE(PG8_SA(0, 0), a2, voffA);
.LBB0_993:
	s_add_u32 s54, vcc_lo, 0xfffc0080
	s_addc_u32 s55, vcc_hi, -1
	s_add_i32 s48, 0, 0x10000
	s_cmp_eq_u32 s89, 12
	s_cselect_b32 s97, s39, s55
	s_cselect_b32 s96, s47, s54
	v_add_u32_e32 v0, s48, v213
	s_cselect_b32 s75, s1, s88
	s_cselect_b32 s74, s31, s45
	s_add_i32 s49, 0, 0x14000
	ds_read_b128 v[66:69], v0
	ds_read_b128 v[70:73], v0 offset:1024
	ds_read_b128 v[74:77], v0 offset:2048
	ds_read_b128 v[78:81], v0 offset:3072
	v_add_u32_e32 v0, s49, v213
	ds_read_b128 v[82:85], v0
	ds_read_b128 v[86:89], v0 offset:1024
	ds_read_b128 v[90:93], v0 offset:2048
	ds_read_b128 v[94:97], v0 offset:3072
	v_lshl_add_u64 v[194:195], vcc, 0, v[214:215]
	s_add_i32 m0, s53, 0xc000
	ds_read_b128 v[106:109], v230
	ds_read_b128 v[110:113], v230 offset:1024
	ds_read_b128 v[114:117], v230 offset:2048
	ds_read_b128 v[118:121], v230 offset:3072
	ds_read_b128 v[130:133], v230 offset:4096
	ds_read_b128 v[134:137], v230 offset:5120
	ds_read_b128 v[138:141], v230 offset:6144
	ds_read_b128 v[142:145], v230 offset:7168
	global_load_lds_dwordx4 v[194:195], off
	v_lshl_add_u64 v[194:195], vcc, 0, v[216:217]
	s_add_i32 m0, s53, 0xe000
	s_nop 0
	global_load_lds_dwordx4 v[194:195], off
	s_waitcnt vmcnt(8)
	s_waitcnt lgkmcnt(0)
	s_barrier
	s_setprio 1
	s_waitcnt lgkmcnt(0)
	v_mfma_f32_16x16x32_bf16 v[190:193], v[66:69], v[106:109], v[190:193]
	v_mfma_f32_16x16x32_bf16 v[186:189], v[74:77], v[106:109], v[186:189]
	v_mfma_f32_16x16x32_bf16 v[174:177], v[66:69], v[114:117], v[174:177]
	v_mfma_f32_16x16x32_bf16 v[170:173], v[74:77], v[114:117], v[170:173]
	v_mfma_f32_16x16x32_bf16 v[158:161], v[66:69], v[130:133], v[158:161]
	v_mfma_f32_16x16x32_bf16 v[154:157], v[74:77], v[130:133], v[154:157]
	v_mfma_f32_16x16x32_bf16 v[126:129], v[66:69], v[138:141], v[126:129]
	v_mfma_f32_16x16x32_bf16 v[122:125], v[74:77], v[138:141], v[122:125]
	v_mfma_f32_16x16x32_bf16 v[190:193], v[70:73], v[110:113], v[190:193]
	v_mfma_f32_16x16x32_bf16 v[186:189], v[78:81], v[110:113], v[186:189]
	v_mfma_f32_16x16x32_bf16 v[174:177], v[70:73], v[118:121], v[174:177]
	v_mfma_f32_16x16x32_bf16 v[170:173], v[78:81], v[118:121], v[170:173]
	v_mfma_f32_16x16x32_bf16 v[158:161], v[70:73], v[134:137], v[158:161]
	v_mfma_f32_16x16x32_bf16 v[154:157], v[78:81], v[134:137], v[154:157]
	v_mfma_f32_16x16x32_bf16 v[126:129], v[70:73], v[142:145], v[126:129]
	v_mfma_f32_16x16x32_bf16 v[122:125], v[78:81], v[142:145], v[122:125]
	s_setprio 0
	s_setprio 1
	v_mfma_f32_16x16x32_bf16 v[182:185], v[82:85], v[106:109], v[182:185]
	v_mfma_f32_16x16x32_bf16 v[106:109], v[90:93], v[106:109], v[178:181]
	v_mfma_f32_16x16x32_bf16 v[182:185], v[86:89], v[110:113], v[182:185]
	v_mfma_f32_16x16x32_bf16 v[106:109], v[94:97], v[110:113], v[106:109]
	v_mfma_f32_16x16x32_bf16 v[110:113], v[82:85], v[114:117], v[166:169]
	v_mfma_f32_16x16x32_bf16 v[114:117], v[90:93], v[114:117], v[162:165]
	v_mfma_f32_16x16x32_bf16 v[102:105], v[82:85], v[138:141], v[102:105]
	v_mfma_f32_16x16x32_bf16 v[98:101], v[90:93], v[138:141], v[98:101]
	v_mfma_f32_16x16x32_bf16 v[110:113], v[86:89], v[118:121], v[110:113]
	v_mfma_f32_16x16x32_bf16 v[114:117], v[94:97], v[118:121], v[114:117]
	v_mfma_f32_16x16x32_bf16 v[118:121], v[82:85], v[130:133], v[150:153]
	v_mfma_f32_16x16x32_bf16 v[130:133], v[90:93], v[130:133], v[146:149]
	v_mfma_f32_16x16x32_bf16 v[102:105], v[86:89], v[142:145], v[102:105]
	v_mfma_f32_16x16x32_bf16 v[98:101], v[94:97], v[142:145], v[98:101]
	v_mfma_f32_16x16x32_bf16 v[118:121], v[86:89], v[134:137], v[118:121]
	v_mfma_f32_16x16x32_bf16 v[130:133], v[94:97], v[134:137], v[130:133]
	s_setprio 0
	s_barrier
	s_add_i32 s48, s48, s35
	v_lshl_add_u64 v[206:207], s[74:75], 0, v[200:201]
	s_mov_b32 m0, s48
	ds_read_b128 v[134:137], v230 offset:16384
	ds_read_b128 v[138:141], v230 offset:17408
	ds_read_b128 v[142:145], v230 offset:18432
	ds_read_b128 v[146:149], v230 offset:19456
	ds_read_b128 v[150:153], v230 offset:20480
	ds_read_b128 v[162:165], v230 offset:21504
	ds_read_b128 v[166:169], v230 offset:22528
	ds_read_b128 v[178:181], v230 offset:23552
	global_load_lds_dwordx4 v[206:207], off
	s_add_i32 m0, s48, 0x2000
	s_add_u32 s54, s74, 0x40000
	v_lshl_add_u64 v[218:219], s[74:75], 0, v[204:205]
	s_addc_u32 s55, s75, 0
	s_add_i32 s48, s49, s35
	global_load_lds_dwordx4 v[218:219], off
	s_mov_b32 m0, s48
	v_lshl_add_u64 v[240:241], s[96:97], 0, v[198:199]
	global_load_lds_dwordx4 v200, s[54:55]
	s_add_i32 m0, s48, 0x2000
	v_lshl_add_u64 v[242:243], s[96:97], 0, v[202:203]
	global_load_lds_dwordx4 v204, s[54:55]
	s_mov_b32 m0, s53
	s_nop 0
	global_load_lds_dwordx4 v[240:241], off
	s_mov_b32 m0, s80
	s_nop 0
	global_load_lds_dwordx4 v[242:243], off
	s_waitcnt vmcnt(8)
	s_waitcnt lgkmcnt(0)
	s_barrier
; #define PG8_STAGE(bufoff, gbase, voff) do { _Pragma("unroll") for (int _i = 0; _i < 2; ++_i) \
;         __builtin_amdgcn_global_load_lds((const unsigned*)((const char*)(gbase) + (voff)[_i]), (PG8_LAS unsigned*)(lds + (bufoff) + ldsw + _i * 8192), 16, 0, 0); } while (0)
; #define PG8_LDA(dst, b, h) do { _Pragma("unroll") for (int m = 0; m < 4; ++m) _Pragma("unroll") for (int k = 0; k < 2; ++k) dst[m][k] = *(const PG8_LAS bf16x8*)(lds + PG8_SA(b, h) + aoff + m * 2048 + k * 1024); } while (0)
; #define PG8_LDB(dst, b, h) do { _Pragma("unroll") for (int n = 0; n < 2; ++n) _Pragma("unroll") for (int k = 0; k < 2; ++k) dst[n][k] = *(const PG8_LAS bf16x8*)(lds + PG8_SB(b, h) + boff + n * 2048 + k * 1024); } while (0)
; #define PG8_MMA(ai, bj, At, Bt) do { __builtin_amdgcn_s_setprio(1); _Pragma("unroll") for (int m = 0; m < 4; ++m) _Pragma("unroll") for (int n = 0; n < 2; ++n) _Pragma("unroll") for (int k = 0; k < 2; ++k) \
;         acc[ai][bj][m][n] = __builtin_amdgcn_mfma_f32_16x16x32_bf16(Bt[n][k], At[m][k], acc[ai][bj][m][n], 0, 0, 0); __builtin_amdgcn_s_setprio(0); } while (0)
; #define PG8_WAIT_V(n) asm volatile("s_waitcnt vmcnt(" #n ")" ::: "memory")
; #define PG8_WAIT_L(n) asm volatile("s_waitcnt lgkmcnt(" #n ")" ::: "memory")
; #define PG8_BAR __builtin_amdgcn_s_barrier()
; #define PG8_SCHED __builtin_amdgcn_sched_barrier(0)
; template <class Epi, class Sched, bool ALIGN_EPI = false, bool SP2 = false>
; __device__ __forceinline__ void gemm_phase(PG8_LAS unsigned char* lds, const Gemm g, const Sched& S, const Epi& E) {
;     ...
;             PG8_WAIT_V(8); PG8_WAIT_L(0); PG8_BAR; PG8_MMA(1, 0, At, B0); PG8_MMA(1, 1, At, B1); PG8_BAR; PG8_SCHED;
;             PG8_LDB(B0, 1, 0); PG8_LDB(B1, 1, 1); PG8_SCHED; PG8_LDA(At, 1, 0); PG8_STAGE(PG8_SA(0, 1), a2 + hstep, voffA);
;             PG8_WAIT_V(8); PG8_WAIT_L(0); PG8_BAR; PG8_MMA(0, 0, At, B0); PG8_MMA(0, 1, At, B1); PG8_BAR; PG8_SCHED;
	s_setprio 1
	s_waitcnt lgkmcnt(0)
	v_mfma_f32_16x16x32_bf16 v[62:65], v[66:69], v[134:137], v[62:65]
	v_mfma_f32_16x16x32_bf16 v[58:61], v[74:77], v[134:137], v[58:61]
	v_mfma_f32_16x16x32_bf16 v[46:49], v[66:69], v[142:145], v[46:49]
	v_mfma_f32_16x16x32_bf16 v[42:45], v[74:77], v[142:145], v[42:45]
	v_mfma_f32_16x16x32_bf16 v[30:33], v[66:69], v[150:153], v[30:33]
	v_mfma_f32_16x16x32_bf16 v[26:29], v[74:77], v[150:153], v[26:29]
	v_mfma_f32_16x16x32_bf16 v[14:17], v[66:69], v[166:169], v[14:17]
	v_mfma_f32_16x16x32_bf16 v[10:13], v[74:77], v[166:169], v[10:13]
	v_mfma_f32_16x16x32_bf16 v[62:65], v[70:73], v[138:141], v[62:65]
	v_mfma_f32_16x16x32_bf16 v[58:61], v[78:81], v[138:141], v[58:61]
	v_mfma_f32_16x16x32_bf16 v[46:49], v[70:73], v[146:149], v[46:49]
	v_mfma_f32_16x16x32_bf16 v[42:45], v[78:81], v[146:149], v[42:45]
	v_mfma_f32_16x16x32_bf16 v[30:33], v[70:73], v[162:165], v[30:33]
	v_mfma_f32_16x16x32_bf16 v[26:29], v[78:81], v[162:165], v[26:29]
	v_mfma_f32_16x16x32_bf16 v[14:17], v[70:73], v[178:181], v[14:17]
	v_mfma_f32_16x16x32_bf16 v[10:13], v[78:81], v[178:181], v[10:13]
	s_setprio 0
	s_setprio 1
	v_mfma_f32_16x16x32_bf16 v[54:57], v[82:85], v[134:137], v[54:57]
	v_mfma_f32_16x16x32_bf16 v[50:53], v[90:93], v[134:137], v[50:53]
	v_mfma_f32_16x16x32_bf16 v[38:41], v[82:85], v[142:145], v[38:41]
	v_mfma_f32_16x16x32_bf16 v[34:37], v[90:93], v[142:145], v[34:37]
	v_mfma_f32_16x16x32_bf16 v[22:25], v[82:85], v[150:153], v[22:25]
	v_mfma_f32_16x16x32_bf16 v[18:21], v[90:93], v[150:153], v[18:21]
	v_mfma_f32_16x16x32_bf16 v[6:9], v[82:85], v[166:169], v[6:9]
	v_mfma_f32_16x16x32_bf16 v[2:5], v[90:93], v[166:169], v[2:5]
	v_mfma_f32_16x16x32_bf16 v[54:57], v[86:89], v[138:141], v[54:57]
	v_mfma_f32_16x16x32_bf16 v[50:53], v[94:97], v[138:141], v[50:53]
	v_mfma_f32_16x16x32_bf16 v[38:41], v[86:89], v[146:149], v[38:41]
	v_mfma_f32_16x16x32_bf16 v[34:37], v[94:97], v[146:149], v[34:37]
	v_mfma_f32_16x16x32_bf16 v[22:25], v[86:89], v[162:165], v[22:25]
	v_mfma_f32_16x16x32_bf16 v[18:21], v[94:97], v[162:165], v[18:21]
	v_mfma_f32_16x16x32_bf16 v[6:9], v[86:89], v[178:181], v[6:9]
	v_mfma_f32_16x16x32_bf16 v[2:5], v[94:97], v[178:181], v[2:5]
	s_setprio 0
	s_barrier
	s_add_i32 s48, 0, 0x18000
	v_add_u32_e32 v0, s48, v213
	s_add_i32 s49, 0, 0x1c000
	ds_read_b128 v[66:69], v0
	ds_read_b128 v[70:73], v0 offset:1024
	ds_read_b128 v[74:77], v0 offset:2048
	ds_read_b128 v[78:81], v0 offset:3072
	v_add_u32_e32 v0, s49, v213
	ds_read_b128 v[82:85], v0
	ds_read_b128 v[86:89], v0 offset:1024
	ds_read_b128 v[90:93], v0 offset:2048
	ds_read_b128 v[94:97], v0 offset:3072
	s_add_u32 s54, s96, 0x40000
	s_addc_u32 s55, s97, 0
	s_mov_b32 m0, s81
	ds_read_b128 v[134:137], v230 offset:32768
	ds_read_b128 v[138:141], v230 offset:33792
	ds_read_b128 v[142:145], v230 offset:34816
	ds_read_b128 v[146:149], v230 offset:35840
	ds_read_b128 v[194:197], v230 offset:36864
	ds_read_b128 v[222:225], v230 offset:37888
	ds_read_b128 v[232:235], v230 offset:38912
	ds_read_b128 v[236:239], v230 offset:39936
	global_load_lds_dwordx4 v198, s[54:55]
	s_mov_b32 m0, s82
	s_nop 0
	global_load_lds_dwordx4 v202, s[54:55]
	s_waitcnt vmcnt(8)
	s_waitcnt lgkmcnt(0)
	s_barrier
	s_setprio 1
	s_waitcnt lgkmcnt(0)
	v_mfma_f32_16x16x32_bf16 v[150:153], v[66:69], v[134:137], v[190:193]
	v_mfma_f32_16x16x32_bf16 v[190:193], v[70:73], v[138:141], v[150:153]
	v_mfma_f32_16x16x32_bf16 v[150:153], v[74:77], v[134:137], v[186:189]
	v_mfma_f32_16x16x32_bf16 v[186:189], v[78:81], v[138:141], v[150:153]
	v_mfma_f32_16x16x32_bf16 v[150:153], v[66:69], v[142:145], v[174:177]
	v_mfma_f32_16x16x32_bf16 v[174:177], v[70:73], v[146:149], v[150:153]
	v_mfma_f32_16x16x32_bf16 v[150:153], v[74:77], v[142:145], v[170:173]
	v_mfma_f32_16x16x32_bf16 v[170:173], v[78:81], v[146:149], v[150:153]
	v_mfma_f32_16x16x32_bf16 v[150:153], v[66:69], v[194:197], v[158:161]
	v_mfma_f32_16x16x32_bf16 v[158:161], v[70:73], v[222:225], v[150:153]
	v_mfma_f32_16x16x32_bf16 v[150:153], v[74:77], v[194:197], v[154:157]
	v_mfma_f32_16x16x32_bf16 v[126:129], v[66:69], v[232:235], v[126:129]
	v_mfma_f32_16x16x32_bf16 v[122:125], v[74:77], v[232:235], v[122:125]
	v_mfma_f32_16x16x32_bf16 v[154:157], v[78:81], v[222:225], v[150:153]
	v_mfma_f32_16x16x32_bf16 v[126:129], v[70:73], v[236:239], v[126:129]
	v_mfma_f32_16x16x32_bf16 v[122:125], v[78:81], v[236:239], v[122:125]
	s_setprio 0
	s_setprio 1
	v_mfma_f32_16x16x32_bf16 v[106:109], v[90:93], v[134:137], v[106:109]
	v_mfma_f32_16x16x32_bf16 v[178:181], v[94:97], v[138:141], v[106:109]
	v_mfma_f32_16x16x32_bf16 v[106:109], v[82:85], v[142:145], v[110:113]
	v_mfma_f32_16x16x32_bf16 v[166:169], v[86:89], v[146:149], v[106:109]
	v_mfma_f32_16x16x32_bf16 v[106:109], v[90:93], v[142:145], v[114:117]
	v_mfma_f32_16x16x32_bf16 v[150:153], v[82:85], v[134:137], v[182:185]
	v_mfma_f32_16x16x32_bf16 v[162:165], v[94:97], v[146:149], v[106:109]
	v_mfma_f32_16x16x32_bf16 v[106:109], v[82:85], v[194:197], v[118:121]
	v_mfma_f32_16x16x32_bf16 v[182:185], v[86:89], v[138:141], v[150:153]
	v_mfma_f32_16x16x32_bf16 v[150:153], v[86:89], v[222:225], v[106:109]
	v_mfma_f32_16x16x32_bf16 v[106:109], v[90:93], v[194:197], v[130:133]
	v_mfma_f32_16x16x32_bf16 v[102:105], v[82:85], v[232:235], v[102:105]
	v_mfma_f32_16x16x32_bf16 v[98:101], v[90:93], v[232:235], v[98:101]
	v_mfma_f32_16x16x32_bf16 v[146:149], v[94:97], v[222:225], v[106:109]
	v_mfma_f32_16x16x32_bf16 v[102:105], v[86:89], v[236:239], v[102:105]
	v_mfma_f32_16x16x32_bf16 v[98:101], v[94:97], v[236:239], v[98:101]
	s_setprio 0
	s_barrier
; #define PG8_STAGE(bufoff, gbase, voff) do { _Pragma("unroll") for (int _i = 0; _i < 2; ++_i) \
;         __builtin_amdgcn_global_load_lds((const unsigned*)((const char*)(gbase) + (voff)[_i]), (PG8_LAS unsigned*)(lds + (bufoff) + ldsw + _i * 8192), 16, 0, 0); } while (0)
; #define PG8_LDA(dst, b, h) do { _Pragma("unroll") for (int m = 0; m < 4; ++m) _Pragma("unroll") for (int k = 0; k < 2; ++k) dst[m][k] = *(const PG8_LAS bf16x8*)(lds + PG8_SA(b, h) + aoff + m * 2048 + k * 1024); } while (0)
; #define PG8_MMA(ai, bj, At, Bt) do { __builtin_amdgcn_s_setprio(1); _Pragma("unroll") for (int m = 0; m < 4; ++m) _Pragma("unroll") for (int n = 0; n < 2; ++n) _Pragma("unroll") for (int k = 0; k < 2; ++k) \
;         acc[ai][bj][m][n] = __builtin_amdgcn_mfma_f32_16x16x32_bf16(Bt[n][k], At[m][k], acc[ai][bj][m][n], 0, 0, 0); __builtin_amdgcn_s_setprio(0); } while (0)
; #define PG8_WAIT_V(n) asm volatile("s_waitcnt vmcnt(" #n ")" ::: "memory")
; #define PG8_WAIT_L(n) asm volatile("s_waitcnt lgkmcnt(" #n ")" ::: "memory")
; #define PG8_BAR __builtin_amdgcn_s_barrier()
; #define PG8_SCHED __builtin_amdgcn_sched_barrier(0)
; template <class Epi, class Sched, bool ALIGN_EPI = false, bool SP2 = false>
; __device__ __forceinline__ void gemm_phase(PG8_LAS unsigned char* lds, const Gemm g, const Sched& S, const Epi& E) {
;     ...
;         for (int t = 0; t < nt; t += 2) {
;     ...
;             PG8_LDA(At, 1, 1); PG8_STAGE(PG8_SB(1, 0), b3, voffB); PG8_STAGE(PG8_SB(1, 1), b3 + hstep, voffB); PG8_STAGE(PG8_SA(1, 0), a3, voffA);
;             PG8_WAIT_V(8); PG8_WAIT_L(0); PG8_BAR; PG8_MMA(1, 0, At, B0); PG8_MMA(1, 1, At, B1); PG8_BAR; PG8_SCHED;
	s_add_i32 s48, s48, s35
	v_lshl_add_u64 v[194:195], v[206:207], 0, s[60:61]
	s_mov_b32 m0, s48
	ds_read_b128 v[106:109], v230 offset:49152
	ds_read_b128 v[110:113], v230 offset:50176
	ds_read_b128 v[114:117], v230 offset:51200
	ds_read_b128 v[118:121], v230 offset:52224
	ds_read_b128 v[130:133], v230 offset:53248
	ds_read_b128 v[134:137], v230 offset:54272
	ds_read_b128 v[138:141], v230 offset:55296
	ds_read_b128 v[142:145], v230 offset:56320
	global_load_lds_dwordx4 v[194:195], off
	s_add_i32 m0, s48, 0x2000
	s_add_u32 s54, s74, 0x40080
	v_lshl_add_u64 v[194:195], v[218:219], 0, s[60:61]
	s_addc_u32 s55, s75, 0
	s_add_i32 s48, s49, s35
	global_load_lds_dwordx4 v[194:195], off
	s_mov_b32 m0, s48
	s_nop 0
	global_load_lds_dwordx4 v200, s[54:55]
	s_add_i32 m0, s48, 0x2000
	s_nop 0
	global_load_lds_dwordx4 v204, s[54:55]
	v_lshl_add_u64 v[194:195], v[240:241], 0, s[60:61]
	s_mov_b32 m0, s84
	s_nop 0
	global_load_lds_dwordx4 v[194:195], off
	v_lshl_add_u64 v[194:195], v[242:243], 0, s[60:61]
	s_mov_b32 m0, s85
	s_nop 0
	global_load_lds_dwordx4 v[194:195], off
	s_waitcnt vmcnt(8)
	s_waitcnt lgkmcnt(0)
	s_barrier
	s_setprio 1
	s_waitcnt lgkmcnt(0)
	v_mfma_f32_16x16x32_bf16 v[62:65], v[66:69], v[106:109], v[62:65]
	v_mfma_f32_16x16x32_bf16 v[58:61], v[74:77], v[106:109], v[58:61]
	v_mfma_f32_16x16x32_bf16 v[46:49], v[66:69], v[114:117], v[46:49]
	v_mfma_f32_16x16x32_bf16 v[42:45], v[74:77], v[114:117], v[42:45]
	v_mfma_f32_16x16x32_bf16 v[30:33], v[66:69], v[130:133], v[30:33]
	v_mfma_f32_16x16x32_bf16 v[26:29], v[74:77], v[130:133], v[26:29]
	v_mfma_f32_16x16x32_bf16 v[14:17], v[66:69], v[138:141], v[14:17]
	v_mfma_f32_16x16x32_bf16 v[10:13], v[74:77], v[138:141], v[10:13]
	v_mfma_f32_16x16x32_bf16 v[62:65], v[70:73], v[110:113], v[62:65]
	v_mfma_f32_16x16x32_bf16 v[58:61], v[78:81], v[110:113], v[58:61]
	v_mfma_f32_16x16x32_bf16 v[46:49], v[70:73], v[118:121], v[46:49]
	v_mfma_f32_16x16x32_bf16 v[42:45], v[78:81], v[118:121], v[42:45]
	v_mfma_f32_16x16x32_bf16 v[30:33], v[70:73], v[134:137], v[30:33]
	v_mfma_f32_16x16x32_bf16 v[26:29], v[78:81], v[134:137], v[26:29]
	v_mfma_f32_16x16x32_bf16 v[14:17], v[70:73], v[142:145], v[14:17]
	v_mfma_f32_16x16x32_bf16 v[10:13], v[78:81], v[142:145], v[10:13]
	s_setprio 0
	s_setprio 1
	v_mfma_f32_16x16x32_bf16 v[54:57], v[82:85], v[106:109], v[54:57]
	v_mfma_f32_16x16x32_bf16 v[50:53], v[90:93], v[106:109], v[50:53]
	v_mfma_f32_16x16x32_bf16 v[38:41], v[82:85], v[114:117], v[38:41]
	v_mfma_f32_16x16x32_bf16 v[34:37], v[90:93], v[114:117], v[34:37]
	v_mfma_f32_16x16x32_bf16 v[22:25], v[82:85], v[130:133], v[22:25]
	v_mfma_f32_16x16x32_bf16 v[18:21], v[90:93], v[130:133], v[18:21]
	v_mfma_f32_16x16x32_bf16 v[6:9], v[82:85], v[138:141], v[6:9]
	v_mfma_f32_16x16x32_bf16 v[2:5], v[90:93], v[138:141], v[2:5]
	v_mfma_f32_16x16x32_bf16 v[54:57], v[86:89], v[110:113], v[54:57]
	v_mfma_f32_16x16x32_bf16 v[50:53], v[94:97], v[110:113], v[50:53]
	v_mfma_f32_16x16x32_bf16 v[38:41], v[86:89], v[118:121], v[38:41]
	v_mfma_f32_16x16x32_bf16 v[34:37], v[94:97], v[118:121], v[34:37]
	v_mfma_f32_16x16x32_bf16 v[22:25], v[86:89], v[134:137], v[22:25]
	v_mfma_f32_16x16x32_bf16 v[18:21], v[94:97], v[134:137], v[18:21]
	v_mfma_f32_16x16x32_bf16 v[6:9], v[86:89], v[142:145], v[6:9]
	v_mfma_f32_16x16x32_bf16 v[2:5], v[94:97], v[142:145], v[2:5]
	s_setprio 0
	s_barrier
	s_add_i32 s89, s89, 2
	s_add_u32 vcc_lo, vcc_lo, 0x100
	s_addc_u32 vcc_hi, vcc_hi, 0
	s_add_u32 s45, s45, 0x100
	s_addc_u32 s88, s88, 0
	s_cmp_gt_u32 s89, 13
	s_cbranch_scc0 .LBB0_993
	s_and_b64 vcc, exec, s[10:11]
	s_cbranch_vccz .LBB0_996
	s_barrier

; #define PG8_STAGE(bufoff, gbase, voff) do { _Pragma("unroll") for (int _i = 0; _i < 2; ++_i) \
;         __builtin_amdgcn_global_load_lds((const unsigned*)((const char*)(gbase) + (voff)[_i]), (PG8_LAS unsigned*)(lds + (bufoff) + ldsw + _i * 8192), 16, 0, 0); } while (0)
; #define PG8_LDA(dst, b, h) do { _Pragma("unroll") for (int m = 0; m < 4; ++m) _Pragma("unroll") for (int k = 0; k < 2; ++k) dst[m][k] = *(const PG8_LAS bf16x8*)(lds + PG8_SA(b, h) + aoff + m * 2048 + k * 1024); } while (0)
; #define PG8_LDB(dst, b, h) do { _Pragma("unroll") for (int n = 0; n < 2; ++n) _Pragma("unroll") for (int k = 0; k < 2; ++k) dst[n][k] = *(const PG8_LAS bf16x8*)(lds + PG8_SB(b, h) + boff + n * 2048 + k * 1024); } while (0)
; #define PG8_MMA(ai, bj, At, Bt) do { __builtin_amdgcn_s_setprio(1); _Pragma("unroll") for (int m = 0; m < 4; ++m) _Pragma("unroll") for (int n = 0; n < 2; ++n) _Pragma("unroll") for (int k = 0; k < 2; ++k) \
;         acc[ai][bj][m][n] = __builtin_amdgcn_mfma_f32_16x16x32_bf16(Bt[n][k], At[m][k], acc[ai][bj][m][n], 0, 0, 0); __builtin_amdgcn_s_setprio(0); } while (0)
; #define PG8_BAR __builtin_amdgcn_s_barrier()
; template <class Epi, class Sched, bool ALIGN_EPI = false, bool SP2 = false>
; __device__ __forceinline__ void gemm_phase(PG8_LAS unsigned char* lds, const Gemm g, const Sched& S, const Epi& E) {
;     ...
;         const bool has_next = S.next(ui + 1, nxt);
;         const char* nA = has_next ? (const char*)g.A + (size_t)nxt.pm * tstep : cA; const char* nB = has_next ? (const char*)g.Bt + (size_t)nxt.pn * tstep : cB;
;         for (int t = 0; t < nt; t += 2) {
;             const bool last = (t == nt - 2);
;             const char* a1 = cA + (size_t)(t + 1) * kstep;
;             const char* a2 = last ? nA : cA + (size_t)(t + 2) * kstep; const char* b2 = last ? nB : cB + (size_t)(t + 2) * kstep;
;             const char* a3 = a2 + kstep; const char* b3 = b2 + kstep;
;             if (last && has_next) S.a_ready(nxt);
;             if constexpr (SP2) {
;             PG8_LDB(B0, 0, 0); PG8_LDB(B1, 0, 1); PG8_SCHED; PG8_LDA(At, 0, 0); PG8_STAGE(PG8_SA(1, 1), a1 + hstep, voffA);
;             PG8_WAIT_V(8); PG8_WAIT_L(0); PG8_BAR; PG8_MMA(0, 0, At, B0); PG8_MMA(0, 1, At, B1); PG8_BAR; PG8_SCHED;
;             PG8_LDA(At, 0, 1); PG8_STAGE(PG8_SB(0, 0), b2, voffB); PG8_STAGE(PG8_SB(0, 1), b2 + hstep, voffB); PG8_STAGE(PG8_SA(0, 0), a2, voffA);
.LBB0_1159:
	s_add_u32 s10, s8, 0x100
	s_addc_u32 s11, s9, 0
	s_add_i32 s31, 0, 0x10000
	s_cmp_eq_u32 s23, 40
	s_cselect_b32 s19, s1, s11
	s_cselect_b32 s18, s0, s10
	s_cselect_b32 s17, s7, s22
	s_cselect_b32 s16, s6, s21
	s_add_i32 s45, 0, 0x14000
	v_add_u32_e32 v142, s31, v170
	v_add_u32_e32 v168, s45, v170
	ds_read_b128 v[114:117], v142
	ds_read_b128 v[126:129], v142 offset:1024
	ds_read_b128 v[130:133], v142 offset:2048
	ds_read_b128 v[142:145], v142 offset:3072
	ds_read_b128 v[174:177], v168
	ds_read_b128 v[178:181], v168 offset:1024
	ds_read_b128 v[182:185], v168 offset:2048
	ds_read_b128 v[186:189], v168 offset:3072
	s_add_i32 m0, s26, 0xc000
	ds_read_b128 v[190:193], v172
	ds_read_b128 v[194:197], v172 offset:1024
	ds_read_b128 v[198:201], v172 offset:2048
	ds_read_b128 v[202:205], v172 offset:3072
	ds_read_b128 v[210:213], v172 offset:4096
	ds_read_b128 v[214:217], v172 offset:5120
	ds_read_b128 v[222:225], v172 offset:6144
	ds_read_b128 v[230:233], v172 offset:7168
	global_load_lds_dwordx4 v164, s[8:9]
	s_add_i32 m0, s26, 0xe000
	s_nop 0
	global_load_lds_dwordx4 v166, s[8:9]
	s_waitcnt vmcnt(8)
	s_waitcnt lgkmcnt(0)
	s_barrier
	s_setprio 1
	s_waitcnt lgkmcnt(0)
	v_mfma_f32_16x16x32_bf16 v[138:141], v[114:117], v[190:193], v[138:141]
	v_mfma_f32_16x16x32_bf16 v[134:137], v[130:133], v[190:193], v[134:137]
	v_mfma_f32_16x16x32_bf16 v[122:125], v[114:117], v[198:201], v[122:125]
	v_mfma_f32_16x16x32_bf16 v[118:121], v[130:133], v[198:201], v[118:121]
	v_mfma_f32_16x16x32_bf16 v[106:109], v[114:117], v[210:213], v[106:109]
	v_mfma_f32_16x16x32_bf16 v[98:101], v[130:133], v[210:213], v[98:101]
	v_mfma_f32_16x16x32_bf16 v[90:93], v[114:117], v[222:225], v[90:93]
	v_mfma_f32_16x16x32_bf16 v[82:85], v[130:133], v[222:225], v[82:85]
	v_mfma_f32_16x16x32_bf16 v[138:141], v[126:129], v[194:197], v[138:141]
	v_mfma_f32_16x16x32_bf16 v[134:137], v[142:145], v[194:197], v[134:137]
	v_mfma_f32_16x16x32_bf16 v[122:125], v[126:129], v[202:205], v[122:125]
	v_mfma_f32_16x16x32_bf16 v[118:121], v[142:145], v[202:205], v[118:121]
	v_mfma_f32_16x16x32_bf16 v[106:109], v[126:129], v[214:217], v[106:109]
	v_mfma_f32_16x16x32_bf16 v[98:101], v[142:145], v[214:217], v[98:101]
	v_mfma_f32_16x16x32_bf16 v[90:93], v[126:129], v[230:233], v[90:93]
	v_mfma_f32_16x16x32_bf16 v[82:85], v[142:145], v[230:233], v[82:85]
	s_setprio 0
	s_setprio 1
	v_mfma_f32_16x16x32_bf16 v[110:113], v[174:177], v[190:193], v[110:113]
	v_mfma_f32_16x16x32_bf16 v[102:105], v[182:185], v[190:193], v[102:105]
	v_mfma_f32_16x16x32_bf16 v[94:97], v[174:177], v[198:201], v[94:97]
	v_mfma_f32_16x16x32_bf16 v[86:89], v[182:185], v[198:201], v[86:89]
	v_mfma_f32_16x16x32_bf16 v[78:81], v[174:177], v[210:213], v[78:81]
	v_mfma_f32_16x16x32_bf16 v[74:77], v[182:185], v[210:213], v[74:77]
	v_mfma_f32_16x16x32_bf16 v[70:73], v[174:177], v[222:225], v[70:73]
	v_mfma_f32_16x16x32_bf16 v[66:69], v[182:185], v[222:225], v[66:69]
	v_mfma_f32_16x16x32_bf16 v[110:113], v[178:181], v[194:197], v[110:113]
	v_mfma_f32_16x16x32_bf16 v[102:105], v[186:189], v[194:197], v[102:105]
	v_mfma_f32_16x16x32_bf16 v[94:97], v[178:181], v[202:205], v[94:97]
	v_mfma_f32_16x16x32_bf16 v[86:89], v[186:189], v[202:205], v[86:89]
	v_mfma_f32_16x16x32_bf16 v[78:81], v[178:181], v[214:217], v[78:81]
	v_mfma_f32_16x16x32_bf16 v[74:77], v[186:189], v[214:217], v[74:77]
	v_mfma_f32_16x16x32_bf16 v[70:73], v[178:181], v[230:233], v[70:73]
	v_mfma_f32_16x16x32_bf16 v[66:69], v[186:189], v[230:233], v[66:69]
	s_setprio 0
	s_barrier
	s_add_i32 s8, s31, s25
	v_lshl_add_u64 v[168:169], s[16:17], 0, v[0:1]
	s_mov_b32 m0, s8
	ds_read_b128 v[190:193], v172 offset:16384
	ds_read_b128 v[194:197], v172 offset:17408
	ds_read_b128 v[198:201], v172 offset:18432
	ds_read_b128 v[202:205], v172 offset:19456
	ds_read_b128 v[210:213], v172 offset:20480
	ds_read_b128 v[214:217], v172 offset:21504
	ds_read_b128 v[222:225], v172 offset:22528
	ds_read_b128 v[230:233], v172 offset:23552
	global_load_lds_dwordx4 v[168:169], off
	s_add_i32 m0, s8, 0x2000
	s_add_u32 s8, s16, 0xb0000
	v_lshl_add_u64 v[206:207], s[16:17], 0, v[146:147]
	s_addc_u32 s9, s17, 0
	s_add_i32 s31, s45, s25
	global_load_lds_dwordx4 v[206:207], off
	s_mov_b32 m0, s31
	v_lshl_add_u64 v[234:235], s[18:19], 0, v[146:147]
	global_load_lds_dwordx4 v0, s[8:9]
	s_add_i32 m0, s31, 0x2000
	s_nop 0
	global_load_lds_dwordx4 v146, s[8:9]
	v_lshl_add_u64 v[218:219], s[18:19], 0, v[0:1]
	s_mov_b32 m0, s26
	s_nop 0
	global_load_lds_dwordx4 v[218:219], off
	s_mov_b32 m0, s27
	s_nop 0
	global_load_lds_dwordx4 v[234:235], off
	s_waitcnt vmcnt(8)
	s_waitcnt lgkmcnt(0)
	s_barrier
; #define PG8_STAGE(bufoff, gbase, voff) do { _Pragma("unroll") for (int _i = 0; _i < 2; ++_i) \
;         __builtin_amdgcn_global_load_lds((const unsigned*)((const char*)(gbase) + (voff)[_i]), (PG8_LAS unsigned*)(lds + (bufoff) + ldsw + _i * 8192), 16, 0, 0); } while (0)
; #define PG8_LDA(dst, b, h) do { _Pragma("unroll") for (int m = 0; m < 4; ++m) _Pragma("unroll") for (int k = 0; k < 2; ++k) dst[m][k] = *(const PG8_LAS bf16x8*)(lds + PG8_SA(b, h) + aoff + m * 2048 + k * 1024); } while (0)
; #define PG8_LDB(dst, b, h) do { _Pragma("unroll") for (int n = 0; n < 2; ++n) _Pragma("unroll") for (int k = 0; k < 2; ++k) dst[n][k] = *(const PG8_LAS bf16x8*)(lds + PG8_SB(b, h) + boff + n * 2048 + k * 1024); } while (0)
; #define PG8_MMA(ai, bj, At, Bt) do { __builtin_amdgcn_s_setprio(1); _Pragma("unroll") for (int m = 0; m < 4; ++m) _Pragma("unroll") for (int n = 0; n < 2; ++n) _Pragma("unroll") for (int k = 0; k < 2; ++k) \
;         acc[ai][bj][m][n] = __builtin_amdgcn_mfma_f32_16x16x32_bf16(Bt[n][k], At[m][k], acc[ai][bj][m][n], 0, 0, 0); __builtin_amdgcn_s_setprio(0); } while (0)
; #define PG8_WAIT_V(n) asm volatile("s_waitcnt vmcnt(" #n ")" ::: "memory")
; #define PG8_WAIT_L(n) asm volatile("s_waitcnt lgkmcnt(" #n ")" ::: "memory")
; #define PG8_BAR __builtin_amdgcn_s_barrier()
; #define PG8_SCHED __builtin_amdgcn_sched_barrier(0)
; template <class Epi, class Sched, bool ALIGN_EPI = false, bool SP2 = false>
; __device__ __forceinline__ void gemm_phase(PG8_LAS unsigned char* lds, const Gemm g, const Sched& S, const Epi& E) {
;     ...
;             PG8_WAIT_V(8); PG8_WAIT_L(0); PG8_BAR; PG8_MMA(1, 0, At, B0); PG8_MMA(1, 1, At, B1); PG8_BAR; PG8_SCHED;
;             PG8_LDB(B0, 1, 0); PG8_LDB(B1, 1, 1); PG8_SCHED; PG8_LDA(At, 1, 0); PG8_STAGE(PG8_SA(0, 1), a2 + hstep, voffA);
;             PG8_WAIT_V(8); PG8_WAIT_L(0); PG8_BAR; PG8_MMA(0, 0, At, B0); PG8_MMA(0, 1, At, B1); PG8_BAR; PG8_SCHED;
	s_setprio 1
	s_waitcnt lgkmcnt(0)
	v_mfma_f32_16x16x32_bf16 v[62:65], v[114:117], v[190:193], v[62:65]
	v_mfma_f32_16x16x32_bf16 v[58:61], v[130:133], v[190:193], v[58:61]
	v_mfma_f32_16x16x32_bf16 v[54:57], v[114:117], v[198:201], v[54:57]
	v_mfma_f32_16x16x32_bf16 v[46:49], v[130:133], v[198:201], v[46:49]
	v_mfma_f32_16x16x32_bf16 v[38:41], v[114:117], v[210:213], v[38:41]
	v_mfma_f32_16x16x32_bf16 v[30:33], v[130:133], v[210:213], v[30:33]
	v_mfma_f32_16x16x32_bf16 v[22:25], v[114:117], v[222:225], v[22:25]
	v_mfma_f32_16x16x32_bf16 v[14:17], v[130:133], v[222:225], v[14:17]
	v_mfma_f32_16x16x32_bf16 v[62:65], v[126:129], v[194:197], v[62:65]
	v_mfma_f32_16x16x32_bf16 v[58:61], v[142:145], v[194:197], v[58:61]
	v_mfma_f32_16x16x32_bf16 v[54:57], v[126:129], v[202:205], v[54:57]
	v_mfma_f32_16x16x32_bf16 v[46:49], v[142:145], v[202:205], v[46:49]
	v_mfma_f32_16x16x32_bf16 v[38:41], v[126:129], v[214:217], v[38:41]
	v_mfma_f32_16x16x32_bf16 v[30:33], v[142:145], v[214:217], v[30:33]
	v_mfma_f32_16x16x32_bf16 v[22:25], v[126:129], v[230:233], v[22:25]
	v_mfma_f32_16x16x32_bf16 v[14:17], v[142:145], v[230:233], v[14:17]
	s_setprio 0
	s_setprio 1
	v_mfma_f32_16x16x32_bf16 v[50:53], v[174:177], v[190:193], v[50:53]
	v_mfma_f32_16x16x32_bf16 v[42:45], v[182:185], v[190:193], v[42:45]
	v_mfma_f32_16x16x32_bf16 v[34:37], v[174:177], v[198:201], v[34:37]
	v_mfma_f32_16x16x32_bf16 v[26:29], v[182:185], v[198:201], v[26:29]
	v_mfma_f32_16x16x32_bf16 v[18:21], v[174:177], v[210:213], v[18:21]
	v_mfma_f32_16x16x32_bf16 v[10:13], v[182:185], v[210:213], v[10:13]
	v_mfma_f32_16x16x32_bf16 v[6:9], v[174:177], v[222:225], v[6:9]
	v_mfma_f32_16x16x32_bf16 v[2:5], v[182:185], v[222:225], v[2:5]
	v_mfma_f32_16x16x32_bf16 v[50:53], v[178:181], v[194:197], v[50:53]
	v_mfma_f32_16x16x32_bf16 v[42:45], v[186:189], v[194:197], v[42:45]
	v_mfma_f32_16x16x32_bf16 v[34:37], v[178:181], v[202:205], v[34:37]
	v_mfma_f32_16x16x32_bf16 v[26:29], v[186:189], v[202:205], v[26:29]
	v_mfma_f32_16x16x32_bf16 v[18:21], v[178:181], v[214:217], v[18:21]
	v_mfma_f32_16x16x32_bf16 v[10:13], v[186:189], v[214:217], v[10:13]
	v_mfma_f32_16x16x32_bf16 v[6:9], v[178:181], v[230:233], v[6:9]
	v_mfma_f32_16x16x32_bf16 v[2:5], v[186:189], v[230:233], v[2:5]
	s_setprio 0
	s_barrier
	s_add_i32 s31, 0, 0x18000
	s_add_i32 s45, 0, 0x1c000
	v_add_u32_e32 v142, s31, v170
	v_add_u32_e32 v173, s45, v170
	ds_read_b128 v[114:117], v142
	ds_read_b128 v[126:129], v142 offset:1024
	ds_read_b128 v[130:133], v142 offset:2048
	ds_read_b128 v[142:145], v142 offset:3072
	ds_read_b128 v[174:177], v173
	ds_read_b128 v[178:181], v173 offset:1024
	ds_read_b128 v[182:185], v173 offset:2048
	ds_read_b128 v[186:189], v173 offset:3072
	s_add_u32 s8, s18, 0xb0000
	s_addc_u32 s9, s19, 0
	s_mov_b32 m0, s28
	ds_read_b128 v[190:193], v172 offset:32768
	ds_read_b128 v[194:197], v172 offset:33792
	ds_read_b128 v[198:201], v172 offset:34816
	ds_read_b128 v[202:205], v172 offset:35840
	ds_read_b128 v[210:213], v172 offset:36864
	ds_read_b128 v[214:217], v172 offset:37888
	ds_read_b128 v[222:225], v172 offset:38912
	ds_read_b128 v[230:233], v172 offset:39936
	global_load_lds_dwordx4 v0, s[8:9]
	s_mov_b32 m0, s29
	s_nop 0
	global_load_lds_dwordx4 v146, s[8:9]
	s_waitcnt vmcnt(8)
	s_waitcnt lgkmcnt(0)
	s_barrier
	s_setprio 1
	s_waitcnt lgkmcnt(0)
	v_mfma_f32_16x16x32_bf16 v[138:141], v[114:117], v[190:193], v[138:141]
	v_mfma_f32_16x16x32_bf16 v[134:137], v[130:133], v[190:193], v[134:137]
	v_mfma_f32_16x16x32_bf16 v[122:125], v[114:117], v[198:201], v[122:125]
	v_mfma_f32_16x16x32_bf16 v[118:121], v[130:133], v[198:201], v[118:121]
	v_mfma_f32_16x16x32_bf16 v[106:109], v[114:117], v[210:213], v[106:109]
	v_mfma_f32_16x16x32_bf16 v[98:101], v[130:133], v[210:213], v[98:101]
	v_mfma_f32_16x16x32_bf16 v[90:93], v[114:117], v[222:225], v[90:93]
	v_mfma_f32_16x16x32_bf16 v[82:85], v[130:133], v[222:225], v[82:85]
	v_mfma_f32_16x16x32_bf16 v[138:141], v[126:129], v[194:197], v[138:141]
	v_mfma_f32_16x16x32_bf16 v[134:137], v[142:145], v[194:197], v[134:137]
	v_mfma_f32_16x16x32_bf16 v[122:125], v[126:129], v[202:205], v[122:125]
	v_mfma_f32_16x16x32_bf16 v[118:121], v[142:145], v[202:205], v[118:121]
	v_mfma_f32_16x16x32_bf16 v[106:109], v[126:129], v[214:217], v[106:109]
	v_mfma_f32_16x16x32_bf16 v[98:101], v[142:145], v[214:217], v[98:101]
	v_mfma_f32_16x16x32_bf16 v[90:93], v[126:129], v[230:233], v[90:93]
	v_mfma_f32_16x16x32_bf16 v[82:85], v[142:145], v[230:233], v[82:85]
	s_setprio 0
	s_setprio 1
	v_mfma_f32_16x16x32_bf16 v[110:113], v[174:177], v[190:193], v[110:113]
	v_mfma_f32_16x16x32_bf16 v[102:105], v[182:185], v[190:193], v[102:105]
	v_mfma_f32_16x16x32_bf16 v[94:97], v[174:177], v[198:201], v[94:97]
	v_mfma_f32_16x16x32_bf16 v[86:89], v[182:185], v[198:201], v[86:89]
	v_mfma_f32_16x16x32_bf16 v[78:81], v[174:177], v[210:213], v[78:81]
	v_mfma_f32_16x16x32_bf16 v[74:77], v[182:185], v[210:213], v[74:77]
	v_mfma_f32_16x16x32_bf16 v[70:73], v[174:177], v[222:225], v[70:73]
	v_mfma_f32_16x16x32_bf16 v[66:69], v[182:185], v[222:225], v[66:69]
	v_mfma_f32_16x16x32_bf16 v[110:113], v[178:181], v[194:197], v[110:113]
	v_mfma_f32_16x16x32_bf16 v[102:105], v[186:189], v[194:197], v[102:105]
	v_mfma_f32_16x16x32_bf16 v[94:97], v[178:181], v[202:205], v[94:97]
	v_mfma_f32_16x16x32_bf16 v[86:89], v[186:189], v[202:205], v[86:89]
	v_mfma_f32_16x16x32_bf16 v[78:81], v[178:181], v[214:217], v[78:81]
	v_mfma_f32_16x16x32_bf16 v[74:77], v[186:189], v[214:217], v[74:77]
	v_mfma_f32_16x16x32_bf16 v[70:73], v[178:181], v[230:233], v[70:73]
	v_mfma_f32_16x16x32_bf16 v[66:69], v[186:189], v[230:233], v[66:69]
	s_setprio 0
	s_barrier
; #define PG8_STAGE(bufoff, gbase, voff) do { _Pragma("unroll") for (int _i = 0; _i < 2; ++_i) \
;         __builtin_amdgcn_global_load_lds((const unsigned*)((const char*)(gbase) + (voff)[_i]), (PG8_LAS unsigned*)(lds + (bufoff) + ldsw + _i * 8192), 16, 0, 0); } while (0)
; #define PG8_LDA(dst, b, h) do { _Pragma("unroll") for (int m = 0; m < 4; ++m) _Pragma("unroll") for (int k = 0; k < 2; ++k) dst[m][k] = *(const PG8_LAS bf16x8*)(lds + PG8_SA(b, h) + aoff + m * 2048 + k * 1024); } while (0)
; #define PG8_MMA(ai, bj, At, Bt) do { __builtin_amdgcn_s_setprio(1); _Pragma("unroll") for (int m = 0; m < 4; ++m) _Pragma("unroll") for (int n = 0; n < 2; ++n) _Pragma("unroll") for (int k = 0; k < 2; ++k) \
;         acc[ai][bj][m][n] = __builtin_amdgcn_mfma_f32_16x16x32_bf16(Bt[n][k], At[m][k], acc[ai][bj][m][n], 0, 0, 0); __builtin_amdgcn_s_setprio(0); } while (0)
; #define PG8_WAIT_V(n) asm volatile("s_waitcnt vmcnt(" #n ")" ::: "memory")
; #define PG8_WAIT_L(n) asm volatile("s_waitcnt lgkmcnt(" #n ")" ::: "memory")
; #define PG8_BAR __builtin_amdgcn_s_barrier()
; #define PG8_SCHED __builtin_amdgcn_sched_barrier(0)
; template <class Epi, class Sched, bool ALIGN_EPI = false, bool SP2 = false>
; __device__ __forceinline__ void gemm_phase(PG8_LAS unsigned char* lds, const Gemm g, const Sched& S, const Epi& E) {
;     ...
;             PG8_LDA(At, 1, 1); PG8_STAGE(PG8_SB(1, 0), b3, voffB); PG8_STAGE(PG8_SB(1, 1), b3 + hstep, voffB); PG8_STAGE(PG8_SA(1, 0), a3, voffA);
;             PG8_WAIT_V(8); PG8_WAIT_L(0); PG8_BAR; PG8_MMA(1, 0, At, B0); PG8_MMA(1, 1, At, B1); PG8_BAR; PG8_SCHED;
	s_add_i32 s8, s31, s25
	v_lshl_add_u64 v[168:169], v[168:169], 0, s[60:61]
	s_mov_b32 m0, s8
	ds_read_b128 v[190:193], v172 offset:49152
	ds_read_b128 v[194:197], v172 offset:50176
	ds_read_b128 v[198:201], v172 offset:51200
	ds_read_b128 v[202:205], v172 offset:52224
	ds_read_b128 v[210:213], v172 offset:53248
	ds_read_b128 v[214:217], v172 offset:54272
	ds_read_b128 v[222:225], v172 offset:55296
	ds_read_b128 v[230:233], v172 offset:56320
	global_load_lds_dwordx4 v[168:169], off
	s_add_i32 m0, s8, 0x2000
	s_add_u32 s8, s16, 0xb0080
	v_lshl_add_u64 v[168:169], v[206:207], 0, s[60:61]
	s_addc_u32 s9, s17, 0
	s_add_i32 s16, s45, s25
	global_load_lds_dwordx4 v[168:169], off
	s_mov_b32 m0, s16
	s_nop 0
	global_load_lds_dwordx4 v0, s[8:9]
	s_add_i32 m0, s16, 0x2000
	s_nop 0
	global_load_lds_dwordx4 v146, s[8:9]
	v_lshl_add_u64 v[168:169], v[218:219], 0, s[60:61]
	s_mov_b32 m0, s35
	s_nop 0
	global_load_lds_dwordx4 v[168:169], off
	v_lshl_add_u64 v[168:169], v[234:235], 0, s[60:61]
	s_mov_b32 m0, s38
	s_nop 0
	global_load_lds_dwordx4 v[168:169], off
	s_waitcnt vmcnt(8)
	s_waitcnt lgkmcnt(0)
	s_barrier
	s_setprio 1
	s_waitcnt lgkmcnt(0)
	v_mfma_f32_16x16x32_bf16 v[62:65], v[114:117], v[190:193], v[62:65]
	v_mfma_f32_16x16x32_bf16 v[58:61], v[130:133], v[190:193], v[58:61]
	v_mfma_f32_16x16x32_bf16 v[54:57], v[114:117], v[198:201], v[54:57]
	v_mfma_f32_16x16x32_bf16 v[46:49], v[130:133], v[198:201], v[46:49]
	v_mfma_f32_16x16x32_bf16 v[38:41], v[114:117], v[210:213], v[38:41]
	v_mfma_f32_16x16x32_bf16 v[30:33], v[130:133], v[210:213], v[30:33]
	v_mfma_f32_16x16x32_bf16 v[22:25], v[114:117], v[222:225], v[22:25]
	v_mfma_f32_16x16x32_bf16 v[14:17], v[130:133], v[222:225], v[14:17]
	v_mfma_f32_16x16x32_bf16 v[62:65], v[126:129], v[194:197], v[62:65]
	v_mfma_f32_16x16x32_bf16 v[58:61], v[142:145], v[194:197], v[58:61]
	v_mfma_f32_16x16x32_bf16 v[54:57], v[126:129], v[202:205], v[54:57]
	v_mfma_f32_16x16x32_bf16 v[46:49], v[142:145], v[202:205], v[46:49]
	v_mfma_f32_16x16x32_bf16 v[38:41], v[126:129], v[214:217], v[38:41]
	v_mfma_f32_16x16x32_bf16 v[30:33], v[142:145], v[214:217], v[30:33]
	v_mfma_f32_16x16x32_bf16 v[22:25], v[126:129], v[230:233], v[22:25]
	v_mfma_f32_16x16x32_bf16 v[14:17], v[142:145], v[230:233], v[14:17]
	s_setprio 0
	s_setprio 1
	v_mfma_f32_16x16x32_bf16 v[50:53], v[174:177], v[190:193], v[50:53]
	v_mfma_f32_16x16x32_bf16 v[42:45], v[182:185], v[190:193], v[42:45]
	v_mfma_f32_16x16x32_bf16 v[34:37], v[174:177], v[198:201], v[34:37]
	v_mfma_f32_16x16x32_bf16 v[26:29], v[182:185], v[198:201], v[26:29]
	v_mfma_f32_16x16x32_bf16 v[18:21], v[174:177], v[210:213], v[18:21]
	v_mfma_f32_16x16x32_bf16 v[10:13], v[182:185], v[210:213], v[10:13]
	v_mfma_f32_16x16x32_bf16 v[6:9], v[174:177], v[222:225], v[6:9]
	v_mfma_f32_16x16x32_bf16 v[2:5], v[182:185], v[222:225], v[2:5]
	v_mfma_f32_16x16x32_bf16 v[50:53], v[178:181], v[194:197], v[50:53]
	v_mfma_f32_16x16x32_bf16 v[42:45], v[186:189], v[194:197], v[42:45]
	v_mfma_f32_16x16x32_bf16 v[34:37], v[178:181], v[202:205], v[34:37]
	v_mfma_f32_16x16x32_bf16 v[26:29], v[186:189], v[202:205], v[26:29]
	v_mfma_f32_16x16x32_bf16 v[18:21], v[178:181], v[214:217], v[18:21]
	v_mfma_f32_16x16x32_bf16 v[10:13], v[186:189], v[214:217], v[10:13]
	v_mfma_f32_16x16x32_bf16 v[6:9], v[178:181], v[230:233], v[6:9]
	v_mfma_f32_16x16x32_bf16 v[2:5], v[186:189], v[230:233], v[2:5]
	s_setprio 0
	s_barrier
	s_add_i32 s23, s23, 2
	s_add_u32 s21, s21, 0x100
	s_addc_u32 s22, s22, 0
	s_cmp_gt_u32 s23, 41
	s_mov_b64 s[8:9], s[10:11]
	s_cbranch_scc0 .LBB0_1159
	v_mov_b32_e32 v173, v220
	s_and_b64 vcc, exec, s[4:5]
	s_cbranch_vccz .LBB0_1162
	s_barrier

; __global__ void __launch_bounds__(NTHR, 2) fwd_megakernel(Args a) {
	.amdhsa_kernel _Z14fwd_megakernel4Args
		.amdhsa_group_segment_fixed_size 0
		.amdhsa_private_segment_fixed_size 0
		.amdhsa_kernarg_size 488
		.amdhsa_user_sgpr_count 2
		.amdhsa_user_sgpr_dispatch_ptr 0
		.amdhsa_user_sgpr_queue_ptr 0
		.amdhsa_user_sgpr_kernarg_segment_ptr 1
		.amdhsa_user_sgpr_dispatch_id 0
		.amdhsa_user_sgpr_kernarg_preload_length 0
		.amdhsa_user_sgpr_kernarg_preload_offset 0
		.amdhsa_user_sgpr_private_segment_size 0
		.amdhsa_uses_dynamic_stack 0
		.amdhsa_enable_private_segment 0
		.amdhsa_system_sgpr_workgroup_id_x 1
		.amdhsa_system_sgpr_workgroup_id_y 0
		.amdhsa_system_sgpr_workgroup_id_z 0
		.amdhsa_system_sgpr_workgroup_info 0
		.amdhsa_system_vgpr_workitem_id 2
		.amdhsa_next_free_vgpr 256
		.amdhsa_next_free_sgpr 102
		.amdhsa_accum_offset 256
		.amdhsa_reserve_vcc 1
		.amdhsa_float_round_mode_32 0
		.amdhsa_float_round_mode_16_64 0
		.amdhsa_float_denorm_mode_32 3
		.amdhsa_float_denorm_mode_16_64 3
		.amdhsa_dx10_clamp 1
		.amdhsa_ieee_mode 1
		.amdhsa_fp16_overflow 0
		.amdhsa_tg_split 0
		.amdhsa_exception_fp_ieee_invalid_op 0
		.amdhsa_exception_fp_denorm_src 0
		.amdhsa_exception_fp_ieee_div_zero 0
		.amdhsa_exception_fp_ieee_overflow 0
		.amdhsa_exception_fp_ieee_underflow 0
		.amdhsa_exception_fp_ieee_inexact 0
		.amdhsa_exception_int_div_zero 0
	.end_amdhsa_kernel

; __global__ void __launch_bounds__(NTHR, 2) fwd_megakernel(Args a) {
amdhsa.kernels:
  - .agpr_count:     0
    .args:
      - .offset:         0
        .size:           232
        .value_kind:     by_value
      - .offset:         232
        .size:           4
        .value_kind:     hidden_block_count_x
      - .offset:         236
        .size:           4
        .value_kind:     hidden_block_count_y
      - .offset:         240
        .size:           4
        .value_kind:     hidden_block_count_z
      - .offset:         244
        .size:           2
        .value_kind:     hidden_group_size_x
      - .offset:         246
        .size:           2
        .value_kind:     hidden_group_size_y
      - .offset:         248
        .size:           2
        .value_kind:     hidden_group_size_z
      - .offset:         250
        .size:           2
        .value_kind:     hidden_remainder_x
      - .offset:         252
        .size:           2
        .value_kind:     hidden_remainder_y
      - .offset:         254
        .size:           2
        .value_kind:     hidden_remainder_z
      - .offset:         272
        .size:           8
        .value_kind:     hidden_global_offset_x
      - .offset:         280
        .size:           8
        .value_kind:     hidden_global_offset_y
      - .offset:         288
        .size:           8
        .value_kind:     hidden_global_offset_z
      - .offset:         296
        .size:           2
        .value_kind:     hidden_grid_dims
      - .offset:         320
        .size:           8
        .value_kind:     hidden_multigrid_sync_arg
      - .offset:         352
        .size:           4
        .value_kind:     hidden_dynamic_lds_size
    .group_segment_fixed_size: 0
    .kernarg_segment_align: 8
    .kernarg_segment_size: 488
    .language:       OpenCL C
    .language_version:
      - 2
      - 0
    .max_flat_workgroup_size: 512
    .name:           _Z14fwd_megakernel4Args
    .private_segment_fixed_size: 0
    .sgpr_count:     108
    .sgpr_spill_count: 191
    .symbol:         _Z14fwd_megakernel4Args.kd
    .uniform_work_group_size: 1
    .uses_dynamic_stack: false
    .vgpr_count:     256
    .vgpr_spill_count: 0
    .wavefront_size: 64
